# A/B: all s_setprio flips in the g256 GEMM K-loops removed
# speedup vs baseline: 1.0006x; 1.0006x over previous
; template <int KK0, int KK1>
; DI void g256_compute(int tid, const char* sA, const char* sB, f32x4 (&acc)[8][4]) {
;   const int wid = tid >> 6, lane = tid & 63, wr = wid >> 2, wc = wid & 3, fr = lane & 15, fq = lane >> 4;
; #pragma unroll
;   for (int kk = KK0; kk < KK1; ++kk) {
;     bf16x8 b[4], a[4], a2[4];
; #pragma unroll
;     for (int n = 0; n < 4; ++n) { int row = wc * 64 + n * 16 + fr; b[n] = *(const bf16x8*)(sB + row * 128 + (((kk * 4 + fq) ^ (row & 7)) << 4)); }
; #pragma unroll
;     for (int m = 0; m < 4; ++m) { int row = wr * 128 + m * 16 + fr; a[m] = *(const bf16x8*)(sA + row * 128 + (((kk * 4 + fq) ^ (row & 7)) << 4)); }
;     __builtin_amdgcn_sched_barrier(0);
; #pragma unroll
;     for (int m = 0; m < 4; ++m) { int row = wr * 128 + (4 + m) * 16 + fr; a2[m] = *(const bf16x8*)(sA + row * 128 + (((kk * 4 + fq) ^ (row & 7)) << 4)); }
;     __builtin_amdgcn_s_setprio(1);
; #pragma unroll
;     for (int m = 0; m < 4; ++m)
; #pragma unroll
;       for (int n = 0; n < 4; ++n) acc[m][n] = __builtin_amdgcn_mfma_f32_16x16x32_bf16(a[m], b[n], acc[m][n], 0, 0, 0);
;     __builtin_amdgcn_sched_barrier(0);
; #pragma unroll
;     for (int m = 0; m < 4; ++m)
; #pragma unroll
;       for (int n = 0; n < 4; ++n) acc[4 + m][n] = __builtin_amdgcn_mfma_f32_16x16x32_bf16(a2[m], b[n], acc[4 + m][n], 0, 0, 0);
;     __builtin_amdgcn_s_setprio(0);
;     __builtin_amdgcn_sched_barrier(0);
;   }
; }
; template <class AF>
; DI void g256_mainloop_t(int tid, const AF& af, const bft* Bt, int ldb, int bcol, int K, f32x4 (&acc)[8][4]) {
;     ...
;   for (int kt = 0; kt < nk; ++kt) {
;     asm volatile("s_waitcnt vmcnt(0)" ::: "memory");
;     __syncthreads();
;     char* cur = smem + (kt & 1) * 65536; char* nxt = smem + ((kt + 1) & 1) * 65536;
;     if (tid < 256) {
;       if (kt + 1 < nk) g256_stage(tid, af, Bt, ldb, bcol, kt + 1, nxt, nxt + 32768);
;       g256_compute<0, 2>(tid, cur, cur + 32768, acc);
;     } else {
;       g256_compute<0, 1>(tid, cur, cur + 32768, acc);
;       if (kt + 1 < nk) g256_stage(tid, af, Bt, ldb, bcol, kt + 1, nxt, nxt + 32768);
;       g256_compute<1, 2>(tid, cur, cur + 32768, acc);
;     }
.LBB0_160:
	v_add_u32_e32 v2, s36, v160
	v_add_u32_e32 v4, v2, v157
	v_add_u32_e32 v2, v2, v158
	ds_read_b128 v[162:165], v4 offset:32768
	ds_read_b128 v[166:169], v4 offset:34816
	ds_read_b128 v[170:173], v4 offset:36864
	ds_read_b128 v[174:177], v4 offset:38912
	ds_read_b128 v[182:185], v2
	ds_read_b128 v[186:189], v2 offset:2048
	ds_read_b128 v[190:193], v2 offset:4096
	ds_read_b128 v[194:197], v2 offset:6144
	ds_read_b128 v[198:201], v2 offset:8192
	ds_read_b128 v[202:205], v2 offset:10240
	ds_read_b128 v[206:209], v2 offset:12288
	ds_read_b128 v[210:213], v2 offset:14336
	s_waitcnt lgkmcnt(0)
	v_mfma_f32_16x16x32_bf16 v[130:133], v[182:185], v[162:165], v[130:133]
	v_mfma_f32_16x16x32_bf16 v[126:129], v[182:185], v[166:169], v[126:129]
	v_mfma_f32_16x16x32_bf16 v[122:125], v[182:185], v[170:173], v[122:125]
	v_mfma_f32_16x16x32_bf16 v[118:121], v[182:185], v[174:177], v[118:121]
	v_mfma_f32_16x16x32_bf16 v[114:117], v[186:189], v[162:165], v[114:117]
	v_mfma_f32_16x16x32_bf16 v[110:113], v[186:189], v[166:169], v[110:113]
	v_mfma_f32_16x16x32_bf16 v[106:109], v[186:189], v[170:173], v[106:109]
	v_mfma_f32_16x16x32_bf16 v[102:105], v[186:189], v[174:177], v[102:105]
	v_mfma_f32_16x16x32_bf16 v[98:101], v[190:193], v[162:165], v[98:101]
	v_mfma_f32_16x16x32_bf16 v[94:97], v[190:193], v[166:169], v[94:97]
	v_mfma_f32_16x16x32_bf16 v[90:93], v[190:193], v[170:173], v[90:93]
	v_mfma_f32_16x16x32_bf16 v[86:89], v[190:193], v[174:177], v[86:89]
	v_mfma_f32_16x16x32_bf16 v[82:85], v[194:197], v[162:165], v[82:85]
	v_mfma_f32_16x16x32_bf16 v[78:81], v[194:197], v[166:169], v[78:81]
	v_mfma_f32_16x16x32_bf16 v[74:77], v[194:197], v[170:173], v[74:77]
	v_mfma_f32_16x16x32_bf16 v[70:73], v[194:197], v[174:177], v[70:73]
	v_mfma_f32_16x16x32_bf16 v[66:69], v[198:201], v[162:165], v[66:69]
	v_mfma_f32_16x16x32_bf16 v[62:65], v[198:201], v[166:169], v[62:65]
	v_mfma_f32_16x16x32_bf16 v[58:61], v[198:201], v[170:173], v[58:61]
	v_mfma_f32_16x16x32_bf16 v[54:57], v[198:201], v[174:177], v[54:57]
	v_mfma_f32_16x16x32_bf16 v[50:53], v[202:205], v[162:165], v[50:53]
	v_mfma_f32_16x16x32_bf16 v[46:49], v[202:205], v[166:169], v[46:49]
	v_mfma_f32_16x16x32_bf16 v[42:45], v[202:205], v[170:173], v[42:45]
	v_mfma_f32_16x16x32_bf16 v[38:41], v[202:205], v[174:177], v[38:41]
	v_mfma_f32_16x16x32_bf16 v[34:37], v[206:209], v[162:165], v[34:37]
	v_mfma_f32_16x16x32_bf16 v[30:33], v[206:209], v[166:169], v[30:33]
	v_mfma_f32_16x16x32_bf16 v[26:29], v[206:209], v[170:173], v[26:29]
	v_mfma_f32_16x16x32_bf16 v[22:25], v[206:209], v[174:177], v[22:25]
	v_mfma_f32_16x16x32_bf16 v[18:21], v[210:213], v[162:165], v[18:21]
	v_mfma_f32_16x16x32_bf16 v[14:17], v[210:213], v[166:169], v[14:17]
	v_mfma_f32_16x16x32_bf16 v[10:13], v[210:213], v[170:173], v[10:13]
	v_mfma_f32_16x16x32_bf16 v[4:7], v[210:213], v[174:177], v[6:9]
	v_add_u32_e32 v2, s36, v159
	s_nop 0
	v_add_u32_e32 v8, v2, v157
	v_add_u32_e32 v2, v2, v158
	ds_read_b128 v[162:165], v8 offset:32768
	ds_read_b128 v[166:169], v8 offset:34816
	ds_read_b128 v[170:173], v8 offset:36864
	ds_read_b128 v[174:177], v8 offset:38912
	ds_read_b128 v[182:185], v2
	ds_read_b128 v[186:189], v2 offset:2048
	ds_read_b128 v[190:193], v2 offset:4096
	ds_read_b128 v[194:197], v2 offset:6144
	ds_read_b128 v[198:201], v2 offset:8192
	ds_read_b128 v[202:205], v2 offset:10240
	ds_read_b128 v[206:209], v2 offset:12288
	ds_read_b128 v[210:213], v2 offset:14336
	s_waitcnt lgkmcnt(0)
	v_mfma_f32_16x16x32_bf16 v[130:133], v[182:185], v[162:165], v[130:133]
	v_mfma_f32_16x16x32_bf16 v[126:129], v[182:185], v[166:169], v[126:129]
	v_mfma_f32_16x16x32_bf16 v[122:125], v[182:185], v[170:173], v[122:125]
	v_mfma_f32_16x16x32_bf16 v[118:121], v[182:185], v[174:177], v[118:121]
	v_mfma_f32_16x16x32_bf16 v[114:117], v[186:189], v[162:165], v[114:117]
	v_mfma_f32_16x16x32_bf16 v[110:113], v[186:189], v[166:169], v[110:113]
	v_mfma_f32_16x16x32_bf16 v[106:109], v[186:189], v[170:173], v[106:109]
	v_mfma_f32_16x16x32_bf16 v[102:105], v[186:189], v[174:177], v[102:105]
	v_mfma_f32_16x16x32_bf16 v[98:101], v[190:193], v[162:165], v[98:101]
	v_mfma_f32_16x16x32_bf16 v[94:97], v[190:193], v[166:169], v[94:97]
	v_mfma_f32_16x16x32_bf16 v[90:93], v[190:193], v[170:173], v[90:93]
	v_mfma_f32_16x16x32_bf16 v[86:89], v[190:193], v[174:177], v[86:89]
	v_mfma_f32_16x16x32_bf16 v[82:85], v[194:197], v[162:165], v[82:85]
	v_mfma_f32_16x16x32_bf16 v[78:81], v[194:197], v[166:169], v[78:81]
	v_mfma_f32_16x16x32_bf16 v[74:77], v[194:197], v[170:173], v[74:77]
	v_mfma_f32_16x16x32_bf16 v[70:73], v[194:197], v[174:177], v[70:73]
	v_mfma_f32_16x16x32_bf16 v[66:69], v[198:201], v[162:165], v[66:69]
	v_mfma_f32_16x16x32_bf16 v[62:65], v[198:201], v[166:169], v[62:65]
	v_mfma_f32_16x16x32_bf16 v[58:61], v[198:201], v[170:173], v[58:61]
	v_mfma_f32_16x16x32_bf16 v[54:57], v[198:201], v[174:177], v[54:57]
	v_mfma_f32_16x16x32_bf16 v[50:53], v[202:205], v[162:165], v[50:53]
	v_mfma_f32_16x16x32_bf16 v[46:49], v[202:205], v[166:169], v[46:49]
	v_mfma_f32_16x16x32_bf16 v[42:45], v[202:205], v[170:173], v[42:45]
	v_mfma_f32_16x16x32_bf16 v[38:41], v[202:205], v[174:177], v[38:41]
	v_mfma_f32_16x16x32_bf16 v[34:37], v[206:209], v[162:165], v[34:37]
	v_mfma_f32_16x16x32_bf16 v[30:33], v[206:209], v[166:169], v[30:33]
	v_mfma_f32_16x16x32_bf16 v[26:29], v[206:209], v[170:173], v[26:29]
	v_mfma_f32_16x16x32_bf16 v[22:25], v[206:209], v[174:177], v[22:25]
	v_mfma_f32_16x16x32_bf16 v[18:21], v[210:213], v[162:165], v[18:21]
	v_mfma_f32_16x16x32_bf16 v[14:17], v[210:213], v[166:169], v[14:17]
	v_mfma_f32_16x16x32_bf16 v[10:13], v[210:213], v[170:173], v[10:13]
	v_mfma_f32_16x16x32_bf16 v[6:9], v[210:213], v[174:177], v[4:7]

; template <class AF>
; DI void g256_mainloop_t(int tid, const AF& af, const bft* Bt, int ldb, int bcol, int K, f32x4 (&acc)[8][4]) {
;     ...
;   for (int kt = 0; kt < nk; ++kt) {
;     asm volatile("s_waitcnt vmcnt(0)" ::: "memory");
;     __syncthreads();
;     char* cur = smem + (kt & 1) * 65536; char* nxt = smem + ((kt + 1) & 1) * 65536;
;     if (tid < 256) {
;       if (kt + 1 < nk) g256_stage(tid, af, Bt, ldb, bcol, kt + 1, nxt, nxt + 32768);
;       g256_compute<0, 2>(tid, cur, cur + 32768, acc);
;     } else {
;       g256_compute<0, 1>(tid, cur, cur + 32768, acc);
;       if (kt + 1 < nk) g256_stage(tid, af, Bt, ldb, bcol, kt + 1, nxt, nxt + 32768);
;       g256_compute<1, 2>(tid, cur, cur + 32768, acc);
;     }
.LBB0_162:
	s_add_i32 s8, s27, 0xffff0000
	s_waitcnt vmcnt(0)
	s_and_b32 s8, s8, 0x10000
	s_add_i32 s36, s8, 16
	s_and_b32 s8, s27, 0x10000
	s_add_i32 s37, s8, 16
	s_waitcnt vmcnt(0) lgkmcnt(0)
	s_barrier
	s_and_saveexec_b64 s[8:9], vcc
	s_xor_b64 s[8:9], exec, s[8:9]
	s_cbranch_execz .LBB0_166
	v_add_u32_e32 v2, s36, v155
	v_add_u32_e32 v4, v2, v157
	v_add_u32_e32 v2, v2, v158
	ds_read_b128 v[162:165], v4 offset:32768
	ds_read_b128 v[166:169], v4 offset:34816
	ds_read_b128 v[170:173], v4 offset:36864
	ds_read_b128 v[174:177], v4 offset:38912
	ds_read_b128 v[182:185], v2
	ds_read_b128 v[186:189], v2 offset:2048
	ds_read_b128 v[190:193], v2 offset:4096
	ds_read_b128 v[194:197], v2 offset:6144
	ds_read_b128 v[198:201], v2 offset:8192
	ds_read_b128 v[202:205], v2 offset:10240
	ds_read_b128 v[206:209], v2 offset:12288
	ds_read_b128 v[210:213], v2 offset:14336
	s_waitcnt lgkmcnt(7)
	v_mfma_f32_16x16x32_bf16 v[130:133], v[182:185], v[162:165], v[130:133]
	v_mfma_f32_16x16x32_bf16 v[126:129], v[182:185], v[166:169], v[126:129]
	v_mfma_f32_16x16x32_bf16 v[122:125], v[182:185], v[170:173], v[122:125]
	v_mfma_f32_16x16x32_bf16 v[118:121], v[182:185], v[174:177], v[118:121]
	s_waitcnt lgkmcnt(6)
	v_mfma_f32_16x16x32_bf16 v[114:117], v[186:189], v[162:165], v[114:117]
	v_mfma_f32_16x16x32_bf16 v[110:113], v[186:189], v[166:169], v[110:113]
	v_mfma_f32_16x16x32_bf16 v[106:109], v[186:189], v[170:173], v[106:109]
	v_mfma_f32_16x16x32_bf16 v[102:105], v[186:189], v[174:177], v[102:105]
	s_waitcnt lgkmcnt(5)
	v_mfma_f32_16x16x32_bf16 v[98:101], v[190:193], v[162:165], v[98:101]
	v_mfma_f32_16x16x32_bf16 v[94:97], v[190:193], v[166:169], v[94:97]
	v_mfma_f32_16x16x32_bf16 v[90:93], v[190:193], v[170:173], v[90:93]
	v_mfma_f32_16x16x32_bf16 v[86:89], v[190:193], v[174:177], v[86:89]
	s_waitcnt lgkmcnt(4)
	v_mfma_f32_16x16x32_bf16 v[82:85], v[194:197], v[162:165], v[82:85]
	v_mfma_f32_16x16x32_bf16 v[78:81], v[194:197], v[166:169], v[78:81]
	v_mfma_f32_16x16x32_bf16 v[74:77], v[194:197], v[170:173], v[74:77]
	v_mfma_f32_16x16x32_bf16 v[70:73], v[194:197], v[174:177], v[70:73]
	s_waitcnt lgkmcnt(3)
	v_mfma_f32_16x16x32_bf16 v[66:69], v[198:201], v[162:165], v[66:69]
	v_mfma_f32_16x16x32_bf16 v[62:65], v[198:201], v[166:169], v[62:65]
	v_mfma_f32_16x16x32_bf16 v[58:61], v[198:201], v[170:173], v[58:61]
	v_mfma_f32_16x16x32_bf16 v[54:57], v[198:201], v[174:177], v[54:57]
	s_waitcnt lgkmcnt(2)
	v_mfma_f32_16x16x32_bf16 v[50:53], v[202:205], v[162:165], v[50:53]
	v_mfma_f32_16x16x32_bf16 v[46:49], v[202:205], v[166:169], v[46:49]
	v_mfma_f32_16x16x32_bf16 v[42:45], v[202:205], v[170:173], v[42:45]
	v_mfma_f32_16x16x32_bf16 v[38:41], v[202:205], v[174:177], v[38:41]
	s_waitcnt lgkmcnt(1)
	v_mfma_f32_16x16x32_bf16 v[34:37], v[206:209], v[162:165], v[34:37]
	v_mfma_f32_16x16x32_bf16 v[30:33], v[206:209], v[166:169], v[30:33]
	v_mfma_f32_16x16x32_bf16 v[26:29], v[206:209], v[170:173], v[26:29]
	v_mfma_f32_16x16x32_bf16 v[22:25], v[206:209], v[174:177], v[22:25]
	s_waitcnt lgkmcnt(0)
	v_mfma_f32_16x16x32_bf16 v[18:21], v[210:213], v[162:165], v[18:21]
	v_mfma_f32_16x16x32_bf16 v[14:17], v[210:213], v[166:169], v[14:17]
	v_mfma_f32_16x16x32_bf16 v[10:13], v[210:213], v[170:173], v[10:13]
	v_mfma_f32_16x16x32_bf16 v[4:7], v[210:213], v[174:177], v[6:9]
	s_cmp_gt_u32 s26, 14
	s_cbranch_scc1 .LBB0_165
	v_add_u32_e32 v2, s37, v151
	v_add_u32_e32 v161, s37, v152
	v_readfirstlane_b32 s38, v2
	v_lshl_add_u64 v[8:9], v[134:135], 0, s[6:7]
	s_mov_b32 m0, s38
	v_readfirstlane_b32 s38, v161
	v_add_u32_e32 v162, s37, v153
	global_load_lds_dwordx4 v[8:9], off
	v_lshl_add_u64 v[8:9], v[136:137], 0, s[6:7]
	s_mov_b32 m0, s38
	v_readfirstlane_b32 s38, v162
	v_add_u32_e32 v163, s37, v154
	global_load_lds_dwordx4 v[8:9], off
	v_lshl_add_u64 v[8:9], v[138:139], 0, s[6:7]
	s_mov_b32 m0, s38
	v_readfirstlane_b32 s38, v163
	v_add_u32_e32 v2, 0x8000, v2
	global_load_lds_dwordx4 v[8:9], off
	v_lshl_add_u64 v[8:9], v[140:141], 0, s[6:7]
	s_mov_b32 m0, s38
	v_readfirstlane_b32 s38, v2
	v_add_u32_e32 v2, 0x8000, v161
	global_load_lds_dwordx4 v[8:9], off
	v_lshl_add_u64 v[8:9], v[142:143], 0, s[6:7]
	s_mov_b32 m0, s38
	v_readfirstlane_b32 s38, v2
	v_add_u32_e32 v2, 0x8000, v162
	global_load_lds_dwordx4 v[8:9], off
	v_lshl_add_u64 v[8:9], v[144:145], 0, s[6:7]
	s_mov_b32 m0, s38
	v_readfirstlane_b32 s38, v2
	v_add_u32_e32 v2, 0x8000, v163
	global_load_lds_dwordx4 v[8:9], off
	v_lshl_add_u64 v[8:9], v[146:147], 0, s[6:7]
	s_mov_b32 m0, s38
	v_readfirstlane_b32 s38, v2
	global_load_lds_dwordx4 v[8:9], off
	v_lshl_add_u64 v[8:9], v[148:149], 0, s[6:7]
	s_mov_b32 m0, s38
	s_nop 0
	global_load_lds_dwordx4 v[8:9], off
; template <int KK0, int KK1>
; DI void g256_compute(int tid, const char* sA, const char* sB, f32x4 (&acc)[8][4]) {
;     ...
;   for (int kk = KK0; kk < KK1; ++kk) {
;     bf16x8 b[4], a[4], a2[4];
; #pragma unroll
;     for (int n = 0; n < 4; ++n) { int row = wc * 64 + n * 16 + fr; b[n] = *(const bf16x8*)(sB + row * 128 + (((kk * 4 + fq) ^ (row & 7)) << 4)); }
; #pragma unroll
;     for (int m = 0; m < 4; ++m) { int row = wr * 128 + m * 16 + fr; a[m] = *(const bf16x8*)(sA + row * 128 + (((kk * 4 + fq) ^ (row & 7)) << 4)); }
;     __builtin_amdgcn_sched_barrier(0);
; #pragma unroll
;     for (int m = 0; m < 4; ++m) { int row = wr * 128 + (4 + m) * 16 + fr; a2[m] = *(const bf16x8*)(sA + row * 128 + (((kk * 4 + fq) ^ (row & 7)) << 4)); }
;     __builtin_amdgcn_s_setprio(1);
; #pragma unroll
;     for (int m = 0; m < 4; ++m)
; #pragma unroll
;       for (int n = 0; n < 4; ++n) acc[m][n] = __builtin_amdgcn_mfma_f32_16x16x32_bf16(a[m], b[n], acc[m][n], 0, 0, 0);
;     __builtin_amdgcn_sched_barrier(0);
; #pragma unroll
;     for (int m = 0; m < 4; ++m)
; #pragma unroll
;       for (int n = 0; n < 4; ++n) acc[4 + m][n] = __builtin_amdgcn_mfma_f32_16x16x32_bf16(a2[m], b[n], acc[4 + m][n], 0, 0, 0);
;     __builtin_amdgcn_s_setprio(0);
;     __builtin_amdgcn_sched_barrier(0);
;   }
.LBB0_165:
	v_add_u32_e32 v2, s36, v159
	v_add_u32_e32 v8, v2, v157
	v_add_u32_e32 v2, v2, v158
	ds_read_b128 v[162:165], v8 offset:32768
	ds_read_b128 v[166:169], v8 offset:34816
	ds_read_b128 v[170:173], v8 offset:36864
	ds_read_b128 v[174:177], v8 offset:38912
	ds_read_b128 v[182:185], v2
	ds_read_b128 v[186:189], v2 offset:2048
	ds_read_b128 v[190:193], v2 offset:4096
	ds_read_b128 v[194:197], v2 offset:6144
	ds_read_b128 v[198:201], v2 offset:8192
	ds_read_b128 v[202:205], v2 offset:10240
	ds_read_b128 v[206:209], v2 offset:12288
	ds_read_b128 v[210:213], v2 offset:14336
	s_waitcnt lgkmcnt(0)
	v_mfma_f32_16x16x32_bf16 v[130:133], v[182:185], v[162:165], v[130:133]
	v_mfma_f32_16x16x32_bf16 v[126:129], v[182:185], v[166:169], v[126:129]
	v_mfma_f32_16x16x32_bf16 v[122:125], v[182:185], v[170:173], v[122:125]
	v_mfma_f32_16x16x32_bf16 v[118:121], v[182:185], v[174:177], v[118:121]
	v_mfma_f32_16x16x32_bf16 v[114:117], v[186:189], v[162:165], v[114:117]
	v_mfma_f32_16x16x32_bf16 v[110:113], v[186:189], v[166:169], v[110:113]
	v_mfma_f32_16x16x32_bf16 v[106:109], v[186:189], v[170:173], v[106:109]
	v_mfma_f32_16x16x32_bf16 v[102:105], v[186:189], v[174:177], v[102:105]
	v_mfma_f32_16x16x32_bf16 v[98:101], v[190:193], v[162:165], v[98:101]
	v_mfma_f32_16x16x32_bf16 v[94:97], v[190:193], v[166:169], v[94:97]
	v_mfma_f32_16x16x32_bf16 v[90:93], v[190:193], v[170:173], v[90:93]
	v_mfma_f32_16x16x32_bf16 v[86:89], v[190:193], v[174:177], v[86:89]
	v_mfma_f32_16x16x32_bf16 v[82:85], v[194:197], v[162:165], v[82:85]
	v_mfma_f32_16x16x32_bf16 v[78:81], v[194:197], v[166:169], v[78:81]
	v_mfma_f32_16x16x32_bf16 v[74:77], v[194:197], v[170:173], v[74:77]
	v_mfma_f32_16x16x32_bf16 v[70:73], v[194:197], v[174:177], v[70:73]
	v_mfma_f32_16x16x32_bf16 v[66:69], v[198:201], v[162:165], v[66:69]
	v_mfma_f32_16x16x32_bf16 v[62:65], v[198:201], v[166:169], v[62:65]
	v_mfma_f32_16x16x32_bf16 v[58:61], v[198:201], v[170:173], v[58:61]
	v_mfma_f32_16x16x32_bf16 v[54:57], v[198:201], v[174:177], v[54:57]
	v_mfma_f32_16x16x32_bf16 v[50:53], v[202:205], v[162:165], v[50:53]
	v_mfma_f32_16x16x32_bf16 v[46:49], v[202:205], v[166:169], v[46:49]
	v_mfma_f32_16x16x32_bf16 v[42:45], v[202:205], v[170:173], v[42:45]
	v_mfma_f32_16x16x32_bf16 v[38:41], v[202:205], v[174:177], v[38:41]
	v_mfma_f32_16x16x32_bf16 v[34:37], v[206:209], v[162:165], v[34:37]
	v_mfma_f32_16x16x32_bf16 v[30:33], v[206:209], v[166:169], v[30:33]
	v_mfma_f32_16x16x32_bf16 v[26:29], v[206:209], v[170:173], v[26:29]
	v_mfma_f32_16x16x32_bf16 v[22:25], v[206:209], v[174:177], v[22:25]
	v_mfma_f32_16x16x32_bf16 v[18:21], v[210:213], v[162:165], v[18:21]
	v_mfma_f32_16x16x32_bf16 v[14:17], v[210:213], v[166:169], v[14:17]
	v_mfma_f32_16x16x32_bf16 v[10:13], v[210:213], v[170:173], v[10:13]
	v_mfma_f32_16x16x32_bf16 v[6:9], v[210:213], v[174:177], v[4:7]

; template <int KK0, int KK1>
; DI void g256_compute(int tid, const char* sA, const char* sB, f32x4 (&acc)[8][4]) {
;     ...
;   for (int kk = KK0; kk < KK1; ++kk) {
;     bf16x8 b[4], a[4], a2[4];
; #pragma unroll
;     for (int n = 0; n < 4; ++n) { int row = wc * 64 + n * 16 + fr; b[n] = *(const bf16x8*)(sB + row * 128 + (((kk * 4 + fq) ^ (row & 7)) << 4)); }
; #pragma unroll
;     for (int m = 0; m < 4; ++m) { int row = wr * 128 + m * 16 + fr; a[m] = *(const bf16x8*)(sA + row * 128 + (((kk * 4 + fq) ^ (row & 7)) << 4)); }
;     __builtin_amdgcn_sched_barrier(0);
; #pragma unroll
;     for (int m = 0; m < 4; ++m) { int row = wr * 128 + (4 + m) * 16 + fr; a2[m] = *(const bf16x8*)(sA + row * 128 + (((kk * 4 + fq) ^ (row & 7)) << 4)); }
;     __builtin_amdgcn_s_setprio(1);
; #pragma unroll
;     for (int m = 0; m < 4; ++m)
; #pragma unroll
;       for (int n = 0; n < 4; ++n) acc[m][n] = __builtin_amdgcn_mfma_f32_16x16x32_bf16(a[m], b[n], acc[m][n], 0, 0, 0);
;     __builtin_amdgcn_sched_barrier(0);
; #pragma unroll
;     for (int m = 0; m < 4; ++m)
; #pragma unroll
;       for (int n = 0; n < 4; ++n) acc[4 + m][n] = __builtin_amdgcn_mfma_f32_16x16x32_bf16(a2[m], b[n], acc[4 + m][n], 0, 0, 0);
;     __builtin_amdgcn_s_setprio(0);
;     __builtin_amdgcn_sched_barrier(0);
;   }
; template <class AF>
; DI void g256_mainloop_t(int tid, const AF& af, const bft* Bt, int ldb, int bcol, int K, f32x4 (&acc)[8][4]) {
;     ...
;     if (tid < 256) {
;       if (kt + 1 < nk) g256_stage(tid, af, Bt, ldb, bcol, kt + 1, nxt, nxt + 32768);
;       g256_compute<0, 2>(tid, cur, cur + 32768, acc);
.LBB0_473:
	v_add_u32_e32 v0, s26, v160
	v_add_u32_e32 v2, v0, v157
	v_add_u32_e32 v0, v0, v158
	ds_read_b128 v[166:169], v2 offset:32768
	ds_read_b128 v[170:173], v2 offset:34816
	ds_read_b128 v[174:177], v2 offset:36864
	ds_read_b128 v[182:185], v2 offset:38912
	ds_read_b128 v[186:189], v0
	ds_read_b128 v[190:193], v0 offset:2048
	ds_read_b128 v[194:197], v0 offset:4096
	ds_read_b128 v[198:201], v0 offset:6144
	ds_read_b128 v[202:205], v0 offset:8192
	ds_read_b128 v[206:209], v0 offset:10240
	ds_read_b128 v[210:213], v0 offset:12288
	ds_read_b128 v[214:217], v0 offset:14336
	s_waitcnt lgkmcnt(0)
	v_mfma_f32_16x16x32_bf16 v[128:131], v[186:189], v[166:169], v[128:131]
	v_mfma_f32_16x16x32_bf16 v[124:127], v[186:189], v[170:173], v[124:127]
	v_mfma_f32_16x16x32_bf16 v[120:123], v[186:189], v[174:177], v[120:123]
	v_mfma_f32_16x16x32_bf16 v[116:119], v[186:189], v[182:185], v[116:119]
	v_mfma_f32_16x16x32_bf16 v[112:115], v[190:193], v[166:169], v[112:115]
	v_mfma_f32_16x16x32_bf16 v[108:111], v[190:193], v[170:173], v[108:111]
	v_mfma_f32_16x16x32_bf16 v[104:107], v[190:193], v[174:177], v[104:107]
	v_mfma_f32_16x16x32_bf16 v[100:103], v[190:193], v[182:185], v[100:103]
	v_mfma_f32_16x16x32_bf16 v[96:99], v[194:197], v[166:169], v[96:99]
	v_mfma_f32_16x16x32_bf16 v[92:95], v[194:197], v[170:173], v[92:95]
	v_mfma_f32_16x16x32_bf16 v[88:91], v[194:197], v[174:177], v[88:91]
	v_mfma_f32_16x16x32_bf16 v[84:87], v[194:197], v[182:185], v[84:87]
	v_mfma_f32_16x16x32_bf16 v[80:83], v[198:201], v[166:169], v[80:83]
	v_mfma_f32_16x16x32_bf16 v[76:79], v[198:201], v[170:173], v[76:79]
	v_mfma_f32_16x16x32_bf16 v[72:75], v[198:201], v[174:177], v[72:75]
	v_mfma_f32_16x16x32_bf16 v[68:71], v[198:201], v[182:185], v[68:71]
	v_mfma_f32_16x16x32_bf16 v[64:67], v[202:205], v[166:169], v[64:67]
	v_mfma_f32_16x16x32_bf16 v[60:63], v[202:205], v[170:173], v[60:63]
	v_mfma_f32_16x16x32_bf16 v[56:59], v[202:205], v[174:177], v[56:59]
	v_mfma_f32_16x16x32_bf16 v[52:55], v[202:205], v[182:185], v[52:55]
	v_mfma_f32_16x16x32_bf16 v[48:51], v[206:209], v[166:169], v[48:51]
	v_mfma_f32_16x16x32_bf16 v[44:47], v[206:209], v[170:173], v[44:47]
	v_mfma_f32_16x16x32_bf16 v[40:43], v[206:209], v[174:177], v[40:43]
	v_mfma_f32_16x16x32_bf16 v[36:39], v[206:209], v[182:185], v[36:39]
	v_mfma_f32_16x16x32_bf16 v[32:35], v[210:213], v[166:169], v[32:35]
	v_mfma_f32_16x16x32_bf16 v[28:31], v[210:213], v[170:173], v[28:31]
	v_mfma_f32_16x16x32_bf16 v[24:27], v[210:213], v[174:177], v[24:27]
	v_mfma_f32_16x16x32_bf16 v[20:23], v[210:213], v[182:185], v[20:23]
	v_mfma_f32_16x16x32_bf16 v[16:19], v[214:217], v[166:169], v[16:19]
	v_mfma_f32_16x16x32_bf16 v[12:15], v[214:217], v[170:173], v[12:15]
	v_mfma_f32_16x16x32_bf16 v[8:11], v[214:217], v[174:177], v[8:11]
	v_mfma_f32_16x16x32_bf16 v[2:5], v[214:217], v[182:185], v[4:7]
	v_add_u32_e32 v0, s26, v159
	s_nop 0
	v_add_u32_e32 v6, v0, v157
	v_add_u32_e32 v0, v0, v158
	ds_read_b128 v[166:169], v6 offset:32768
	ds_read_b128 v[170:173], v6 offset:34816
	ds_read_b128 v[174:177], v6 offset:36864
	ds_read_b128 v[182:185], v6 offset:38912
	ds_read_b128 v[186:189], v0
	ds_read_b128 v[190:193], v0 offset:2048
	ds_read_b128 v[194:197], v0 offset:4096
	ds_read_b128 v[198:201], v0 offset:6144
	ds_read_b128 v[202:205], v0 offset:8192
	ds_read_b128 v[206:209], v0 offset:10240
	ds_read_b128 v[210:213], v0 offset:12288
	ds_read_b128 v[214:217], v0 offset:14336
	s_waitcnt lgkmcnt(0)
	v_mfma_f32_16x16x32_bf16 v[128:131], v[186:189], v[166:169], v[128:131]
	v_mfma_f32_16x16x32_bf16 v[124:127], v[186:189], v[170:173], v[124:127]
	v_mfma_f32_16x16x32_bf16 v[120:123], v[186:189], v[174:177], v[120:123]
	v_mfma_f32_16x16x32_bf16 v[116:119], v[186:189], v[182:185], v[116:119]
	v_mfma_f32_16x16x32_bf16 v[112:115], v[190:193], v[166:169], v[112:115]
	v_mfma_f32_16x16x32_bf16 v[108:111], v[190:193], v[170:173], v[108:111]
	v_mfma_f32_16x16x32_bf16 v[104:107], v[190:193], v[174:177], v[104:107]
	v_mfma_f32_16x16x32_bf16 v[100:103], v[190:193], v[182:185], v[100:103]
	v_mfma_f32_16x16x32_bf16 v[96:99], v[194:197], v[166:169], v[96:99]
	v_mfma_f32_16x16x32_bf16 v[92:95], v[194:197], v[170:173], v[92:95]
	v_mfma_f32_16x16x32_bf16 v[88:91], v[194:197], v[174:177], v[88:91]
	v_mfma_f32_16x16x32_bf16 v[84:87], v[194:197], v[182:185], v[84:87]
	v_mfma_f32_16x16x32_bf16 v[80:83], v[198:201], v[166:169], v[80:83]
	v_mfma_f32_16x16x32_bf16 v[76:79], v[198:201], v[170:173], v[76:79]
	v_mfma_f32_16x16x32_bf16 v[72:75], v[198:201], v[174:177], v[72:75]
	v_mfma_f32_16x16x32_bf16 v[68:71], v[198:201], v[182:185], v[68:71]
	v_mfma_f32_16x16x32_bf16 v[64:67], v[202:205], v[166:169], v[64:67]
	v_mfma_f32_16x16x32_bf16 v[60:63], v[202:205], v[170:173], v[60:63]
	v_mfma_f32_16x16x32_bf16 v[56:59], v[202:205], v[174:177], v[56:59]
	v_mfma_f32_16x16x32_bf16 v[52:55], v[202:205], v[182:185], v[52:55]
	v_mfma_f32_16x16x32_bf16 v[48:51], v[206:209], v[166:169], v[48:51]
	v_mfma_f32_16x16x32_bf16 v[44:47], v[206:209], v[170:173], v[44:47]
	v_mfma_f32_16x16x32_bf16 v[40:43], v[206:209], v[174:177], v[40:43]
	v_mfma_f32_16x16x32_bf16 v[36:39], v[206:209], v[182:185], v[36:39]
	v_mfma_f32_16x16x32_bf16 v[32:35], v[210:213], v[166:169], v[32:35]
	v_mfma_f32_16x16x32_bf16 v[28:31], v[210:213], v[170:173], v[28:31]
	v_mfma_f32_16x16x32_bf16 v[24:27], v[210:213], v[174:177], v[24:27]
	v_mfma_f32_16x16x32_bf16 v[20:23], v[210:213], v[182:185], v[20:23]
	v_mfma_f32_16x16x32_bf16 v[16:19], v[214:217], v[166:169], v[16:19]
	v_mfma_f32_16x16x32_bf16 v[12:15], v[214:217], v[170:173], v[12:15]
	v_mfma_f32_16x16x32_bf16 v[8:11], v[214:217], v[174:177], v[8:11]
	v_mfma_f32_16x16x32_bf16 v[4:7], v[214:217], v[182:185], v[2:5]

; template <class AF>
; DI void g256_mainloop_t(int tid, const AF& af, const bft* Bt, int ldb, int bcol, int K, f32x4 (&acc)[8][4]) {
;     ...
;   for (int kt = 0; kt < nk; ++kt) {
;     asm volatile("s_waitcnt vmcnt(0)" ::: "memory");
;     __syncthreads();
;     char* cur = smem + (kt & 1) * 65536; char* nxt = smem + ((kt + 1) & 1) * 65536;
;     if (tid < 256) {
;       if (kt + 1 < nk) g256_stage(tid, af, Bt, ldb, bcol, kt + 1, nxt, nxt + 32768);
;       g256_compute<0, 2>(tid, cur, cur + 32768, acc);
;     } else {
;       g256_compute<0, 1>(tid, cur, cur + 32768, acc);
;       if (kt + 1 < nk) g256_stage(tid, af, Bt, ldb, bcol, kt + 1, nxt, nxt + 32768);
;       g256_compute<1, 2>(tid, cur, cur + 32768, acc);
;     }
.LBB0_475:
	s_add_i32 s16, s18, 0xffff0000
	s_waitcnt vmcnt(0)
	s_and_b32 s16, s16, 0x10000
	s_add_i32 s26, s16, 16
	s_and_b32 s16, s18, 0x10000
	s_add_i32 s27, s16, 16
	s_waitcnt vmcnt(0) lgkmcnt(0)
	s_barrier
	s_and_saveexec_b64 s[16:17], vcc
	s_xor_b64 s[16:17], exec, s[16:17]
	s_cbranch_execz .LBB0_479
	v_add_u32_e32 v0, s26, v155
	v_add_u32_e32 v2, v0, v157
	v_add_u32_e32 v0, v0, v158
	ds_read_b128 v[166:169], v2 offset:32768
	ds_read_b128 v[170:173], v2 offset:34816
	ds_read_b128 v[174:177], v2 offset:36864
	ds_read_b128 v[182:185], v2 offset:38912
	ds_read_b128 v[186:189], v0
	ds_read_b128 v[190:193], v0 offset:2048
	ds_read_b128 v[194:197], v0 offset:4096
	ds_read_b128 v[198:201], v0 offset:6144
	ds_read_b128 v[202:205], v0 offset:8192
	ds_read_b128 v[206:209], v0 offset:10240
	ds_read_b128 v[210:213], v0 offset:12288
	ds_read_b128 v[214:217], v0 offset:14336
	s_waitcnt lgkmcnt(7)
	v_mfma_f32_16x16x32_bf16 v[128:131], v[186:189], v[166:169], v[128:131]
	v_mfma_f32_16x16x32_bf16 v[124:127], v[186:189], v[170:173], v[124:127]
	v_mfma_f32_16x16x32_bf16 v[120:123], v[186:189], v[174:177], v[120:123]
	v_mfma_f32_16x16x32_bf16 v[116:119], v[186:189], v[182:185], v[116:119]
	s_waitcnt lgkmcnt(6)
	v_mfma_f32_16x16x32_bf16 v[112:115], v[190:193], v[166:169], v[112:115]
	v_mfma_f32_16x16x32_bf16 v[108:111], v[190:193], v[170:173], v[108:111]
	v_mfma_f32_16x16x32_bf16 v[104:107], v[190:193], v[174:177], v[104:107]
	v_mfma_f32_16x16x32_bf16 v[100:103], v[190:193], v[182:185], v[100:103]
	s_waitcnt lgkmcnt(5)
	v_mfma_f32_16x16x32_bf16 v[96:99], v[194:197], v[166:169], v[96:99]
	v_mfma_f32_16x16x32_bf16 v[92:95], v[194:197], v[170:173], v[92:95]
	v_mfma_f32_16x16x32_bf16 v[88:91], v[194:197], v[174:177], v[88:91]
	v_mfma_f32_16x16x32_bf16 v[84:87], v[194:197], v[182:185], v[84:87]
	s_waitcnt lgkmcnt(4)
	v_mfma_f32_16x16x32_bf16 v[80:83], v[198:201], v[166:169], v[80:83]
	v_mfma_f32_16x16x32_bf16 v[76:79], v[198:201], v[170:173], v[76:79]
	v_mfma_f32_16x16x32_bf16 v[72:75], v[198:201], v[174:177], v[72:75]
	v_mfma_f32_16x16x32_bf16 v[68:71], v[198:201], v[182:185], v[68:71]
	s_waitcnt lgkmcnt(3)
	v_mfma_f32_16x16x32_bf16 v[64:67], v[202:205], v[166:169], v[64:67]
	v_mfma_f32_16x16x32_bf16 v[60:63], v[202:205], v[170:173], v[60:63]
	v_mfma_f32_16x16x32_bf16 v[56:59], v[202:205], v[174:177], v[56:59]
	v_mfma_f32_16x16x32_bf16 v[52:55], v[202:205], v[182:185], v[52:55]
	s_waitcnt lgkmcnt(2)
	v_mfma_f32_16x16x32_bf16 v[48:51], v[206:209], v[166:169], v[48:51]
	v_mfma_f32_16x16x32_bf16 v[44:47], v[206:209], v[170:173], v[44:47]
	v_mfma_f32_16x16x32_bf16 v[40:43], v[206:209], v[174:177], v[40:43]
	v_mfma_f32_16x16x32_bf16 v[36:39], v[206:209], v[182:185], v[36:39]
	s_waitcnt lgkmcnt(1)
	v_mfma_f32_16x16x32_bf16 v[32:35], v[210:213], v[166:169], v[32:35]
	v_mfma_f32_16x16x32_bf16 v[28:31], v[210:213], v[170:173], v[28:31]
	v_mfma_f32_16x16x32_bf16 v[24:27], v[210:213], v[174:177], v[24:27]
	v_mfma_f32_16x16x32_bf16 v[20:23], v[210:213], v[182:185], v[20:23]
	s_waitcnt lgkmcnt(0)
	v_mfma_f32_16x16x32_bf16 v[16:19], v[214:217], v[166:169], v[16:19]
	v_mfma_f32_16x16x32_bf16 v[12:15], v[214:217], v[170:173], v[12:15]
	v_mfma_f32_16x16x32_bf16 v[8:11], v[214:217], v[174:177], v[8:11]
	v_mfma_f32_16x16x32_bf16 v[2:5], v[214:217], v[182:185], v[4:7]
	s_cmp_gt_u32 s19, 6
	s_cbranch_scc1 .LBB0_478
	v_add_u32_e32 v6, s13, v164
	v_ashrrev_i32_e32 v7, 31, v6
	v_add_u32_e32 v0, s27, v151
	v_lshlrev_b64 v[6:7], 11, v[6:7]
	v_readfirstlane_b32 s30, v0
	v_lshl_add_u64 v[6:7], v[132:133], 0, v[6:7]
	s_mov_b32 m0, s30
	v_add_u32_e32 v165, s27, v152
	global_load_lds_dwordx4 v[6:7], off
	v_add_u32_e32 v6, s13, v163
	v_ashrrev_i32_e32 v7, 31, v6
	v_lshlrev_b64 v[6:7], 11, v[6:7]
	v_readfirstlane_b32 s30, v165
	v_lshl_add_u64 v[6:7], v[134:135], 0, v[6:7]
	s_mov_b32 m0, s30
	v_add_u32_e32 v166, s27, v153
	global_load_lds_dwordx4 v[6:7], off
	v_add_u32_e32 v6, s13, v162
	v_ashrrev_i32_e32 v7, 31, v6
	v_lshlrev_b64 v[6:7], 11, v[6:7]
	v_readfirstlane_b32 s30, v166
	v_lshl_add_u64 v[6:7], v[136:137], 0, v[6:7]
	s_mov_b32 m0, s30
	v_add_u32_e32 v167, s27, v154
	global_load_lds_dwordx4 v[6:7], off
	v_add_u32_e32 v6, s13, v161
	v_ashrrev_i32_e32 v7, 31, v6
	v_lshlrev_b64 v[6:7], 11, v[6:7]
	v_readfirstlane_b32 s30, v167
	v_add_u32_e32 v0, 0x8000, v0
	v_lshl_add_u64 v[6:7], v[138:139], 0, v[6:7]
	s_mov_b32 m0, s30
	v_readfirstlane_b32 s30, v0
	v_add_u32_e32 v0, 0x8000, v165
	global_load_lds_dwordx4 v[6:7], off
	v_lshl_add_u64 v[6:7], s[14:15], 0, v[140:141]
	s_mov_b32 m0, s30
	v_readfirstlane_b32 s30, v0
	v_add_u32_e32 v0, 0x8000, v166
	global_load_lds_dwordx4 v[6:7], off
	v_lshl_add_u64 v[6:7], s[14:15], 0, v[142:143]
	s_mov_b32 m0, s30
	v_readfirstlane_b32 s30, v0
	v_add_u32_e32 v0, 0x8000, v167
	global_load_lds_dwordx4 v[6:7], off
	v_lshl_add_u64 v[6:7], s[14:15], 0, v[144:145]
	s_mov_b32 m0, s30
	v_readfirstlane_b32 s30, v0
	global_load_lds_dwordx4 v[6:7], off
	v_lshl_add_u64 v[6:7], s[14:15], 0, v[146:147]
	s_mov_b32 m0, s30
	s_nop 0
	global_load_lds_dwordx4 v[6:7], off
; template <int KK0, int KK1>
; DI void g256_compute(int tid, const char* sA, const char* sB, f32x4 (&acc)[8][4]) {
;     ...
;   for (int kk = KK0; kk < KK1; ++kk) {
;     bf16x8 b[4], a[4], a2[4];
; #pragma unroll
;     for (int n = 0; n < 4; ++n) { int row = wc * 64 + n * 16 + fr; b[n] = *(const bf16x8*)(sB + row * 128 + (((kk * 4 + fq) ^ (row & 7)) << 4)); }
; #pragma unroll
;     for (int m = 0; m < 4; ++m) { int row = wr * 128 + m * 16 + fr; a[m] = *(const bf16x8*)(sA + row * 128 + (((kk * 4 + fq) ^ (row & 7)) << 4)); }
;     __builtin_amdgcn_sched_barrier(0);
; #pragma unroll
;     for (int m = 0; m < 4; ++m) { int row = wr * 128 + (4 + m) * 16 + fr; a2[m] = *(const bf16x8*)(sA + row * 128 + (((kk * 4 + fq) ^ (row & 7)) << 4)); }
;     __builtin_amdgcn_s_setprio(1);
; #pragma unroll
;     for (int m = 0; m < 4; ++m)
; #pragma unroll
;       for (int n = 0; n < 4; ++n) acc[m][n] = __builtin_amdgcn_mfma_f32_16x16x32_bf16(a[m], b[n], acc[m][n], 0, 0, 0);
;     __builtin_amdgcn_sched_barrier(0);
; #pragma unroll
;     for (int m = 0; m < 4; ++m)
; #pragma unroll
;       for (int n = 0; n < 4; ++n) acc[4 + m][n] = __builtin_amdgcn_mfma_f32_16x16x32_bf16(a2[m], b[n], acc[4 + m][n], 0, 0, 0);
;     __builtin_amdgcn_s_setprio(0);
;     __builtin_amdgcn_sched_barrier(0);
;   }
.LBB0_478:
	v_add_u32_e32 v0, s26, v159
	v_add_u32_e32 v6, v0, v157
	v_add_u32_e32 v0, v0, v158
	ds_read_b128 v[166:169], v6 offset:32768
	ds_read_b128 v[170:173], v6 offset:34816
	ds_read_b128 v[174:177], v6 offset:36864
	ds_read_b128 v[182:185], v6 offset:38912
	ds_read_b128 v[186:189], v0
	ds_read_b128 v[190:193], v0 offset:2048
	ds_read_b128 v[194:197], v0 offset:4096
	ds_read_b128 v[198:201], v0 offset:6144
	ds_read_b128 v[202:205], v0 offset:8192
	ds_read_b128 v[206:209], v0 offset:10240
	ds_read_b128 v[210:213], v0 offset:12288
	ds_read_b128 v[214:217], v0 offset:14336
	s_waitcnt lgkmcnt(0)
	v_mfma_f32_16x16x32_bf16 v[128:131], v[186:189], v[166:169], v[128:131]
	v_mfma_f32_16x16x32_bf16 v[124:127], v[186:189], v[170:173], v[124:127]
	v_mfma_f32_16x16x32_bf16 v[120:123], v[186:189], v[174:177], v[120:123]
	v_mfma_f32_16x16x32_bf16 v[116:119], v[186:189], v[182:185], v[116:119]
	v_mfma_f32_16x16x32_bf16 v[112:115], v[190:193], v[166:169], v[112:115]
	v_mfma_f32_16x16x32_bf16 v[108:111], v[190:193], v[170:173], v[108:111]
	v_mfma_f32_16x16x32_bf16 v[104:107], v[190:193], v[174:177], v[104:107]
	v_mfma_f32_16x16x32_bf16 v[100:103], v[190:193], v[182:185], v[100:103]
	v_mfma_f32_16x16x32_bf16 v[96:99], v[194:197], v[166:169], v[96:99]
	v_mfma_f32_16x16x32_bf16 v[92:95], v[194:197], v[170:173], v[92:95]
	v_mfma_f32_16x16x32_bf16 v[88:91], v[194:197], v[174:177], v[88:91]
	v_mfma_f32_16x16x32_bf16 v[84:87], v[194:197], v[182:185], v[84:87]
	v_mfma_f32_16x16x32_bf16 v[80:83], v[198:201], v[166:169], v[80:83]
	v_mfma_f32_16x16x32_bf16 v[76:79], v[198:201], v[170:173], v[76:79]
	v_mfma_f32_16x16x32_bf16 v[72:75], v[198:201], v[174:177], v[72:75]
	v_mfma_f32_16x16x32_bf16 v[68:71], v[198:201], v[182:185], v[68:71]
	v_mfma_f32_16x16x32_bf16 v[64:67], v[202:205], v[166:169], v[64:67]
	v_mfma_f32_16x16x32_bf16 v[60:63], v[202:205], v[170:173], v[60:63]
	v_mfma_f32_16x16x32_bf16 v[56:59], v[202:205], v[174:177], v[56:59]
	v_mfma_f32_16x16x32_bf16 v[52:55], v[202:205], v[182:185], v[52:55]
	v_mfma_f32_16x16x32_bf16 v[48:51], v[206:209], v[166:169], v[48:51]
	v_mfma_f32_16x16x32_bf16 v[44:47], v[206:209], v[170:173], v[44:47]
	v_mfma_f32_16x16x32_bf16 v[40:43], v[206:209], v[174:177], v[40:43]
	v_mfma_f32_16x16x32_bf16 v[36:39], v[206:209], v[182:185], v[36:39]
	v_mfma_f32_16x16x32_bf16 v[32:35], v[210:213], v[166:169], v[32:35]
	v_mfma_f32_16x16x32_bf16 v[28:31], v[210:213], v[170:173], v[28:31]
	v_mfma_f32_16x16x32_bf16 v[24:27], v[210:213], v[174:177], v[24:27]
	v_mfma_f32_16x16x32_bf16 v[20:23], v[210:213], v[182:185], v[20:23]
	v_mfma_f32_16x16x32_bf16 v[16:19], v[214:217], v[166:169], v[16:19]
	v_mfma_f32_16x16x32_bf16 v[12:15], v[214:217], v[170:173], v[12:15]
	v_mfma_f32_16x16x32_bf16 v[8:11], v[214:217], v[174:177], v[8:11]
	v_mfma_f32_16x16x32_bf16 v[4:7], v[214:217], v[182:185], v[2:5]

; template <int KK0, int KK1>
; DI void g256_compute(int tid, const char* sA, const char* sB, f32x4 (&acc)[8][4]) {
;     ...
;   for (int kk = KK0; kk < KK1; ++kk) {
;     bf16x8 b[4], a[4], a2[4];
; #pragma unroll
;     for (int n = 0; n < 4; ++n) { int row = wc * 64 + n * 16 + fr; b[n] = *(const bf16x8*)(sB + row * 128 + (((kk * 4 + fq) ^ (row & 7)) << 4)); }
; #pragma unroll
;     for (int m = 0; m < 4; ++m) { int row = wr * 128 + m * 16 + fr; a[m] = *(const bf16x8*)(sA + row * 128 + (((kk * 4 + fq) ^ (row & 7)) << 4)); }
;     __builtin_amdgcn_sched_barrier(0);
; #pragma unroll
;     for (int m = 0; m < 4; ++m) { int row = wr * 128 + (4 + m) * 16 + fr; a2[m] = *(const bf16x8*)(sA + row * 128 + (((kk * 4 + fq) ^ (row & 7)) << 4)); }
;     __builtin_amdgcn_s_setprio(1);
; #pragma unroll
;     for (int m = 0; m < 4; ++m)
; #pragma unroll
;       for (int n = 0; n < 4; ++n) acc[m][n] = __builtin_amdgcn_mfma_f32_16x16x32_bf16(a[m], b[n], acc[m][n], 0, 0, 0);
;     __builtin_amdgcn_sched_barrier(0);
; #pragma unroll
;     for (int m = 0; m < 4; ++m)
; #pragma unroll
;       for (int n = 0; n < 4; ++n) acc[4 + m][n] = __builtin_amdgcn_mfma_f32_16x16x32_bf16(a2[m], b[n], acc[4 + m][n], 0, 0, 0);
;     __builtin_amdgcn_s_setprio(0);
;     __builtin_amdgcn_sched_barrier(0);
;   }
; template <class AF>
; DI void g256_mainloop_t(int tid, const AF& af, const bft* Bt, int ldb, int bcol, int K, f32x4 (&acc)[8][4]) {
;     ...
;     if (tid < 256) {
;       if (kt + 1 < nk) g256_stage(tid, af, Bt, ldb, bcol, kt + 1, nxt, nxt + 32768);
;       g256_compute<0, 2>(tid, cur, cur + 32768, acc);
.LBB0_597:
	v_add_u32_e32 v0, s43, v168
	v_add_u32_e32 v2, v0, v165
	v_add_u32_e32 v0, v0, v166
	ds_read_b128 v[174:177], v2 offset:32768
	ds_read_b128 v[182:185], v2 offset:34816
	ds_read_b128 v[186:189], v2 offset:36864
	ds_read_b128 v[190:193], v2 offset:38912
	ds_read_b128 v[194:197], v0
	ds_read_b128 v[198:201], v0 offset:2048
	ds_read_b128 v[202:205], v0 offset:4096
	ds_read_b128 v[206:209], v0 offset:6144
	ds_read_b128 v[210:213], v0 offset:8192
	ds_read_b128 v[214:217], v0 offset:10240
	ds_read_b128 v[218:221], v0 offset:12288
	ds_read_b128 v[222:225], v0 offset:14336
	s_waitcnt lgkmcnt(0)
	v_mfma_f32_16x16x32_bf16 v[128:131], v[194:197], v[174:177], v[128:131]
	v_mfma_f32_16x16x32_bf16 v[124:127], v[194:197], v[182:185], v[124:127]
	v_mfma_f32_16x16x32_bf16 v[120:123], v[194:197], v[186:189], v[120:123]
	v_mfma_f32_16x16x32_bf16 v[116:119], v[194:197], v[190:193], v[116:119]
	v_mfma_f32_16x16x32_bf16 v[112:115], v[198:201], v[174:177], v[112:115]
	v_mfma_f32_16x16x32_bf16 v[108:111], v[198:201], v[182:185], v[108:111]
	v_mfma_f32_16x16x32_bf16 v[104:107], v[198:201], v[186:189], v[104:107]
	v_mfma_f32_16x16x32_bf16 v[100:103], v[198:201], v[190:193], v[100:103]
	v_mfma_f32_16x16x32_bf16 v[96:99], v[202:205], v[174:177], v[96:99]
	v_mfma_f32_16x16x32_bf16 v[92:95], v[202:205], v[182:185], v[92:95]
	v_mfma_f32_16x16x32_bf16 v[88:91], v[202:205], v[186:189], v[88:91]
	v_mfma_f32_16x16x32_bf16 v[84:87], v[202:205], v[190:193], v[84:87]
	v_mfma_f32_16x16x32_bf16 v[80:83], v[206:209], v[174:177], v[80:83]
	v_mfma_f32_16x16x32_bf16 v[76:79], v[206:209], v[182:185], v[76:79]
	v_mfma_f32_16x16x32_bf16 v[72:75], v[206:209], v[186:189], v[72:75]
	v_mfma_f32_16x16x32_bf16 v[68:71], v[206:209], v[190:193], v[68:71]
	v_mfma_f32_16x16x32_bf16 v[64:67], v[210:213], v[174:177], v[64:67]
	v_mfma_f32_16x16x32_bf16 v[60:63], v[210:213], v[182:185], v[60:63]
	v_mfma_f32_16x16x32_bf16 v[56:59], v[210:213], v[186:189], v[56:59]
	v_mfma_f32_16x16x32_bf16 v[52:55], v[210:213], v[190:193], v[52:55]
	v_mfma_f32_16x16x32_bf16 v[48:51], v[214:217], v[174:177], v[48:51]
	v_mfma_f32_16x16x32_bf16 v[44:47], v[214:217], v[182:185], v[44:47]
	v_mfma_f32_16x16x32_bf16 v[40:43], v[214:217], v[186:189], v[40:43]
	v_mfma_f32_16x16x32_bf16 v[36:39], v[214:217], v[190:193], v[36:39]
	v_mfma_f32_16x16x32_bf16 v[32:35], v[218:221], v[174:177], v[32:35]
	v_mfma_f32_16x16x32_bf16 v[28:31], v[218:221], v[182:185], v[28:31]
	v_mfma_f32_16x16x32_bf16 v[24:27], v[218:221], v[186:189], v[24:27]
	v_mfma_f32_16x16x32_bf16 v[20:23], v[218:221], v[190:193], v[20:23]
	v_mfma_f32_16x16x32_bf16 v[16:19], v[222:225], v[174:177], v[16:19]
	v_mfma_f32_16x16x32_bf16 v[12:15], v[222:225], v[182:185], v[12:15]
	v_mfma_f32_16x16x32_bf16 v[8:11], v[222:225], v[186:189], v[8:11]
	v_mfma_f32_16x16x32_bf16 v[2:5], v[222:225], v[190:193], v[4:7]
	v_add_u32_e32 v0, s43, v167
	s_nop 0
	v_add_u32_e32 v6, v0, v165
	v_add_u32_e32 v0, v0, v166
	ds_read_b128 v[174:177], v6 offset:32768
	ds_read_b128 v[182:185], v6 offset:34816
	ds_read_b128 v[186:189], v6 offset:36864
	ds_read_b128 v[190:193], v6 offset:38912
	ds_read_b128 v[194:197], v0
	ds_read_b128 v[198:201], v0 offset:2048
	ds_read_b128 v[202:205], v0 offset:4096
	ds_read_b128 v[206:209], v0 offset:6144
	ds_read_b128 v[210:213], v0 offset:8192
	ds_read_b128 v[214:217], v0 offset:10240
	ds_read_b128 v[218:221], v0 offset:12288
	ds_read_b128 v[222:225], v0 offset:14336
	s_waitcnt lgkmcnt(0)
	v_mfma_f32_16x16x32_bf16 v[128:131], v[194:197], v[174:177], v[128:131]
	v_mfma_f32_16x16x32_bf16 v[124:127], v[194:197], v[182:185], v[124:127]
	v_mfma_f32_16x16x32_bf16 v[120:123], v[194:197], v[186:189], v[120:123]
	v_mfma_f32_16x16x32_bf16 v[116:119], v[194:197], v[190:193], v[116:119]
	v_mfma_f32_16x16x32_bf16 v[112:115], v[198:201], v[174:177], v[112:115]
	v_mfma_f32_16x16x32_bf16 v[108:111], v[198:201], v[182:185], v[108:111]
	v_mfma_f32_16x16x32_bf16 v[104:107], v[198:201], v[186:189], v[104:107]
	v_mfma_f32_16x16x32_bf16 v[100:103], v[198:201], v[190:193], v[100:103]
	v_mfma_f32_16x16x32_bf16 v[96:99], v[202:205], v[174:177], v[96:99]
	v_mfma_f32_16x16x32_bf16 v[92:95], v[202:205], v[182:185], v[92:95]
	v_mfma_f32_16x16x32_bf16 v[88:91], v[202:205], v[186:189], v[88:91]
	v_mfma_f32_16x16x32_bf16 v[84:87], v[202:205], v[190:193], v[84:87]
	v_mfma_f32_16x16x32_bf16 v[80:83], v[206:209], v[174:177], v[80:83]
	v_mfma_f32_16x16x32_bf16 v[76:79], v[206:209], v[182:185], v[76:79]
	v_mfma_f32_16x16x32_bf16 v[72:75], v[206:209], v[186:189], v[72:75]
	v_mfma_f32_16x16x32_bf16 v[68:71], v[206:209], v[190:193], v[68:71]
	v_mfma_f32_16x16x32_bf16 v[64:67], v[210:213], v[174:177], v[64:67]
	v_mfma_f32_16x16x32_bf16 v[60:63], v[210:213], v[182:185], v[60:63]
	v_mfma_f32_16x16x32_bf16 v[56:59], v[210:213], v[186:189], v[56:59]
	v_mfma_f32_16x16x32_bf16 v[52:55], v[210:213], v[190:193], v[52:55]
	v_mfma_f32_16x16x32_bf16 v[48:51], v[214:217], v[174:177], v[48:51]
	v_mfma_f32_16x16x32_bf16 v[44:47], v[214:217], v[182:185], v[44:47]
	v_mfma_f32_16x16x32_bf16 v[40:43], v[214:217], v[186:189], v[40:43]
	v_mfma_f32_16x16x32_bf16 v[36:39], v[214:217], v[190:193], v[36:39]
	v_mfma_f32_16x16x32_bf16 v[32:35], v[218:221], v[174:177], v[32:35]
	v_mfma_f32_16x16x32_bf16 v[28:31], v[218:221], v[182:185], v[28:31]
	v_mfma_f32_16x16x32_bf16 v[24:27], v[218:221], v[186:189], v[24:27]
	v_mfma_f32_16x16x32_bf16 v[20:23], v[218:221], v[190:193], v[20:23]
	v_mfma_f32_16x16x32_bf16 v[16:19], v[222:225], v[174:177], v[16:19]
	v_mfma_f32_16x16x32_bf16 v[12:15], v[222:225], v[182:185], v[12:15]
	v_mfma_f32_16x16x32_bf16 v[8:11], v[222:225], v[186:189], v[8:11]
	v_mfma_f32_16x16x32_bf16 v[4:7], v[222:225], v[190:193], v[2:5]

; template <class AF>
; DI void g256_mainloop_t(int tid, const AF& af, const bft* Bt, int ldb, int bcol, int K, f32x4 (&acc)[8][4]) {
;     ...
;   for (int kt = 0; kt < nk; ++kt) {
;     asm volatile("s_waitcnt vmcnt(0)" ::: "memory");
;     __syncthreads();
;     char* cur = smem + (kt & 1) * 65536; char* nxt = smem + ((kt + 1) & 1) * 65536;
;     if (tid < 256) {
;       if (kt + 1 < nk) g256_stage(tid, af, Bt, ldb, bcol, kt + 1, nxt, nxt + 32768);
;       g256_compute<0, 2>(tid, cur, cur + 32768, acc);
;     } else {
;       g256_compute<0, 1>(tid, cur, cur + 32768, acc);
;       if (kt + 1 < nk) g256_stage(tid, af, Bt, ldb, bcol, kt + 1, nxt, nxt + 32768);
;       g256_compute<1, 2>(tid, cur, cur + 32768, acc);
;     }
.LBB0_599:
	s_add_i32 s10, s42, 0xffff0000
	s_waitcnt vmcnt(0)
	s_and_b32 s10, s10, 0x10000
	s_add_i32 s43, s10, 16
	s_and_b32 s10, s42, 0x10000
	s_add_i32 s44, s10, 16
	s_waitcnt vmcnt(0) lgkmcnt(0)
	s_barrier
	s_and_saveexec_b64 s[10:11], s[8:9]
	s_xor_b64 s[18:19], exec, s[10:11]
	s_cbranch_execz .LBB0_619
	v_add_u32_e32 v0, s43, v164
	v_add_u32_e32 v2, v0, v165
	v_add_u32_e32 v0, v0, v166
	ds_read_b128 v[174:177], v2 offset:32768
	ds_read_b128 v[182:185], v2 offset:34816
	ds_read_b128 v[186:189], v2 offset:36864
	ds_read_b128 v[190:193], v2 offset:38912
	ds_read_b128 v[194:197], v0
	ds_read_b128 v[198:201], v0 offset:2048
	ds_read_b128 v[202:205], v0 offset:4096
	ds_read_b128 v[206:209], v0 offset:6144
	ds_read_b128 v[210:213], v0 offset:8192
	ds_read_b128 v[214:217], v0 offset:10240
	ds_read_b128 v[218:221], v0 offset:12288
	ds_read_b128 v[222:225], v0 offset:14336
	s_waitcnt lgkmcnt(7)
	v_mfma_f32_16x16x32_bf16 v[128:131], v[194:197], v[174:177], v[128:131]
	v_mfma_f32_16x16x32_bf16 v[124:127], v[194:197], v[182:185], v[124:127]
	v_mfma_f32_16x16x32_bf16 v[120:123], v[194:197], v[186:189], v[120:123]
	v_mfma_f32_16x16x32_bf16 v[116:119], v[194:197], v[190:193], v[116:119]
	s_waitcnt lgkmcnt(6)
	v_mfma_f32_16x16x32_bf16 v[112:115], v[198:201], v[174:177], v[112:115]
	v_mfma_f32_16x16x32_bf16 v[108:111], v[198:201], v[182:185], v[108:111]
	v_mfma_f32_16x16x32_bf16 v[104:107], v[198:201], v[186:189], v[104:107]
	v_mfma_f32_16x16x32_bf16 v[100:103], v[198:201], v[190:193], v[100:103]
	s_waitcnt lgkmcnt(5)
	v_mfma_f32_16x16x32_bf16 v[96:99], v[202:205], v[174:177], v[96:99]
	v_mfma_f32_16x16x32_bf16 v[92:95], v[202:205], v[182:185], v[92:95]
	v_mfma_f32_16x16x32_bf16 v[88:91], v[202:205], v[186:189], v[88:91]
	v_mfma_f32_16x16x32_bf16 v[84:87], v[202:205], v[190:193], v[84:87]
	s_waitcnt lgkmcnt(4)
	v_mfma_f32_16x16x32_bf16 v[80:83], v[206:209], v[174:177], v[80:83]
	v_mfma_f32_16x16x32_bf16 v[76:79], v[206:209], v[182:185], v[76:79]
	v_mfma_f32_16x16x32_bf16 v[72:75], v[206:209], v[186:189], v[72:75]
	v_mfma_f32_16x16x32_bf16 v[68:71], v[206:209], v[190:193], v[68:71]
	s_waitcnt lgkmcnt(3)
	v_mfma_f32_16x16x32_bf16 v[64:67], v[210:213], v[174:177], v[64:67]
	v_mfma_f32_16x16x32_bf16 v[60:63], v[210:213], v[182:185], v[60:63]
	v_mfma_f32_16x16x32_bf16 v[56:59], v[210:213], v[186:189], v[56:59]
	v_mfma_f32_16x16x32_bf16 v[52:55], v[210:213], v[190:193], v[52:55]
	s_waitcnt lgkmcnt(2)
	v_mfma_f32_16x16x32_bf16 v[48:51], v[214:217], v[174:177], v[48:51]
	v_mfma_f32_16x16x32_bf16 v[44:47], v[214:217], v[182:185], v[44:47]
	v_mfma_f32_16x16x32_bf16 v[40:43], v[214:217], v[186:189], v[40:43]
	v_mfma_f32_16x16x32_bf16 v[36:39], v[214:217], v[190:193], v[36:39]
	s_waitcnt lgkmcnt(1)
	v_mfma_f32_16x16x32_bf16 v[32:35], v[218:221], v[174:177], v[32:35]
	v_mfma_f32_16x16x32_bf16 v[28:31], v[218:221], v[182:185], v[28:31]
	v_mfma_f32_16x16x32_bf16 v[24:27], v[218:221], v[186:189], v[24:27]
	v_mfma_f32_16x16x32_bf16 v[20:23], v[218:221], v[190:193], v[20:23]
	s_waitcnt lgkmcnt(0)
	v_mfma_f32_16x16x32_bf16 v[16:19], v[222:225], v[174:177], v[16:19]
	v_mfma_f32_16x16x32_bf16 v[12:15], v[222:225], v[182:185], v[12:15]
	v_mfma_f32_16x16x32_bf16 v[8:11], v[222:225], v[186:189], v[8:11]
	v_mfma_f32_16x16x32_bf16 v[2:5], v[222:225], v[190:193], v[4:7]
	s_cmp_gt_u32 s41, 10
	s_cbranch_scc1 .LBB0_618
	s_cmp_gt_u32 s41, 6
	s_cselect_b64 s[20:21], -1, 0
	s_mov_b64 s[10:11], -1
	s_and_b64 vcc, exec, s[20:21]
	s_cbranch_vccz .LBB0_603
	v_lshl_add_u64 v[6:7], v[146:147], 0, s[16:17]
	s_mov_b64 s[10:11], 0

; template <int KK0, int KK1>
; DI void g256_compute(int tid, const char* sA, const char* sB, f32x4 (&acc)[8][4]) {
;     ...
;   for (int kk = KK0; kk < KK1; ++kk) {
;     bf16x8 b[4], a[4], a2[4];
; #pragma unroll
;     for (int n = 0; n < 4; ++n) { int row = wc * 64 + n * 16 + fr; b[n] = *(const bf16x8*)(sB + row * 128 + (((kk * 4 + fq) ^ (row & 7)) << 4)); }
; #pragma unroll
;     for (int m = 0; m < 4; ++m) { int row = wr * 128 + m * 16 + fr; a[m] = *(const bf16x8*)(sA + row * 128 + (((kk * 4 + fq) ^ (row & 7)) << 4)); }
;     __builtin_amdgcn_sched_barrier(0);
; #pragma unroll
;     for (int m = 0; m < 4; ++m) { int row = wr * 128 + (4 + m) * 16 + fr; a2[m] = *(const bf16x8*)(sA + row * 128 + (((kk * 4 + fq) ^ (row & 7)) << 4)); }
;     __builtin_amdgcn_s_setprio(1);
; #pragma unroll
;     for (int m = 0; m < 4; ++m)
; #pragma unroll
;       for (int n = 0; n < 4; ++n) acc[m][n] = __builtin_amdgcn_mfma_f32_16x16x32_bf16(a[m], b[n], acc[m][n], 0, 0, 0);
;     __builtin_amdgcn_sched_barrier(0);
; #pragma unroll
;     for (int m = 0; m < 4; ++m)
; #pragma unroll
;       for (int n = 0; n < 4; ++n) acc[4 + m][n] = __builtin_amdgcn_mfma_f32_16x16x32_bf16(a2[m], b[n], acc[4 + m][n], 0, 0, 0);
;     __builtin_amdgcn_s_setprio(0);
;     __builtin_amdgcn_sched_barrier(0);
;   }
.LBB0_618:
	v_add_u32_e32 v0, s43, v167
	v_add_u32_e32 v6, v0, v165
	v_add_u32_e32 v0, v0, v166
	ds_read_b128 v[174:177], v6 offset:32768
	ds_read_b128 v[182:185], v6 offset:34816
	ds_read_b128 v[186:189], v6 offset:36864
	ds_read_b128 v[190:193], v6 offset:38912
	ds_read_b128 v[194:197], v0
	ds_read_b128 v[198:201], v0 offset:2048
	ds_read_b128 v[202:205], v0 offset:4096
	ds_read_b128 v[206:209], v0 offset:6144
	ds_read_b128 v[210:213], v0 offset:8192
	ds_read_b128 v[214:217], v0 offset:10240
	ds_read_b128 v[218:221], v0 offset:12288
	ds_read_b128 v[222:225], v0 offset:14336
	s_waitcnt lgkmcnt(0)
	v_mfma_f32_16x16x32_bf16 v[128:131], v[194:197], v[174:177], v[128:131]
	v_mfma_f32_16x16x32_bf16 v[124:127], v[194:197], v[182:185], v[124:127]
	v_mfma_f32_16x16x32_bf16 v[120:123], v[194:197], v[186:189], v[120:123]
	v_mfma_f32_16x16x32_bf16 v[116:119], v[194:197], v[190:193], v[116:119]
	v_mfma_f32_16x16x32_bf16 v[112:115], v[198:201], v[174:177], v[112:115]
	v_mfma_f32_16x16x32_bf16 v[108:111], v[198:201], v[182:185], v[108:111]
	v_mfma_f32_16x16x32_bf16 v[104:107], v[198:201], v[186:189], v[104:107]
	v_mfma_f32_16x16x32_bf16 v[100:103], v[198:201], v[190:193], v[100:103]
	v_mfma_f32_16x16x32_bf16 v[96:99], v[202:205], v[174:177], v[96:99]
	v_mfma_f32_16x16x32_bf16 v[92:95], v[202:205], v[182:185], v[92:95]
	v_mfma_f32_16x16x32_bf16 v[88:91], v[202:205], v[186:189], v[88:91]
	v_mfma_f32_16x16x32_bf16 v[84:87], v[202:205], v[190:193], v[84:87]
	v_mfma_f32_16x16x32_bf16 v[80:83], v[206:209], v[174:177], v[80:83]
	v_mfma_f32_16x16x32_bf16 v[76:79], v[206:209], v[182:185], v[76:79]
	v_mfma_f32_16x16x32_bf16 v[72:75], v[206:209], v[186:189], v[72:75]
	v_mfma_f32_16x16x32_bf16 v[68:71], v[206:209], v[190:193], v[68:71]
	v_mfma_f32_16x16x32_bf16 v[64:67], v[210:213], v[174:177], v[64:67]
	v_mfma_f32_16x16x32_bf16 v[60:63], v[210:213], v[182:185], v[60:63]
	v_mfma_f32_16x16x32_bf16 v[56:59], v[210:213], v[186:189], v[56:59]
	v_mfma_f32_16x16x32_bf16 v[52:55], v[210:213], v[190:193], v[52:55]
	v_mfma_f32_16x16x32_bf16 v[48:51], v[214:217], v[174:177], v[48:51]
	v_mfma_f32_16x16x32_bf16 v[44:47], v[214:217], v[182:185], v[44:47]
	v_mfma_f32_16x16x32_bf16 v[40:43], v[214:217], v[186:189], v[40:43]
	v_mfma_f32_16x16x32_bf16 v[36:39], v[214:217], v[190:193], v[36:39]
	v_mfma_f32_16x16x32_bf16 v[32:35], v[218:221], v[174:177], v[32:35]
	v_mfma_f32_16x16x32_bf16 v[28:31], v[218:221], v[182:185], v[28:31]
	v_mfma_f32_16x16x32_bf16 v[24:27], v[218:221], v[186:189], v[24:27]
	v_mfma_f32_16x16x32_bf16 v[20:23], v[218:221], v[190:193], v[20:23]
	v_mfma_f32_16x16x32_bf16 v[16:19], v[222:225], v[174:177], v[16:19]
	v_mfma_f32_16x16x32_bf16 v[12:15], v[222:225], v[182:185], v[12:15]
	v_mfma_f32_16x16x32_bf16 v[8:11], v[222:225], v[186:189], v[8:11]
	v_mfma_f32_16x16x32_bf16 v[4:7], v[222:225], v[190:193], v[2:5]

; template <int KK0, int KK1>
; DI void g256_compute(int tid, const char* sA, const char* sB, f32x4 (&acc)[8][4]) {
;     ...
;   for (int kk = KK0; kk < KK1; ++kk) {
;     bf16x8 b[4], a[4], a2[4];
; #pragma unroll
;     for (int n = 0; n < 4; ++n) { int row = wc * 64 + n * 16 + fr; b[n] = *(const bf16x8*)(sB + row * 128 + (((kk * 4 + fq) ^ (row & 7)) << 4)); }
; #pragma unroll
;     for (int m = 0; m < 4; ++m) { int row = wr * 128 + m * 16 + fr; a[m] = *(const bf16x8*)(sA + row * 128 + (((kk * 4 + fq) ^ (row & 7)) << 4)); }
;     __builtin_amdgcn_sched_barrier(0);
; #pragma unroll
;     for (int m = 0; m < 4; ++m) { int row = wr * 128 + (4 + m) * 16 + fr; a2[m] = *(const bf16x8*)(sA + row * 128 + (((kk * 4 + fq) ^ (row & 7)) << 4)); }
;     __builtin_amdgcn_s_setprio(1);
; #pragma unroll
;     for (int m = 0; m < 4; ++m)
; #pragma unroll
;       for (int n = 0; n < 4; ++n) acc[m][n] = __builtin_amdgcn_mfma_f32_16x16x32_bf16(a[m], b[n], acc[m][n], 0, 0, 0);
;     __builtin_amdgcn_sched_barrier(0);
; #pragma unroll
;     for (int m = 0; m < 4; ++m)
; #pragma unroll
;       for (int n = 0; n < 4; ++n) acc[4 + m][n] = __builtin_amdgcn_mfma_f32_16x16x32_bf16(a2[m], b[n], acc[4 + m][n], 0, 0, 0);
;     __builtin_amdgcn_s_setprio(0);
;     __builtin_amdgcn_sched_barrier(0);
;   }
; template <class AF>
; DI void g256_mainloop_t(int tid, const AF& af, const bft* Bt, int ldb, int bcol, int K, f32x4 (&acc)[8][4]) {
;     ...
;     if (tid < 256) {
;       if (kt + 1 < nk) g256_stage(tid, af, Bt, ldb, bcol, kt + 1, nxt, nxt + 32768);
;       g256_compute<0, 2>(tid, cur, cur + 32768, acc);
.LBB0_699:
	v_add_u32_e32 v96, s84, v171
	v_add_u32_e32 v98, v96, v156
	v_add_u32_e32 v96, v96, v169
	ds_read_b128 v[172:175], v98 offset:32768
	ds_read_b128 v[176:179], v98 offset:34816
	ds_read_b128 v[200:203], v98 offset:36864
	ds_read_b128 v[204:207], v98 offset:38912
	ds_read_b128 v[208:211], v96
	ds_read_b128 v[212:215], v96 offset:2048
	ds_read_b128 v[216:219], v96 offset:4096
	ds_read_b128 v[220:223], v96 offset:6144
	ds_read_b128 v[224:227], v96 offset:8192
	ds_read_b128 v[228:231], v96 offset:10240
	ds_read_b128 v[232:235], v96 offset:12288
	ds_read_b128 v[236:239], v96 offset:14336
	s_waitcnt lgkmcnt(0)
	v_mfma_f32_16x16x32_bf16 v[128:131], v[208:211], v[172:175], v[128:131]
	v_mfma_f32_16x16x32_bf16 v[124:127], v[208:211], v[176:179], v[124:127]
	v_mfma_f32_16x16x32_bf16 v[120:123], v[208:211], v[200:203], v[120:123]
	v_mfma_f32_16x16x32_bf16 v[116:119], v[208:211], v[204:207], v[116:119]
	v_mfma_f32_16x16x32_bf16 v[112:115], v[212:215], v[172:175], v[112:115]
	v_mfma_f32_16x16x32_bf16 v[108:111], v[212:215], v[176:179], v[108:111]
	v_mfma_f32_16x16x32_bf16 v[104:107], v[212:215], v[200:203], v[104:107]
	v_mfma_f32_16x16x32_bf16 v[98:101], v[212:215], v[204:207], v[100:103]
	v_mfma_f32_16x16x32_bf16 v[92:95], v[216:219], v[172:175], v[92:95]
	v_mfma_f32_16x16x32_bf16 v[88:91], v[216:219], v[176:179], v[88:91]
	v_mfma_f32_16x16x32_bf16 v[84:87], v[216:219], v[200:203], v[84:87]
	v_mfma_f32_16x16x32_bf16 v[80:83], v[216:219], v[204:207], v[80:83]
	v_mfma_f32_16x16x32_bf16 v[76:79], v[220:223], v[172:175], v[76:79]
	v_mfma_f32_16x16x32_bf16 v[72:75], v[220:223], v[176:179], v[72:75]
	v_mfma_f32_16x16x32_bf16 v[68:71], v[220:223], v[200:203], v[68:71]
	v_mfma_f32_16x16x32_bf16 v[64:67], v[220:223], v[204:207], v[64:67]
	v_mfma_f32_16x16x32_bf16 v[60:63], v[224:227], v[172:175], v[60:63]
	v_mfma_f32_16x16x32_bf16 v[56:59], v[224:227], v[176:179], v[56:59]
	v_mfma_f32_16x16x32_bf16 v[52:55], v[224:227], v[200:203], v[52:55]
	v_mfma_f32_16x16x32_bf16 v[48:51], v[224:227], v[204:207], v[48:51]
	v_mfma_f32_16x16x32_bf16 v[44:47], v[228:231], v[172:175], v[44:47]
	v_mfma_f32_16x16x32_bf16 v[40:43], v[228:231], v[176:179], v[40:43]
	v_mfma_f32_16x16x32_bf16 v[36:39], v[228:231], v[200:203], v[36:39]
	v_mfma_f32_16x16x32_bf16 v[32:35], v[228:231], v[204:207], v[32:35]
	v_mfma_f32_16x16x32_bf16 v[28:31], v[232:235], v[172:175], v[28:31]
	v_mfma_f32_16x16x32_bf16 v[24:27], v[232:235], v[176:179], v[24:27]
	v_mfma_f32_16x16x32_bf16 v[20:23], v[232:235], v[200:203], v[20:23]
	v_mfma_f32_16x16x32_bf16 v[16:19], v[232:235], v[204:207], v[16:19]
	v_mfma_f32_16x16x32_bf16 v[12:15], v[236:239], v[172:175], v[12:15]
	v_mfma_f32_16x16x32_bf16 v[8:11], v[236:239], v[176:179], v[8:11]
	v_mfma_f32_16x16x32_bf16 v[4:7], v[236:239], v[200:203], v[4:7]
	v_mfma_f32_16x16x32_bf16 v[0:3], v[236:239], v[204:207], v[0:3]
	v_add_u32_e32 v96, s84, v170
	v_add_u32_e32 v102, v96, v156
	v_add_u32_e32 v96, v96, v169
	ds_read_b128 v[172:175], v102 offset:32768
	ds_read_b128 v[176:179], v102 offset:34816
	ds_read_b128 v[200:203], v102 offset:36864
	ds_read_b128 v[204:207], v102 offset:38912
	ds_read_b128 v[208:211], v96
	ds_read_b128 v[212:215], v96 offset:2048
	ds_read_b128 v[216:219], v96 offset:4096
	ds_read_b128 v[220:223], v96 offset:6144
	ds_read_b128 v[224:227], v96 offset:8192
	ds_read_b128 v[228:231], v96 offset:10240
	ds_read_b128 v[232:235], v96 offset:12288
	ds_read_b128 v[236:239], v96 offset:14336
	s_waitcnt lgkmcnt(0)
	v_mfma_f32_16x16x32_bf16 v[128:131], v[208:211], v[172:175], v[128:131]
	v_mfma_f32_16x16x32_bf16 v[124:127], v[208:211], v[176:179], v[124:127]
	v_mfma_f32_16x16x32_bf16 v[120:123], v[208:211], v[200:203], v[120:123]
	v_mfma_f32_16x16x32_bf16 v[116:119], v[208:211], v[204:207], v[116:119]
	v_mfma_f32_16x16x32_bf16 v[112:115], v[212:215], v[172:175], v[112:115]
	v_mfma_f32_16x16x32_bf16 v[108:111], v[212:215], v[176:179], v[108:111]
	v_mfma_f32_16x16x32_bf16 v[104:107], v[212:215], v[200:203], v[104:107]
	v_mfma_f32_16x16x32_bf16 v[100:103], v[212:215], v[204:207], v[98:101]
	v_mfma_f32_16x16x32_bf16 v[92:95], v[216:219], v[172:175], v[92:95]
	v_mfma_f32_16x16x32_bf16 v[88:91], v[216:219], v[176:179], v[88:91]
	v_mfma_f32_16x16x32_bf16 v[84:87], v[216:219], v[200:203], v[84:87]
	v_mfma_f32_16x16x32_bf16 v[80:83], v[216:219], v[204:207], v[80:83]
	v_mfma_f32_16x16x32_bf16 v[76:79], v[220:223], v[172:175], v[76:79]
	v_mfma_f32_16x16x32_bf16 v[72:75], v[220:223], v[176:179], v[72:75]
	v_mfma_f32_16x16x32_bf16 v[68:71], v[220:223], v[200:203], v[68:71]
	v_mfma_f32_16x16x32_bf16 v[64:67], v[220:223], v[204:207], v[64:67]
	v_mfma_f32_16x16x32_bf16 v[60:63], v[224:227], v[172:175], v[60:63]
	v_mfma_f32_16x16x32_bf16 v[56:59], v[224:227], v[176:179], v[56:59]
	v_mfma_f32_16x16x32_bf16 v[52:55], v[224:227], v[200:203], v[52:55]
	v_mfma_f32_16x16x32_bf16 v[48:51], v[224:227], v[204:207], v[48:51]
	v_mfma_f32_16x16x32_bf16 v[44:47], v[228:231], v[172:175], v[44:47]
	v_mfma_f32_16x16x32_bf16 v[40:43], v[228:231], v[176:179], v[40:43]
	v_mfma_f32_16x16x32_bf16 v[36:39], v[228:231], v[200:203], v[36:39]
	v_mfma_f32_16x16x32_bf16 v[32:35], v[228:231], v[204:207], v[32:35]
	v_mfma_f32_16x16x32_bf16 v[28:31], v[232:235], v[172:175], v[28:31]
	v_mfma_f32_16x16x32_bf16 v[24:27], v[232:235], v[176:179], v[24:27]
	v_mfma_f32_16x16x32_bf16 v[20:23], v[232:235], v[200:203], v[20:23]
	v_mfma_f32_16x16x32_bf16 v[16:19], v[232:235], v[204:207], v[16:19]
	v_mfma_f32_16x16x32_bf16 v[12:15], v[236:239], v[172:175], v[12:15]
	v_mfma_f32_16x16x32_bf16 v[8:11], v[236:239], v[176:179], v[8:11]
	v_mfma_f32_16x16x32_bf16 v[4:7], v[236:239], v[200:203], v[4:7]
	v_mfma_f32_16x16x32_bf16 v[0:3], v[236:239], v[204:207], v[0:3]

; template <class AF>
; DI void g256_mainloop_t(int tid, const AF& af, const bft* Bt, int ldb, int bcol, int K, f32x4 (&acc)[8][4]) {
;     ...
;   for (int kt = 0; kt < nk; ++kt) {
;     asm volatile("s_waitcnt vmcnt(0)" ::: "memory");
;     __syncthreads();
;     char* cur = smem + (kt & 1) * 65536; char* nxt = smem + ((kt + 1) & 1) * 65536;
;     if (tid < 256) {
;       if (kt + 1 < nk) g256_stage(tid, af, Bt, ldb, bcol, kt + 1, nxt, nxt + 32768);
;       g256_compute<0, 2>(tid, cur, cur + 32768, acc);
;     } else {
;       g256_compute<0, 1>(tid, cur, cur + 32768, acc);
;       if (kt + 1 < nk) g256_stage(tid, af, Bt, ldb, bcol, kt + 1, nxt, nxt + 32768);
;       g256_compute<1, 2>(tid, cur, cur + 32768, acc);
;     }
.LBB0_701:
	s_add_i32 s10, s74, 0xffff0000
	s_waitcnt vmcnt(0)
	s_and_b32 s10, s10, 0x10000
	s_add_i32 s84, s10, 16
	s_and_b32 s10, s74, 0x10000
	s_add_i32 s85, s10, 16
	s_waitcnt vmcnt(0) lgkmcnt(0)
	s_barrier
	s_and_saveexec_b64 s[10:11], vcc
	s_xor_b64 s[10:11], exec, s[10:11]
	s_cbranch_execz .LBB0_705
	v_add_u32_e32 v96, s84, v155
	v_add_u32_e32 v98, v96, v156
	v_add_u32_e32 v96, v96, v169
	ds_read_b128 v[172:175], v98 offset:32768
	ds_read_b128 v[176:179], v98 offset:34816
	ds_read_b128 v[200:203], v98 offset:36864
	ds_read_b128 v[204:207], v98 offset:38912
	ds_read_b128 v[208:211], v96
	ds_read_b128 v[212:215], v96 offset:2048
	ds_read_b128 v[216:219], v96 offset:4096
	ds_read_b128 v[220:223], v96 offset:6144
	ds_read_b128 v[224:227], v96 offset:8192
	ds_read_b128 v[228:231], v96 offset:10240
	ds_read_b128 v[232:235], v96 offset:12288
	ds_read_b128 v[236:239], v96 offset:14336
	s_waitcnt lgkmcnt(7)
	v_mfma_f32_16x16x32_bf16 v[128:131], v[208:211], v[172:175], v[128:131]
	v_mfma_f32_16x16x32_bf16 v[124:127], v[208:211], v[176:179], v[124:127]
	v_mfma_f32_16x16x32_bf16 v[120:123], v[208:211], v[200:203], v[120:123]
	v_mfma_f32_16x16x32_bf16 v[116:119], v[208:211], v[204:207], v[116:119]
	s_waitcnt lgkmcnt(6)
	v_mfma_f32_16x16x32_bf16 v[112:115], v[212:215], v[172:175], v[112:115]
	v_mfma_f32_16x16x32_bf16 v[108:111], v[212:215], v[176:179], v[108:111]
	v_mfma_f32_16x16x32_bf16 v[104:107], v[212:215], v[200:203], v[104:107]
	v_mfma_f32_16x16x32_bf16 v[98:101], v[212:215], v[204:207], v[100:103]
	s_waitcnt lgkmcnt(5)
	v_mfma_f32_16x16x32_bf16 v[92:95], v[216:219], v[172:175], v[92:95]
	v_mfma_f32_16x16x32_bf16 v[88:91], v[216:219], v[176:179], v[88:91]
	v_mfma_f32_16x16x32_bf16 v[84:87], v[216:219], v[200:203], v[84:87]
	v_mfma_f32_16x16x32_bf16 v[80:83], v[216:219], v[204:207], v[80:83]
	s_waitcnt lgkmcnt(4)
	v_mfma_f32_16x16x32_bf16 v[76:79], v[220:223], v[172:175], v[76:79]
	v_mfma_f32_16x16x32_bf16 v[72:75], v[220:223], v[176:179], v[72:75]
	v_mfma_f32_16x16x32_bf16 v[68:71], v[220:223], v[200:203], v[68:71]
	v_mfma_f32_16x16x32_bf16 v[64:67], v[220:223], v[204:207], v[64:67]
	s_waitcnt lgkmcnt(3)
	v_mfma_f32_16x16x32_bf16 v[60:63], v[224:227], v[172:175], v[60:63]
	v_mfma_f32_16x16x32_bf16 v[56:59], v[224:227], v[176:179], v[56:59]
	v_mfma_f32_16x16x32_bf16 v[52:55], v[224:227], v[200:203], v[52:55]
	v_mfma_f32_16x16x32_bf16 v[48:51], v[224:227], v[204:207], v[48:51]
	s_waitcnt lgkmcnt(2)
	v_mfma_f32_16x16x32_bf16 v[44:47], v[228:231], v[172:175], v[44:47]
	v_mfma_f32_16x16x32_bf16 v[40:43], v[228:231], v[176:179], v[40:43]
	v_mfma_f32_16x16x32_bf16 v[36:39], v[228:231], v[200:203], v[36:39]
	v_mfma_f32_16x16x32_bf16 v[32:35], v[228:231], v[204:207], v[32:35]
	s_waitcnt lgkmcnt(1)
	v_mfma_f32_16x16x32_bf16 v[28:31], v[232:235], v[172:175], v[28:31]
	v_mfma_f32_16x16x32_bf16 v[24:27], v[232:235], v[176:179], v[24:27]
	v_mfma_f32_16x16x32_bf16 v[20:23], v[232:235], v[200:203], v[20:23]
	v_mfma_f32_16x16x32_bf16 v[16:19], v[232:235], v[204:207], v[16:19]
	s_waitcnt lgkmcnt(0)
	v_mfma_f32_16x16x32_bf16 v[12:15], v[236:239], v[172:175], v[12:15]
	v_mfma_f32_16x16x32_bf16 v[8:11], v[236:239], v[176:179], v[8:11]
	v_mfma_f32_16x16x32_bf16 v[4:7], v[236:239], v[200:203], v[4:7]
	v_mfma_f32_16x16x32_bf16 v[0:3], v[236:239], v[204:207], v[0:3]
	s_cmp_gt_u32 s37, 2
	s_cbranch_scc1 .LBB0_704
	v_add_u32_e32 v96, s85, v148
	v_add_u32_e32 v172, s85, v152
	v_readfirstlane_b32 s38, v96
	v_lshl_add_u64 v[102:103], v[138:139], 0, s[0:1]
	s_mov_b32 m0, s38
	v_readfirstlane_b32 s38, v172
	v_add_u32_e32 v173, s85, v153
	global_load_lds_dwordx4 v[102:103], off
	v_lshl_add_u64 v[102:103], v[136:137], 0, s[0:1]
	s_mov_b32 m0, s38
	v_readfirstlane_b32 s38, v173
	v_add_u32_e32 v174, s85, v154
	global_load_lds_dwordx4 v[102:103], off
	v_lshl_add_u64 v[102:103], v[134:135], 0, s[0:1]
	s_mov_b32 m0, s38
	v_readfirstlane_b32 s38, v174
	v_add_u32_e32 v96, 0x8000, v96
	global_load_lds_dwordx4 v[102:103], off
	v_lshl_add_u64 v[102:103], v[132:133], 0, s[0:1]
	s_mov_b32 m0, s38
	v_readfirstlane_b32 s38, v96
	v_add_u32_e32 v96, 0x8000, v172
	global_load_lds_dwordx4 v[102:103], off
	v_lshl_add_u64 v[102:103], v[140:141], 0, s[0:1]
	s_mov_b32 m0, s38
	v_readfirstlane_b32 s38, v96
	v_add_u32_e32 v96, 0x8000, v173
	global_load_lds_dwordx4 v[102:103], off
	v_lshl_add_u64 v[102:103], v[142:143], 0, s[0:1]
	s_mov_b32 m0, s38
	v_readfirstlane_b32 s38, v96
	v_add_u32_e32 v96, 0x8000, v174
	global_load_lds_dwordx4 v[102:103], off
	v_lshl_add_u64 v[102:103], v[144:145], 0, s[0:1]
	s_mov_b32 m0, s38
	v_readfirstlane_b32 s38, v96
	global_load_lds_dwordx4 v[102:103], off
	v_lshl_add_u64 v[102:103], v[146:147], 0, s[0:1]
	s_mov_b32 m0, s38
	s_nop 0
	global_load_lds_dwordx4 v[102:103], off
; template <int KK0, int KK1>
; DI void g256_compute(int tid, const char* sA, const char* sB, f32x4 (&acc)[8][4]) {
;     ...
;   for (int kk = KK0; kk < KK1; ++kk) {
;     bf16x8 b[4], a[4], a2[4];
; #pragma unroll
;     for (int n = 0; n < 4; ++n) { int row = wc * 64 + n * 16 + fr; b[n] = *(const bf16x8*)(sB + row * 128 + (((kk * 4 + fq) ^ (row & 7)) << 4)); }
; #pragma unroll
;     for (int m = 0; m < 4; ++m) { int row = wr * 128 + m * 16 + fr; a[m] = *(const bf16x8*)(sA + row * 128 + (((kk * 4 + fq) ^ (row & 7)) << 4)); }
;     __builtin_amdgcn_sched_barrier(0);
; #pragma unroll
;     for (int m = 0; m < 4; ++m) { int row = wr * 128 + (4 + m) * 16 + fr; a2[m] = *(const bf16x8*)(sA + row * 128 + (((kk * 4 + fq) ^ (row & 7)) << 4)); }
;     __builtin_amdgcn_s_setprio(1);
; #pragma unroll
;     for (int m = 0; m < 4; ++m)
; #pragma unroll
;       for (int n = 0; n < 4; ++n) acc[m][n] = __builtin_amdgcn_mfma_f32_16x16x32_bf16(a[m], b[n], acc[m][n], 0, 0, 0);
;     __builtin_amdgcn_sched_barrier(0);
; #pragma unroll
;     for (int m = 0; m < 4; ++m)
; #pragma unroll
;       for (int n = 0; n < 4; ++n) acc[4 + m][n] = __builtin_amdgcn_mfma_f32_16x16x32_bf16(a2[m], b[n], acc[4 + m][n], 0, 0, 0);
;     __builtin_amdgcn_s_setprio(0);
;     __builtin_amdgcn_sched_barrier(0);
;   }
.LBB0_704:
	v_add_u32_e32 v96, s84, v170
	v_add_u32_e32 v102, v96, v156
	v_add_u32_e32 v96, v96, v169
	ds_read_b128 v[172:175], v102 offset:32768
	ds_read_b128 v[176:179], v102 offset:34816
	ds_read_b128 v[200:203], v102 offset:36864
	ds_read_b128 v[204:207], v102 offset:38912
	ds_read_b128 v[208:211], v96
	ds_read_b128 v[212:215], v96 offset:2048
	ds_read_b128 v[216:219], v96 offset:4096
	ds_read_b128 v[220:223], v96 offset:6144
	ds_read_b128 v[224:227], v96 offset:8192
	ds_read_b128 v[228:231], v96 offset:10240
	ds_read_b128 v[232:235], v96 offset:12288
	ds_read_b128 v[236:239], v96 offset:14336
	s_waitcnt lgkmcnt(0)
	v_mfma_f32_16x16x32_bf16 v[128:131], v[208:211], v[172:175], v[128:131]
	v_mfma_f32_16x16x32_bf16 v[124:127], v[208:211], v[176:179], v[124:127]
	v_mfma_f32_16x16x32_bf16 v[120:123], v[208:211], v[200:203], v[120:123]
	v_mfma_f32_16x16x32_bf16 v[116:119], v[208:211], v[204:207], v[116:119]
	v_mfma_f32_16x16x32_bf16 v[112:115], v[212:215], v[172:175], v[112:115]
	v_mfma_f32_16x16x32_bf16 v[108:111], v[212:215], v[176:179], v[108:111]
	v_mfma_f32_16x16x32_bf16 v[104:107], v[212:215], v[200:203], v[104:107]
	v_mfma_f32_16x16x32_bf16 v[100:103], v[212:215], v[204:207], v[98:101]
	v_mfma_f32_16x16x32_bf16 v[92:95], v[216:219], v[172:175], v[92:95]
	v_mfma_f32_16x16x32_bf16 v[88:91], v[216:219], v[176:179], v[88:91]
	v_mfma_f32_16x16x32_bf16 v[84:87], v[216:219], v[200:203], v[84:87]
	v_mfma_f32_16x16x32_bf16 v[80:83], v[216:219], v[204:207], v[80:83]
	v_mfma_f32_16x16x32_bf16 v[76:79], v[220:223], v[172:175], v[76:79]
	v_mfma_f32_16x16x32_bf16 v[72:75], v[220:223], v[176:179], v[72:75]
	v_mfma_f32_16x16x32_bf16 v[68:71], v[220:223], v[200:203], v[68:71]
	v_mfma_f32_16x16x32_bf16 v[64:67], v[220:223], v[204:207], v[64:67]
	v_mfma_f32_16x16x32_bf16 v[60:63], v[224:227], v[172:175], v[60:63]
	v_mfma_f32_16x16x32_bf16 v[56:59], v[224:227], v[176:179], v[56:59]
	v_mfma_f32_16x16x32_bf16 v[52:55], v[224:227], v[200:203], v[52:55]
	v_mfma_f32_16x16x32_bf16 v[48:51], v[224:227], v[204:207], v[48:51]
	v_mfma_f32_16x16x32_bf16 v[44:47], v[228:231], v[172:175], v[44:47]
	v_mfma_f32_16x16x32_bf16 v[40:43], v[228:231], v[176:179], v[40:43]
	v_mfma_f32_16x16x32_bf16 v[36:39], v[228:231], v[200:203], v[36:39]
	v_mfma_f32_16x16x32_bf16 v[32:35], v[228:231], v[204:207], v[32:35]
	v_mfma_f32_16x16x32_bf16 v[28:31], v[232:235], v[172:175], v[28:31]
	v_mfma_f32_16x16x32_bf16 v[24:27], v[232:235], v[176:179], v[24:27]
	v_mfma_f32_16x16x32_bf16 v[20:23], v[232:235], v[200:203], v[20:23]
	v_mfma_f32_16x16x32_bf16 v[16:19], v[232:235], v[204:207], v[16:19]
	v_mfma_f32_16x16x32_bf16 v[12:15], v[236:239], v[172:175], v[12:15]
	v_mfma_f32_16x16x32_bf16 v[8:11], v[236:239], v[176:179], v[8:11]
	v_mfma_f32_16x16x32_bf16 v[4:7], v[236:239], v[200:203], v[4:7]
	v_mfma_f32_16x16x32_bf16 v[0:3], v[236:239], v[204:207], v[0:3]

; template <int KK0, int KK1>
; DI void g256_compute(int tid, const char* sA, const char* sB, f32x4 (&acc)[8][4]) {
;     ...
;   for (int kk = KK0; kk < KK1; ++kk) {
;     bf16x8 b[4], a[4], a2[4];
; #pragma unroll
;     for (int n = 0; n < 4; ++n) { int row = wc * 64 + n * 16 + fr; b[n] = *(const bf16x8*)(sB + row * 128 + (((kk * 4 + fq) ^ (row & 7)) << 4)); }
; #pragma unroll
;     for (int m = 0; m < 4; ++m) { int row = wr * 128 + m * 16 + fr; a[m] = *(const bf16x8*)(sA + row * 128 + (((kk * 4 + fq) ^ (row & 7)) << 4)); }
;     __builtin_amdgcn_sched_barrier(0);
; #pragma unroll
;     for (int m = 0; m < 4; ++m) { int row = wr * 128 + (4 + m) * 16 + fr; a2[m] = *(const bf16x8*)(sA + row * 128 + (((kk * 4 + fq) ^ (row & 7)) << 4)); }
;     __builtin_amdgcn_s_setprio(1);
; #pragma unroll
;     for (int m = 0; m < 4; ++m)
; #pragma unroll
;       for (int n = 0; n < 4; ++n) acc[m][n] = __builtin_amdgcn_mfma_f32_16x16x32_bf16(a[m], b[n], acc[m][n], 0, 0, 0);
;     __builtin_amdgcn_sched_barrier(0);
; #pragma unroll
;     for (int m = 0; m < 4; ++m)
; #pragma unroll
;       for (int n = 0; n < 4; ++n) acc[4 + m][n] = __builtin_amdgcn_mfma_f32_16x16x32_bf16(a2[m], b[n], acc[4 + m][n], 0, 0, 0);
;     __builtin_amdgcn_s_setprio(0);
;     __builtin_amdgcn_sched_barrier(0);
;   }
; template <class AF>
; DI void g256_mainloop_t(int tid, const AF& af, const bft* Bt, int ldb, int bcol, int K, f32x4 (&acc)[8][4]) {
;     ...
;     if (tid < 256) {
;       if (kt + 1 < nk) g256_stage(tid, af, Bt, ldb, bcol, kt + 1, nxt, nxt + 32768);
;       g256_compute<0, 2>(tid, cur, cur + 32768, acc);
.LBB0_746:
	v_add_u32_e32 v96, s37, v162
	v_add_u32_e32 v98, v96, v156
	v_add_u32_e32 v96, v96, v160
	ds_read_b128 v[164:167], v98 offset:32768
	ds_read_b128 v[168:171], v98 offset:34816
	ds_read_b128 v[172:175], v98 offset:36864
	ds_read_b128 v[176:179], v98 offset:38912
	ds_read_b128 v[200:203], v96
	ds_read_b128 v[204:207], v96 offset:2048
	ds_read_b128 v[208:211], v96 offset:4096
	ds_read_b128 v[212:215], v96 offset:6144
	ds_read_b128 v[216:219], v96 offset:8192
	ds_read_b128 v[220:223], v96 offset:10240
	ds_read_b128 v[224:227], v96 offset:12288
	ds_read_b128 v[228:231], v96 offset:14336
	s_waitcnt lgkmcnt(0)
	v_mfma_f32_16x16x32_bf16 v[128:131], v[200:203], v[164:167], v[128:131]
	v_mfma_f32_16x16x32_bf16 v[124:127], v[200:203], v[168:171], v[124:127]
	v_mfma_f32_16x16x32_bf16 v[120:123], v[200:203], v[172:175], v[120:123]
	v_mfma_f32_16x16x32_bf16 v[116:119], v[200:203], v[176:179], v[116:119]
	v_mfma_f32_16x16x32_bf16 v[112:115], v[204:207], v[164:167], v[112:115]
	v_mfma_f32_16x16x32_bf16 v[108:111], v[204:207], v[168:171], v[108:111]
	v_mfma_f32_16x16x32_bf16 v[104:107], v[204:207], v[172:175], v[104:107]
	v_mfma_f32_16x16x32_bf16 v[98:101], v[204:207], v[176:179], v[100:103]
	v_mfma_f32_16x16x32_bf16 v[92:95], v[208:211], v[164:167], v[92:95]
	v_mfma_f32_16x16x32_bf16 v[88:91], v[208:211], v[168:171], v[88:91]
	v_mfma_f32_16x16x32_bf16 v[84:87], v[208:211], v[172:175], v[84:87]
	v_mfma_f32_16x16x32_bf16 v[80:83], v[208:211], v[176:179], v[80:83]
	v_mfma_f32_16x16x32_bf16 v[76:79], v[212:215], v[164:167], v[76:79]
	v_mfma_f32_16x16x32_bf16 v[72:75], v[212:215], v[168:171], v[72:75]
	v_mfma_f32_16x16x32_bf16 v[68:71], v[212:215], v[172:175], v[68:71]
	v_mfma_f32_16x16x32_bf16 v[64:67], v[212:215], v[176:179], v[64:67]
	v_mfma_f32_16x16x32_bf16 v[60:63], v[216:219], v[164:167], v[60:63]
	v_mfma_f32_16x16x32_bf16 v[56:59], v[216:219], v[168:171], v[56:59]
	v_mfma_f32_16x16x32_bf16 v[52:55], v[216:219], v[172:175], v[52:55]
	v_mfma_f32_16x16x32_bf16 v[48:51], v[216:219], v[176:179], v[48:51]
	v_mfma_f32_16x16x32_bf16 v[44:47], v[220:223], v[164:167], v[44:47]
	v_mfma_f32_16x16x32_bf16 v[40:43], v[220:223], v[168:171], v[40:43]
	v_mfma_f32_16x16x32_bf16 v[36:39], v[220:223], v[172:175], v[36:39]
	v_mfma_f32_16x16x32_bf16 v[32:35], v[220:223], v[176:179], v[32:35]
	v_mfma_f32_16x16x32_bf16 v[28:31], v[224:227], v[164:167], v[28:31]
	v_mfma_f32_16x16x32_bf16 v[24:27], v[224:227], v[168:171], v[24:27]
	v_mfma_f32_16x16x32_bf16 v[20:23], v[224:227], v[172:175], v[20:23]
	v_mfma_f32_16x16x32_bf16 v[16:19], v[224:227], v[176:179], v[16:19]
	v_mfma_f32_16x16x32_bf16 v[12:15], v[228:231], v[164:167], v[12:15]
	v_mfma_f32_16x16x32_bf16 v[8:11], v[228:231], v[168:171], v[8:11]
	v_mfma_f32_16x16x32_bf16 v[4:7], v[228:231], v[172:175], v[4:7]
	v_mfma_f32_16x16x32_bf16 v[0:3], v[228:231], v[176:179], v[0:3]
	v_add_u32_e32 v96, s37, v161
	v_add_u32_e32 v102, v96, v156
	v_add_u32_e32 v96, v96, v160
	ds_read_b128 v[164:167], v102 offset:32768
	ds_read_b128 v[168:171], v102 offset:34816
	ds_read_b128 v[172:175], v102 offset:36864
	ds_read_b128 v[176:179], v102 offset:38912
	ds_read_b128 v[200:203], v96
	ds_read_b128 v[204:207], v96 offset:2048
	ds_read_b128 v[208:211], v96 offset:4096
	ds_read_b128 v[212:215], v96 offset:6144
	ds_read_b128 v[216:219], v96 offset:8192
	ds_read_b128 v[220:223], v96 offset:10240
	ds_read_b128 v[224:227], v96 offset:12288
	ds_read_b128 v[228:231], v96 offset:14336
	s_waitcnt lgkmcnt(0)
	v_mfma_f32_16x16x32_bf16 v[128:131], v[200:203], v[164:167], v[128:131]
	v_mfma_f32_16x16x32_bf16 v[124:127], v[200:203], v[168:171], v[124:127]
	v_mfma_f32_16x16x32_bf16 v[120:123], v[200:203], v[172:175], v[120:123]
	v_mfma_f32_16x16x32_bf16 v[116:119], v[200:203], v[176:179], v[116:119]
	v_mfma_f32_16x16x32_bf16 v[112:115], v[204:207], v[164:167], v[112:115]
	v_mfma_f32_16x16x32_bf16 v[108:111], v[204:207], v[168:171], v[108:111]
	v_mfma_f32_16x16x32_bf16 v[104:107], v[204:207], v[172:175], v[104:107]
	v_mfma_f32_16x16x32_bf16 v[100:103], v[204:207], v[176:179], v[98:101]
	v_mfma_f32_16x16x32_bf16 v[92:95], v[208:211], v[164:167], v[92:95]
	v_mfma_f32_16x16x32_bf16 v[88:91], v[208:211], v[168:171], v[88:91]
	v_mfma_f32_16x16x32_bf16 v[84:87], v[208:211], v[172:175], v[84:87]
	v_mfma_f32_16x16x32_bf16 v[80:83], v[208:211], v[176:179], v[80:83]
	v_mfma_f32_16x16x32_bf16 v[76:79], v[212:215], v[164:167], v[76:79]
	v_mfma_f32_16x16x32_bf16 v[72:75], v[212:215], v[168:171], v[72:75]
	v_mfma_f32_16x16x32_bf16 v[68:71], v[212:215], v[172:175], v[68:71]
	v_mfma_f32_16x16x32_bf16 v[64:67], v[212:215], v[176:179], v[64:67]
	v_mfma_f32_16x16x32_bf16 v[60:63], v[216:219], v[164:167], v[60:63]
	v_mfma_f32_16x16x32_bf16 v[56:59], v[216:219], v[168:171], v[56:59]
	v_mfma_f32_16x16x32_bf16 v[52:55], v[216:219], v[172:175], v[52:55]
	v_mfma_f32_16x16x32_bf16 v[48:51], v[216:219], v[176:179], v[48:51]
	v_mfma_f32_16x16x32_bf16 v[44:47], v[220:223], v[164:167], v[44:47]
	v_mfma_f32_16x16x32_bf16 v[40:43], v[220:223], v[168:171], v[40:43]
	v_mfma_f32_16x16x32_bf16 v[36:39], v[220:223], v[172:175], v[36:39]
	v_mfma_f32_16x16x32_bf16 v[32:35], v[220:223], v[176:179], v[32:35]
	v_mfma_f32_16x16x32_bf16 v[28:31], v[224:227], v[164:167], v[28:31]
	v_mfma_f32_16x16x32_bf16 v[24:27], v[224:227], v[168:171], v[24:27]
	v_mfma_f32_16x16x32_bf16 v[20:23], v[224:227], v[172:175], v[20:23]
	v_mfma_f32_16x16x32_bf16 v[16:19], v[224:227], v[176:179], v[16:19]
	v_mfma_f32_16x16x32_bf16 v[12:15], v[228:231], v[164:167], v[12:15]
	v_mfma_f32_16x16x32_bf16 v[8:11], v[228:231], v[168:171], v[8:11]
	v_mfma_f32_16x16x32_bf16 v[4:7], v[228:231], v[172:175], v[4:7]
	v_mfma_f32_16x16x32_bf16 v[0:3], v[228:231], v[176:179], v[0:3]

; template <class AF>
; DI void g256_mainloop_t(int tid, const AF& af, const bft* Bt, int ldb, int bcol, int K, f32x4 (&acc)[8][4]) {
;     ...
;   for (int kt = 0; kt < nk; ++kt) {
;     asm volatile("s_waitcnt vmcnt(0)" ::: "memory");
;     __syncthreads();
;     char* cur = smem + (kt & 1) * 65536; char* nxt = smem + ((kt + 1) & 1) * 65536;
;     if (tid < 256) {
;       if (kt + 1 < nk) g256_stage(tid, af, Bt, ldb, bcol, kt + 1, nxt, nxt + 32768);
;       g256_compute<0, 2>(tid, cur, cur + 32768, acc);
;     } else {
;       g256_compute<0, 1>(tid, cur, cur + 32768, acc);
;       if (kt + 1 < nk) g256_stage(tid, af, Bt, ldb, bcol, kt + 1, nxt, nxt + 32768);
;       g256_compute<1, 2>(tid, cur, cur + 32768, acc);
;     }
.LBB0_748:
	s_add_i32 s10, s36, 0xffff0000
	s_waitcnt vmcnt(0)
	s_and_b32 s10, s10, 0x10000
	s_add_i32 s37, s10, 16
	s_and_b32 s10, s36, 0x10000
	s_add_i32 s74, s10, 16
	s_waitcnt vmcnt(0) lgkmcnt(0)
	s_barrier
	s_and_saveexec_b64 s[10:11], vcc
	s_xor_b64 s[10:11], exec, s[10:11]
	s_cbranch_execz .LBB0_752
	v_add_u32_e32 v96, s37, v155
	v_add_u32_e32 v98, v96, v156
	v_add_u32_e32 v96, v96, v160
	ds_read_b128 v[164:167], v98 offset:32768
	ds_read_b128 v[168:171], v98 offset:34816
	ds_read_b128 v[172:175], v98 offset:36864
	ds_read_b128 v[176:179], v98 offset:38912
	ds_read_b128 v[200:203], v96
	ds_read_b128 v[204:207], v96 offset:2048
	ds_read_b128 v[208:211], v96 offset:4096
	ds_read_b128 v[212:215], v96 offset:6144
	ds_read_b128 v[216:219], v96 offset:8192
	ds_read_b128 v[220:223], v96 offset:10240
	ds_read_b128 v[224:227], v96 offset:12288
	ds_read_b128 v[228:231], v96 offset:14336
	s_waitcnt lgkmcnt(7)
	v_mfma_f32_16x16x32_bf16 v[128:131], v[200:203], v[164:167], v[128:131]
	v_mfma_f32_16x16x32_bf16 v[124:127], v[200:203], v[168:171], v[124:127]
	v_mfma_f32_16x16x32_bf16 v[120:123], v[200:203], v[172:175], v[120:123]
	v_mfma_f32_16x16x32_bf16 v[116:119], v[200:203], v[176:179], v[116:119]
	s_waitcnt lgkmcnt(6)
	v_mfma_f32_16x16x32_bf16 v[112:115], v[204:207], v[164:167], v[112:115]
	v_mfma_f32_16x16x32_bf16 v[108:111], v[204:207], v[168:171], v[108:111]
	v_mfma_f32_16x16x32_bf16 v[104:107], v[204:207], v[172:175], v[104:107]
	v_mfma_f32_16x16x32_bf16 v[98:101], v[204:207], v[176:179], v[100:103]
	s_waitcnt lgkmcnt(5)
	v_mfma_f32_16x16x32_bf16 v[92:95], v[208:211], v[164:167], v[92:95]
	v_mfma_f32_16x16x32_bf16 v[88:91], v[208:211], v[168:171], v[88:91]
	v_mfma_f32_16x16x32_bf16 v[84:87], v[208:211], v[172:175], v[84:87]
	v_mfma_f32_16x16x32_bf16 v[80:83], v[208:211], v[176:179], v[80:83]
	s_waitcnt lgkmcnt(4)
	v_mfma_f32_16x16x32_bf16 v[76:79], v[212:215], v[164:167], v[76:79]
	v_mfma_f32_16x16x32_bf16 v[72:75], v[212:215], v[168:171], v[72:75]
	v_mfma_f32_16x16x32_bf16 v[68:71], v[212:215], v[172:175], v[68:71]
	v_mfma_f32_16x16x32_bf16 v[64:67], v[212:215], v[176:179], v[64:67]
	s_waitcnt lgkmcnt(3)
	v_mfma_f32_16x16x32_bf16 v[60:63], v[216:219], v[164:167], v[60:63]
	v_mfma_f32_16x16x32_bf16 v[56:59], v[216:219], v[168:171], v[56:59]
	v_mfma_f32_16x16x32_bf16 v[52:55], v[216:219], v[172:175], v[52:55]
	v_mfma_f32_16x16x32_bf16 v[48:51], v[216:219], v[176:179], v[48:51]
	s_waitcnt lgkmcnt(2)
	v_mfma_f32_16x16x32_bf16 v[44:47], v[220:223], v[164:167], v[44:47]
	v_mfma_f32_16x16x32_bf16 v[40:43], v[220:223], v[168:171], v[40:43]
	v_mfma_f32_16x16x32_bf16 v[36:39], v[220:223], v[172:175], v[36:39]
	v_mfma_f32_16x16x32_bf16 v[32:35], v[220:223], v[176:179], v[32:35]
	s_waitcnt lgkmcnt(1)
	v_mfma_f32_16x16x32_bf16 v[28:31], v[224:227], v[164:167], v[28:31]
	v_mfma_f32_16x16x32_bf16 v[24:27], v[224:227], v[168:171], v[24:27]
	v_mfma_f32_16x16x32_bf16 v[20:23], v[224:227], v[172:175], v[20:23]
	v_mfma_f32_16x16x32_bf16 v[16:19], v[224:227], v[176:179], v[16:19]
	s_waitcnt lgkmcnt(0)
	v_mfma_f32_16x16x32_bf16 v[12:15], v[228:231], v[164:167], v[12:15]
	v_mfma_f32_16x16x32_bf16 v[8:11], v[228:231], v[168:171], v[8:11]
	v_mfma_f32_16x16x32_bf16 v[4:7], v[228:231], v[172:175], v[4:7]
	v_mfma_f32_16x16x32_bf16 v[0:3], v[228:231], v[176:179], v[0:3]
	s_cmp_gt_u32 s13, 4
	s_cbranch_scc1 .LBB0_751
	v_add_u32_e32 v96, s74, v148
	v_add_u32_e32 v157, s74, v152
	v_readfirstlane_b32 s38, v96
	v_lshl_add_u64 v[102:103], v[132:133], 0, s[0:1]
	s_mov_b32 m0, s38
	v_readfirstlane_b32 s38, v157
	v_add_u32_e32 v158, s74, v153
	global_load_lds_dwordx4 v[102:103], off
	v_lshl_add_u64 v[102:103], v[134:135], 0, s[0:1]
	s_mov_b32 m0, s38
	v_readfirstlane_b32 s38, v158
	v_add_u32_e32 v159, s74, v154
	global_load_lds_dwordx4 v[102:103], off
	v_lshl_add_u64 v[102:103], v[136:137], 0, s[0:1]
	s_mov_b32 m0, s38
	v_readfirstlane_b32 s38, v159
	v_add_u32_e32 v96, 0x8000, v96
	global_load_lds_dwordx4 v[102:103], off
	v_lshl_add_u64 v[102:103], v[138:139], 0, s[0:1]
	s_mov_b32 m0, s38
	v_readfirstlane_b32 s38, v96
	v_add_u32_e32 v96, 0x8000, v157
	global_load_lds_dwordx4 v[102:103], off
	v_lshl_add_u64 v[102:103], v[140:141], 0, s[0:1]
	s_mov_b32 m0, s38
	v_readfirstlane_b32 s38, v96
	v_add_u32_e32 v96, 0x8000, v158
	global_load_lds_dwordx4 v[102:103], off
	v_lshl_add_u64 v[102:103], v[142:143], 0, s[0:1]
	s_mov_b32 m0, s38
	v_readfirstlane_b32 s38, v96
	v_add_u32_e32 v96, 0x8000, v159
	global_load_lds_dwordx4 v[102:103], off
	v_lshl_add_u64 v[102:103], v[144:145], 0, s[0:1]
	s_mov_b32 m0, s38
	v_readfirstlane_b32 s38, v96
	global_load_lds_dwordx4 v[102:103], off
	v_lshl_add_u64 v[102:103], v[146:147], 0, s[0:1]
	s_mov_b32 m0, s38
	s_nop 0
	global_load_lds_dwordx4 v[102:103], off
; template <int KK0, int KK1>
; DI void g256_compute(int tid, const char* sA, const char* sB, f32x4 (&acc)[8][4]) {
;     ...
;   for (int kk = KK0; kk < KK1; ++kk) {
;     bf16x8 b[4], a[4], a2[4];
; #pragma unroll
;     for (int n = 0; n < 4; ++n) { int row = wc * 64 + n * 16 + fr; b[n] = *(const bf16x8*)(sB + row * 128 + (((kk * 4 + fq) ^ (row & 7)) << 4)); }
; #pragma unroll
;     for (int m = 0; m < 4; ++m) { int row = wr * 128 + m * 16 + fr; a[m] = *(const bf16x8*)(sA + row * 128 + (((kk * 4 + fq) ^ (row & 7)) << 4)); }
;     __builtin_amdgcn_sched_barrier(0);
; #pragma unroll
;     for (int m = 0; m < 4; ++m) { int row = wr * 128 + (4 + m) * 16 + fr; a2[m] = *(const bf16x8*)(sA + row * 128 + (((kk * 4 + fq) ^ (row & 7)) << 4)); }
;     __builtin_amdgcn_s_setprio(1);
; #pragma unroll
;     for (int m = 0; m < 4; ++m)
; #pragma unroll
;       for (int n = 0; n < 4; ++n) acc[m][n] = __builtin_amdgcn_mfma_f32_16x16x32_bf16(a[m], b[n], acc[m][n], 0, 0, 0);
;     __builtin_amdgcn_sched_barrier(0);
; #pragma unroll
;     for (int m = 0; m < 4; ++m)
; #pragma unroll
;       for (int n = 0; n < 4; ++n) acc[4 + m][n] = __builtin_amdgcn_mfma_f32_16x16x32_bf16(a2[m], b[n], acc[4 + m][n], 0, 0, 0);
;     __builtin_amdgcn_s_setprio(0);
;     __builtin_amdgcn_sched_barrier(0);
;   }
.LBB0_751:
	v_add_u32_e32 v96, s37, v161
	v_add_u32_e32 v102, v96, v156
	v_add_u32_e32 v96, v96, v160
	ds_read_b128 v[164:167], v102 offset:32768
	ds_read_b128 v[168:171], v102 offset:34816
	ds_read_b128 v[172:175], v102 offset:36864
	ds_read_b128 v[176:179], v102 offset:38912
	ds_read_b128 v[200:203], v96
	ds_read_b128 v[204:207], v96 offset:2048
	ds_read_b128 v[208:211], v96 offset:4096
	ds_read_b128 v[212:215], v96 offset:6144
	ds_read_b128 v[216:219], v96 offset:8192
	ds_read_b128 v[220:223], v96 offset:10240
	ds_read_b128 v[224:227], v96 offset:12288
	ds_read_b128 v[228:231], v96 offset:14336
	s_waitcnt lgkmcnt(0)
	v_mfma_f32_16x16x32_bf16 v[128:131], v[200:203], v[164:167], v[128:131]
	v_mfma_f32_16x16x32_bf16 v[124:127], v[200:203], v[168:171], v[124:127]
	v_mfma_f32_16x16x32_bf16 v[120:123], v[200:203], v[172:175], v[120:123]
	v_mfma_f32_16x16x32_bf16 v[116:119], v[200:203], v[176:179], v[116:119]
	v_mfma_f32_16x16x32_bf16 v[112:115], v[204:207], v[164:167], v[112:115]
	v_mfma_f32_16x16x32_bf16 v[108:111], v[204:207], v[168:171], v[108:111]
	v_mfma_f32_16x16x32_bf16 v[104:107], v[204:207], v[172:175], v[104:107]
	v_mfma_f32_16x16x32_bf16 v[100:103], v[204:207], v[176:179], v[98:101]
	v_mfma_f32_16x16x32_bf16 v[92:95], v[208:211], v[164:167], v[92:95]
	v_mfma_f32_16x16x32_bf16 v[88:91], v[208:211], v[168:171], v[88:91]
	v_mfma_f32_16x16x32_bf16 v[84:87], v[208:211], v[172:175], v[84:87]
	v_mfma_f32_16x16x32_bf16 v[80:83], v[208:211], v[176:179], v[80:83]
	v_mfma_f32_16x16x32_bf16 v[76:79], v[212:215], v[164:167], v[76:79]
	v_mfma_f32_16x16x32_bf16 v[72:75], v[212:215], v[168:171], v[72:75]
	v_mfma_f32_16x16x32_bf16 v[68:71], v[212:215], v[172:175], v[68:71]
	v_mfma_f32_16x16x32_bf16 v[64:67], v[212:215], v[176:179], v[64:67]
	v_mfma_f32_16x16x32_bf16 v[60:63], v[216:219], v[164:167], v[60:63]
	v_mfma_f32_16x16x32_bf16 v[56:59], v[216:219], v[168:171], v[56:59]
	v_mfma_f32_16x16x32_bf16 v[52:55], v[216:219], v[172:175], v[52:55]
	v_mfma_f32_16x16x32_bf16 v[48:51], v[216:219], v[176:179], v[48:51]
	v_mfma_f32_16x16x32_bf16 v[44:47], v[220:223], v[164:167], v[44:47]
	v_mfma_f32_16x16x32_bf16 v[40:43], v[220:223], v[168:171], v[40:43]
	v_mfma_f32_16x16x32_bf16 v[36:39], v[220:223], v[172:175], v[36:39]
	v_mfma_f32_16x16x32_bf16 v[32:35], v[220:223], v[176:179], v[32:35]
	v_mfma_f32_16x16x32_bf16 v[28:31], v[224:227], v[164:167], v[28:31]
	v_mfma_f32_16x16x32_bf16 v[24:27], v[224:227], v[168:171], v[24:27]
	v_mfma_f32_16x16x32_bf16 v[20:23], v[224:227], v[172:175], v[20:23]
	v_mfma_f32_16x16x32_bf16 v[16:19], v[224:227], v[176:179], v[16:19]
	v_mfma_f32_16x16x32_bf16 v[12:15], v[228:231], v[164:167], v[12:15]
	v_mfma_f32_16x16x32_bf16 v[8:11], v[228:231], v[168:171], v[8:11]
	v_mfma_f32_16x16x32_bf16 v[4:7], v[228:231], v[172:175], v[4:7]
	v_mfma_f32_16x16x32_bf16 v[0:3], v[228:231], v[176:179], v[0:3]

; template <int KK0, int KK1>
; DI void g256_compute(int tid, const char* sA, const char* sB, f32x4 (&acc)[8][4]) {
;     ...
;   for (int kk = KK0; kk < KK1; ++kk) {
;     bf16x8 b[4], a[4], a2[4];
; #pragma unroll
;     for (int n = 0; n < 4; ++n) { int row = wc * 64 + n * 16 + fr; b[n] = *(const bf16x8*)(sB + row * 128 + (((kk * 4 + fq) ^ (row & 7)) << 4)); }
; #pragma unroll
;     for (int m = 0; m < 4; ++m) { int row = wr * 128 + m * 16 + fr; a[m] = *(const bf16x8*)(sA + row * 128 + (((kk * 4 + fq) ^ (row & 7)) << 4)); }
;     __builtin_amdgcn_sched_barrier(0);
; #pragma unroll
;     for (int m = 0; m < 4; ++m) { int row = wr * 128 + (4 + m) * 16 + fr; a2[m] = *(const bf16x8*)(sA + row * 128 + (((kk * 4 + fq) ^ (row & 7)) << 4)); }
;     __builtin_amdgcn_s_setprio(1);
; #pragma unroll
;     for (int m = 0; m < 4; ++m)
; #pragma unroll
;       for (int n = 0; n < 4; ++n) acc[m][n] = __builtin_amdgcn_mfma_f32_16x16x32_bf16(a[m], b[n], acc[m][n], 0, 0, 0);
;     __builtin_amdgcn_sched_barrier(0);
; #pragma unroll
;     for (int m = 0; m < 4; ++m)
; #pragma unroll
;       for (int n = 0; n < 4; ++n) acc[4 + m][n] = __builtin_amdgcn_mfma_f32_16x16x32_bf16(a2[m], b[n], acc[4 + m][n], 0, 0, 0);
;     __builtin_amdgcn_s_setprio(0);
;     __builtin_amdgcn_sched_barrier(0);
;   }
; template <class AF>
; DI void g256_mainloop_t(int tid, const AF& af, const bft* Bt, int ldb, int bcol, int K, f32x4 (&acc)[8][4]) {
;     ...
;     if (tid < 256) {
;       if (kt + 1 < nk) g256_stage(tid, af, Bt, ldb, bcol, kt + 1, nxt, nxt + 32768);
;       g256_compute<0, 2>(tid, cur, cur + 32768, acc);
.LBB0_896:
	v_add_u32_e32 v0, s30, v174
	v_add_u32_e32 v2, v0, v171
	v_add_u32_e32 v0, v0, v172
	ds_read_b128 v[20:23], v2 offset:32768
	ds_read_b128 v[24:27], v2 offset:34816
	ds_read_b128 v[44:47], v2 offset:36864
	ds_read_b128 v[48:51], v2 offset:38912
	ds_read_b128 v[176:179], v0
	ds_read_b128 v[182:185], v0 offset:2048
	ds_read_b128 v[186:189], v0 offset:4096
	ds_read_b128 v[190:193], v0 offset:6144
	ds_read_b128 v[194:197], v0 offset:8192
	ds_read_b128 v[198:201], v0 offset:10240
	ds_read_b128 v[202:205], v0 offset:12288
	ds_read_b128 v[206:209], v0 offset:14336
	s_waitcnt lgkmcnt(0)
	v_mfma_f32_16x16x32_bf16 v[144:147], v[176:179], v[20:23], v[144:147]
	v_mfma_f32_16x16x32_bf16 v[140:143], v[176:179], v[24:27], v[140:143]
	v_mfma_f32_16x16x32_bf16 v[136:139], v[176:179], v[44:47], v[136:139]
	v_mfma_f32_16x16x32_bf16 v[132:135], v[176:179], v[48:51], v[132:135]
	v_mfma_f32_16x16x32_bf16 v[128:131], v[182:185], v[20:23], v[128:131]
	v_mfma_f32_16x16x32_bf16 v[124:127], v[182:185], v[24:27], v[124:127]
	v_mfma_f32_16x16x32_bf16 v[120:123], v[182:185], v[44:47], v[120:123]
	v_mfma_f32_16x16x32_bf16 v[116:119], v[182:185], v[48:51], v[116:119]
	v_mfma_f32_16x16x32_bf16 v[112:115], v[186:189], v[20:23], v[112:115]
	v_mfma_f32_16x16x32_bf16 v[108:111], v[186:189], v[24:27], v[108:111]
	v_mfma_f32_16x16x32_bf16 v[104:107], v[186:189], v[44:47], v[104:107]
	v_mfma_f32_16x16x32_bf16 v[100:103], v[186:189], v[48:51], v[100:103]
	v_mfma_f32_16x16x32_bf16 v[96:99], v[190:193], v[20:23], v[96:99]
	v_mfma_f32_16x16x32_bf16 v[92:95], v[190:193], v[24:27], v[92:95]
	v_mfma_f32_16x16x32_bf16 v[88:91], v[190:193], v[44:47], v[88:91]
	v_mfma_f32_16x16x32_bf16 v[84:87], v[190:193], v[48:51], v[84:87]
	v_mfma_f32_16x16x32_bf16 v[76:79], v[194:197], v[20:23], v[76:79]
	v_mfma_f32_16x16x32_bf16 v[80:83], v[194:197], v[24:27], v[80:83]
	v_mfma_f32_16x16x32_bf16 v[68:71], v[194:197], v[44:47], v[68:71]
	v_mfma_f32_16x16x32_bf16 v[72:75], v[194:197], v[48:51], v[72:75]
	v_mfma_f32_16x16x32_bf16 v[60:63], v[198:201], v[20:23], v[60:63]
	v_mfma_f32_16x16x32_bf16 v[64:67], v[198:201], v[24:27], v[64:67]
	v_mfma_f32_16x16x32_bf16 v[52:55], v[198:201], v[44:47], v[52:55]
	v_mfma_f32_16x16x32_bf16 v[56:59], v[198:201], v[48:51], v[56:59]
	v_mfma_f32_16x16x32_bf16 v[36:39], v[202:205], v[20:23], v[36:39]
	v_mfma_f32_16x16x32_bf16 v[40:43], v[202:205], v[24:27], v[40:43]
	v_mfma_f32_16x16x32_bf16 v[28:31], v[202:205], v[44:47], v[28:31]
	v_mfma_f32_16x16x32_bf16 v[32:35], v[202:205], v[48:51], v[32:35]
	v_mfma_f32_16x16x32_bf16 v[12:15], v[206:209], v[20:23], v[12:15]
	v_mfma_f32_16x16x32_bf16 v[16:19], v[206:209], v[24:27], v[16:19]
	v_mfma_f32_16x16x32_bf16 v[2:5], v[206:209], v[44:47], v[4:7]
	v_mfma_f32_16x16x32_bf16 v[8:11], v[206:209], v[48:51], v[8:11]
	v_add_u32_e32 v0, s30, v173
	v_add_u32_e32 v6, v0, v171
	v_add_u32_e32 v0, v0, v172
	ds_read_b128 v[20:23], v6 offset:32768
	ds_read_b128 v[24:27], v6 offset:34816
	ds_read_b128 v[44:47], v6 offset:36864
	ds_read_b128 v[48:51], v6 offset:38912
	ds_read_b128 v[176:179], v0
	ds_read_b128 v[182:185], v0 offset:2048
	ds_read_b128 v[186:189], v0 offset:4096
	ds_read_b128 v[190:193], v0 offset:6144
	ds_read_b128 v[194:197], v0 offset:8192
	ds_read_b128 v[198:201], v0 offset:10240
	ds_read_b128 v[202:205], v0 offset:12288
	ds_read_b128 v[206:209], v0 offset:14336
	s_waitcnt lgkmcnt(0)
	v_mfma_f32_16x16x32_bf16 v[144:147], v[176:179], v[20:23], v[144:147]
	v_mfma_f32_16x16x32_bf16 v[140:143], v[176:179], v[24:27], v[140:143]
	v_mfma_f32_16x16x32_bf16 v[136:139], v[176:179], v[44:47], v[136:139]
	v_mfma_f32_16x16x32_bf16 v[132:135], v[176:179], v[48:51], v[132:135]
	v_mfma_f32_16x16x32_bf16 v[128:131], v[182:185], v[20:23], v[128:131]
	v_mfma_f32_16x16x32_bf16 v[124:127], v[182:185], v[24:27], v[124:127]
	v_mfma_f32_16x16x32_bf16 v[120:123], v[182:185], v[44:47], v[120:123]
	v_mfma_f32_16x16x32_bf16 v[116:119], v[182:185], v[48:51], v[116:119]
	v_mfma_f32_16x16x32_bf16 v[112:115], v[186:189], v[20:23], v[112:115]
	v_mfma_f32_16x16x32_bf16 v[108:111], v[186:189], v[24:27], v[108:111]
	v_mfma_f32_16x16x32_bf16 v[104:107], v[186:189], v[44:47], v[104:107]
	v_mfma_f32_16x16x32_bf16 v[100:103], v[186:189], v[48:51], v[100:103]
	v_mfma_f32_16x16x32_bf16 v[96:99], v[190:193], v[20:23], v[96:99]
	v_mfma_f32_16x16x32_bf16 v[92:95], v[190:193], v[24:27], v[92:95]
	v_mfma_f32_16x16x32_bf16 v[88:91], v[190:193], v[44:47], v[88:91]
	v_mfma_f32_16x16x32_bf16 v[84:87], v[190:193], v[48:51], v[84:87]
	v_mfma_f32_16x16x32_bf16 v[76:79], v[194:197], v[20:23], v[76:79]
	v_mfma_f32_16x16x32_bf16 v[80:83], v[194:197], v[24:27], v[80:83]
	v_mfma_f32_16x16x32_bf16 v[68:71], v[194:197], v[44:47], v[68:71]
	v_mfma_f32_16x16x32_bf16 v[72:75], v[194:197], v[48:51], v[72:75]
	v_mfma_f32_16x16x32_bf16 v[60:63], v[198:201], v[20:23], v[60:63]
	v_mfma_f32_16x16x32_bf16 v[64:67], v[198:201], v[24:27], v[64:67]
	v_mfma_f32_16x16x32_bf16 v[52:55], v[198:201], v[44:47], v[52:55]
	v_mfma_f32_16x16x32_bf16 v[56:59], v[198:201], v[48:51], v[56:59]
	v_mfma_f32_16x16x32_bf16 v[36:39], v[202:205], v[20:23], v[36:39]
	v_mfma_f32_16x16x32_bf16 v[40:43], v[202:205], v[24:27], v[40:43]
	v_mfma_f32_16x16x32_bf16 v[28:31], v[202:205], v[44:47], v[28:31]
	v_mfma_f32_16x16x32_bf16 v[32:35], v[202:205], v[48:51], v[32:35]
	v_mfma_f32_16x16x32_bf16 v[12:15], v[206:209], v[20:23], v[12:15]
	v_mfma_f32_16x16x32_bf16 v[16:19], v[206:209], v[24:27], v[16:19]
	v_mfma_f32_16x16x32_bf16 v[4:7], v[206:209], v[44:47], v[2:5]
	v_mfma_f32_16x16x32_bf16 v[8:11], v[206:209], v[48:51], v[8:11]

; template <class AF>
; DI void g256_mainloop_t(int tid, const AF& af, const bft* Bt, int ldb, int bcol, int K, f32x4 (&acc)[8][4]) {
;     ...
;   for (int kt = 0; kt < nk; ++kt) {
;     asm volatile("s_waitcnt vmcnt(0)" ::: "memory");
;     __syncthreads();
;     char* cur = smem + (kt & 1) * 65536; char* nxt = smem + ((kt + 1) & 1) * 65536;
;     if (tid < 256) {
;       if (kt + 1 < nk) g256_stage(tid, af, Bt, ldb, bcol, kt + 1, nxt, nxt + 32768);
;       g256_compute<0, 2>(tid, cur, cur + 32768, acc);
;     } else {
;       g256_compute<0, 1>(tid, cur, cur + 32768, acc);
;       if (kt + 1 < nk) g256_stage(tid, af, Bt, ldb, bcol, kt + 1, nxt, nxt + 32768);
;       g256_compute<1, 2>(tid, cur, cur + 32768, acc);
;     }
.LBB0_898:
	s_add_i32 s18, s29, 0xffff0000
	s_waitcnt vmcnt(0)
	s_and_b32 s18, s18, 0x10000
	s_add_i32 s30, s18, 16
	s_and_b32 s18, s29, 0x10000
	s_add_i32 s31, s18, 16
	s_waitcnt vmcnt(0) lgkmcnt(0)
	s_barrier
	s_and_saveexec_b64 s[18:19], vcc
	s_xor_b64 s[18:19], exec, s[18:19]
	s_cbranch_execz .LBB0_902
	v_add_u32_e32 v0, s30, v170
	v_add_u32_e32 v2, v0, v171
	v_add_u32_e32 v0, v0, v172
	ds_read_b128 v[176:179], v2 offset:32768
	ds_read_b128 v[182:185], v2 offset:34816
	ds_read_b128 v[186:189], v2 offset:36864
	ds_read_b128 v[190:193], v2 offset:38912
	ds_read_b128 v[48:51], v0
	ds_read_b128 v[194:197], v0 offset:2048
	ds_read_b128 v[198:201], v0 offset:4096
	ds_read_b128 v[202:205], v0 offset:6144
	ds_read_b128 v[206:209], v0 offset:8192
	ds_read_b128 v[210:213], v0 offset:10240
	ds_read_b128 v[214:217], v0 offset:12288
	ds_read_b128 v[218:221], v0 offset:14336
	s_waitcnt lgkmcnt(7)
	v_mfma_f32_16x16x32_bf16 v[20:23], v[48:51], v[176:179], v[144:147]
	v_mfma_f32_16x16x32_bf16 v[24:27], v[48:51], v[182:185], v[140:143]
	v_mfma_f32_16x16x32_bf16 v[44:47], v[48:51], v[186:189], v[136:139]
	v_mfma_f32_16x16x32_bf16 v[48:51], v[48:51], v[190:193], v[132:135]
	s_waitcnt lgkmcnt(6)
	v_mfma_f32_16x16x32_bf16 v[128:131], v[194:197], v[176:179], v[128:131]
	v_mfma_f32_16x16x32_bf16 v[124:127], v[194:197], v[182:185], v[124:127]
	v_mfma_f32_16x16x32_bf16 v[120:123], v[194:197], v[186:189], v[120:123]
	v_mfma_f32_16x16x32_bf16 v[116:119], v[194:197], v[190:193], v[116:119]
	s_waitcnt lgkmcnt(5)
	v_mfma_f32_16x16x32_bf16 v[112:115], v[198:201], v[176:179], v[112:115]
	v_mfma_f32_16x16x32_bf16 v[108:111], v[198:201], v[182:185], v[108:111]
	v_mfma_f32_16x16x32_bf16 v[104:107], v[198:201], v[186:189], v[104:107]
	v_mfma_f32_16x16x32_bf16 v[100:103], v[198:201], v[190:193], v[100:103]
	s_waitcnt lgkmcnt(4)
	v_mfma_f32_16x16x32_bf16 v[96:99], v[202:205], v[176:179], v[96:99]
	v_mfma_f32_16x16x32_bf16 v[92:95], v[202:205], v[182:185], v[92:95]
	v_mfma_f32_16x16x32_bf16 v[88:91], v[202:205], v[186:189], v[88:91]
	v_mfma_f32_16x16x32_bf16 v[84:87], v[202:205], v[190:193], v[84:87]
	s_waitcnt lgkmcnt(3)
	v_mfma_f32_16x16x32_bf16 v[76:79], v[206:209], v[176:179], v[76:79]
	v_mfma_f32_16x16x32_bf16 v[80:83], v[206:209], v[182:185], v[80:83]
	v_mfma_f32_16x16x32_bf16 v[68:71], v[206:209], v[186:189], v[68:71]
	v_mfma_f32_16x16x32_bf16 v[72:75], v[206:209], v[190:193], v[72:75]
	s_waitcnt lgkmcnt(2)
	v_mfma_f32_16x16x32_bf16 v[60:63], v[210:213], v[176:179], v[60:63]
	v_mfma_f32_16x16x32_bf16 v[64:67], v[210:213], v[182:185], v[64:67]
	v_mfma_f32_16x16x32_bf16 v[52:55], v[210:213], v[186:189], v[52:55]
	v_mfma_f32_16x16x32_bf16 v[56:59], v[210:213], v[190:193], v[56:59]
	s_waitcnt lgkmcnt(1)
	v_mfma_f32_16x16x32_bf16 v[36:39], v[214:217], v[176:179], v[36:39]
	v_mfma_f32_16x16x32_bf16 v[40:43], v[214:217], v[182:185], v[40:43]
	v_mfma_f32_16x16x32_bf16 v[28:31], v[214:217], v[186:189], v[28:31]
	v_mfma_f32_16x16x32_bf16 v[32:35], v[214:217], v[190:193], v[32:35]
	s_waitcnt lgkmcnt(0)
	v_mfma_f32_16x16x32_bf16 v[12:15], v[218:221], v[176:179], v[12:15]
	v_mfma_f32_16x16x32_bf16 v[16:19], v[218:221], v[182:185], v[16:19]
	v_mfma_f32_16x16x32_bf16 v[2:5], v[218:221], v[186:189], v[4:7]
	v_mfma_f32_16x16x32_bf16 v[8:11], v[218:221], v[190:193], v[8:11]
	s_cmp_gt_u32 s27, 14
	s_cbranch_scc1 .LBB0_901
	v_add_u32_e32 v0, s31, v166
	v_add_u32_e32 v132, s31, v167
	v_readfirstlane_b32 s34, v0
	v_lshl_add_u64 v[6:7], v[148:149], 0, s[0:1]
	s_mov_b32 m0, s34
	v_readfirstlane_b32 s34, v132
	v_add_u32_e32 v133, s31, v168
	global_load_lds_dwordx4 v[6:7], off
	v_lshl_add_u64 v[6:7], v[150:151], 0, s[0:1]
	s_mov_b32 m0, s34
	v_readfirstlane_b32 s34, v133
	v_add_u32_e32 v134, s31, v169
	global_load_lds_dwordx4 v[6:7], off
	v_lshl_add_u64 v[6:7], v[152:153], 0, s[0:1]
	s_mov_b32 m0, s34
	v_readfirstlane_b32 s34, v134
	v_add_u32_e32 v0, 0x8000, v0
	global_load_lds_dwordx4 v[6:7], off
	v_lshl_add_u64 v[6:7], v[154:155], 0, s[0:1]
	s_mov_b32 m0, s34
	v_readfirstlane_b32 s34, v0
	v_add_u32_e32 v0, 0x8000, v132
	global_load_lds_dwordx4 v[6:7], off
	v_lshl_add_u64 v[6:7], v[156:157], 0, s[0:1]
	s_mov_b32 m0, s34
	v_readfirstlane_b32 s34, v0
	v_add_u32_e32 v0, 0x8000, v133
	global_load_lds_dwordx4 v[6:7], off
	v_lshl_add_u64 v[6:7], v[158:159], 0, s[0:1]
	s_mov_b32 m0, s34
	v_readfirstlane_b32 s34, v0
	v_add_u32_e32 v0, 0x8000, v134
	global_load_lds_dwordx4 v[6:7], off
	v_lshl_add_u64 v[6:7], v[160:161], 0, s[0:1]
	s_mov_b32 m0, s34
	v_readfirstlane_b32 s34, v0
	global_load_lds_dwordx4 v[6:7], off
	v_lshl_add_u64 v[6:7], v[162:163], 0, s[0:1]
	s_mov_b32 m0, s34
	s_nop 0
	global_load_lds_dwordx4 v[6:7], off
; template <int KK0, int KK1>
; DI void g256_compute(int tid, const char* sA, const char* sB, f32x4 (&acc)[8][4]) {
;     ...
;   for (int kk = KK0; kk < KK1; ++kk) {
;     bf16x8 b[4], a[4], a2[4];
; #pragma unroll
;     for (int n = 0; n < 4; ++n) { int row = wc * 64 + n * 16 + fr; b[n] = *(const bf16x8*)(sB + row * 128 + (((kk * 4 + fq) ^ (row & 7)) << 4)); }
; #pragma unroll
;     for (int m = 0; m < 4; ++m) { int row = wr * 128 + m * 16 + fr; a[m] = *(const bf16x8*)(sA + row * 128 + (((kk * 4 + fq) ^ (row & 7)) << 4)); }
;     __builtin_amdgcn_sched_barrier(0);
; #pragma unroll
;     for (int m = 0; m < 4; ++m) { int row = wr * 128 + (4 + m) * 16 + fr; a2[m] = *(const bf16x8*)(sA + row * 128 + (((kk * 4 + fq) ^ (row & 7)) << 4)); }
;     __builtin_amdgcn_s_setprio(1);
; #pragma unroll
;     for (int m = 0; m < 4; ++m)
; #pragma unroll
;       for (int n = 0; n < 4; ++n) acc[m][n] = __builtin_amdgcn_mfma_f32_16x16x32_bf16(a[m], b[n], acc[m][n], 0, 0, 0);
;     __builtin_amdgcn_sched_barrier(0);
; #pragma unroll
;     for (int m = 0; m < 4; ++m)
; #pragma unroll
;       for (int n = 0; n < 4; ++n) acc[4 + m][n] = __builtin_amdgcn_mfma_f32_16x16x32_bf16(a2[m], b[n], acc[4 + m][n], 0, 0, 0);
;     __builtin_amdgcn_s_setprio(0);
;     __builtin_amdgcn_sched_barrier(0);
;   }
.LBB0_901:
	v_add_u32_e32 v0, s30, v173
	v_add_u32_e32 v6, v0, v171
	v_add_u32_e32 v0, v0, v172
	ds_read_b128 v[176:179], v6 offset:32768
	ds_read_b128 v[182:185], v6 offset:34816
	ds_read_b128 v[186:189], v6 offset:36864
	ds_read_b128 v[190:193], v6 offset:38912
	ds_read_b128 v[132:135], v0
	ds_read_b128 v[194:197], v0 offset:2048
	ds_read_b128 v[198:201], v0 offset:4096
	ds_read_b128 v[202:205], v0 offset:6144
	ds_read_b128 v[206:209], v0 offset:8192
	ds_read_b128 v[210:213], v0 offset:10240
	ds_read_b128 v[214:217], v0 offset:12288
	ds_read_b128 v[218:221], v0 offset:14336
	s_waitcnt lgkmcnt(0)
	v_mfma_f32_16x16x32_bf16 v[144:147], v[132:135], v[176:179], v[20:23]
	v_mfma_f32_16x16x32_bf16 v[140:143], v[132:135], v[182:185], v[24:27]
	v_mfma_f32_16x16x32_bf16 v[136:139], v[132:135], v[186:189], v[44:47]
	v_mfma_f32_16x16x32_bf16 v[132:135], v[132:135], v[190:193], v[48:51]
	v_mfma_f32_16x16x32_bf16 v[128:131], v[194:197], v[176:179], v[128:131]
	v_mfma_f32_16x16x32_bf16 v[124:127], v[194:197], v[182:185], v[124:127]
	v_mfma_f32_16x16x32_bf16 v[120:123], v[194:197], v[186:189], v[120:123]
	v_mfma_f32_16x16x32_bf16 v[116:119], v[194:197], v[190:193], v[116:119]
	v_mfma_f32_16x16x32_bf16 v[112:115], v[198:201], v[176:179], v[112:115]
	v_mfma_f32_16x16x32_bf16 v[108:111], v[198:201], v[182:185], v[108:111]
	v_mfma_f32_16x16x32_bf16 v[104:107], v[198:201], v[186:189], v[104:107]
	v_mfma_f32_16x16x32_bf16 v[100:103], v[198:201], v[190:193], v[100:103]
	v_mfma_f32_16x16x32_bf16 v[96:99], v[202:205], v[176:179], v[96:99]
	v_mfma_f32_16x16x32_bf16 v[92:95], v[202:205], v[182:185], v[92:95]
	v_mfma_f32_16x16x32_bf16 v[88:91], v[202:205], v[186:189], v[88:91]
	v_mfma_f32_16x16x32_bf16 v[84:87], v[202:205], v[190:193], v[84:87]
	v_mfma_f32_16x16x32_bf16 v[76:79], v[206:209], v[176:179], v[76:79]
	v_mfma_f32_16x16x32_bf16 v[80:83], v[206:209], v[182:185], v[80:83]
	v_mfma_f32_16x16x32_bf16 v[68:71], v[206:209], v[186:189], v[68:71]
	v_mfma_f32_16x16x32_bf16 v[72:75], v[206:209], v[190:193], v[72:75]
	v_mfma_f32_16x16x32_bf16 v[60:63], v[210:213], v[176:179], v[60:63]
	v_mfma_f32_16x16x32_bf16 v[64:67], v[210:213], v[182:185], v[64:67]
	v_mfma_f32_16x16x32_bf16 v[52:55], v[210:213], v[186:189], v[52:55]
	v_mfma_f32_16x16x32_bf16 v[56:59], v[210:213], v[190:193], v[56:59]
	v_mfma_f32_16x16x32_bf16 v[36:39], v[214:217], v[176:179], v[36:39]
	v_mfma_f32_16x16x32_bf16 v[40:43], v[214:217], v[182:185], v[40:43]
	v_mfma_f32_16x16x32_bf16 v[28:31], v[214:217], v[186:189], v[28:31]
	v_mfma_f32_16x16x32_bf16 v[32:35], v[214:217], v[190:193], v[32:35]
	v_mfma_f32_16x16x32_bf16 v[12:15], v[218:221], v[176:179], v[12:15]
	v_mfma_f32_16x16x32_bf16 v[16:19], v[218:221], v[182:185], v[16:19]
	v_mfma_f32_16x16x32_bf16 v[4:7], v[218:221], v[186:189], v[2:5]
	v_mfma_f32_16x16x32_bf16 v[8:11], v[218:221], v[190:193], v[8:11]

; template <int KK0, int KK1>
; DI void g256_compute(int tid, const char* sA, const char* sB, f32x4 (&acc)[8][4]) {
;     ...
;   for (int kk = KK0; kk < KK1; ++kk) {
;     bf16x8 b[4], a[4], a2[4];
; #pragma unroll
;     for (int n = 0; n < 4; ++n) { int row = wc * 64 + n * 16 + fr; b[n] = *(const bf16x8*)(sB + row * 128 + (((kk * 4 + fq) ^ (row & 7)) << 4)); }
; #pragma unroll
;     for (int m = 0; m < 4; ++m) { int row = wr * 128 + m * 16 + fr; a[m] = *(const bf16x8*)(sA + row * 128 + (((kk * 4 + fq) ^ (row & 7)) << 4)); }
;     __builtin_amdgcn_sched_barrier(0);
; #pragma unroll
;     for (int m = 0; m < 4; ++m) { int row = wr * 128 + (4 + m) * 16 + fr; a2[m] = *(const bf16x8*)(sA + row * 128 + (((kk * 4 + fq) ^ (row & 7)) << 4)); }
;     __builtin_amdgcn_s_setprio(1);
; #pragma unroll
;     for (int m = 0; m < 4; ++m)
; #pragma unroll
;       for (int n = 0; n < 4; ++n) acc[m][n] = __builtin_amdgcn_mfma_f32_16x16x32_bf16(a[m], b[n], acc[m][n], 0, 0, 0);
;     __builtin_amdgcn_sched_barrier(0);
; #pragma unroll
;     for (int m = 0; m < 4; ++m)
; #pragma unroll
;       for (int n = 0; n < 4; ++n) acc[4 + m][n] = __builtin_amdgcn_mfma_f32_16x16x32_bf16(a2[m], b[n], acc[4 + m][n], 0, 0, 0);
;     __builtin_amdgcn_s_setprio(0);
;     __builtin_amdgcn_sched_barrier(0);
;   }
; template <class AF>
; DI void g256_mainloop_t(int tid, const AF& af, const bft* Bt, int ldb, int bcol, int K, f32x4 (&acc)[8][4]) {
;     ...
;     if (tid < 256) {
;       if (kt + 1 < nk) g256_stage(tid, af, Bt, ldb, bcol, kt + 1, nxt, nxt + 32768);
;       g256_compute<0, 2>(tid, cur, cur + 32768, acc);
.LBB0_965:
	v_add_u32_e32 v0, s70, v158
	v_add_u32_e32 v2, v0, v155
	v_add_u32_e32 v0, v0, v156
	ds_read_b128 v[160:163], v2 offset:32768
	ds_read_b128 v[164:167], v2 offset:34816
	ds_read_b128 v[168:171], v2 offset:36864
	ds_read_b128 v[172:175], v2 offset:38912
	ds_read_b128 v[176:179], v0
	ds_read_b128 v[182:185], v0 offset:2048
	ds_read_b128 v[186:189], v0 offset:4096
	ds_read_b128 v[190:193], v0 offset:6144
	ds_read_b128 v[194:197], v0 offset:8192
	ds_read_b128 v[198:201], v0 offset:10240
	ds_read_b128 v[202:205], v0 offset:12288
	ds_read_b128 v[206:209], v0 offset:14336
	s_waitcnt lgkmcnt(0)
	v_mfma_f32_16x16x32_bf16 v[128:131], v[176:179], v[160:163], v[128:131]
	v_mfma_f32_16x16x32_bf16 v[124:127], v[176:179], v[164:167], v[124:127]
	v_mfma_f32_16x16x32_bf16 v[120:123], v[176:179], v[168:171], v[120:123]
	v_mfma_f32_16x16x32_bf16 v[116:119], v[176:179], v[172:175], v[116:119]
	v_mfma_f32_16x16x32_bf16 v[112:115], v[182:185], v[160:163], v[112:115]
	v_mfma_f32_16x16x32_bf16 v[108:111], v[182:185], v[164:167], v[108:111]
	v_mfma_f32_16x16x32_bf16 v[104:107], v[182:185], v[168:171], v[104:107]
	v_mfma_f32_16x16x32_bf16 v[100:103], v[182:185], v[172:175], v[100:103]
	v_mfma_f32_16x16x32_bf16 v[96:99], v[186:189], v[160:163], v[96:99]
	v_mfma_f32_16x16x32_bf16 v[92:95], v[186:189], v[164:167], v[92:95]
	v_mfma_f32_16x16x32_bf16 v[88:91], v[186:189], v[168:171], v[88:91]
	v_mfma_f32_16x16x32_bf16 v[84:87], v[186:189], v[172:175], v[84:87]
	v_mfma_f32_16x16x32_bf16 v[80:83], v[190:193], v[160:163], v[80:83]
	v_mfma_f32_16x16x32_bf16 v[76:79], v[190:193], v[164:167], v[76:79]
	v_mfma_f32_16x16x32_bf16 v[72:75], v[190:193], v[168:171], v[72:75]
	v_mfma_f32_16x16x32_bf16 v[68:71], v[190:193], v[172:175], v[68:71]
	v_mfma_f32_16x16x32_bf16 v[64:67], v[194:197], v[160:163], v[64:67]
	v_mfma_f32_16x16x32_bf16 v[60:63], v[194:197], v[164:167], v[60:63]
	v_mfma_f32_16x16x32_bf16 v[56:59], v[194:197], v[168:171], v[56:59]
	v_mfma_f32_16x16x32_bf16 v[52:55], v[194:197], v[172:175], v[52:55]
	v_mfma_f32_16x16x32_bf16 v[48:51], v[198:201], v[160:163], v[48:51]
	v_mfma_f32_16x16x32_bf16 v[44:47], v[198:201], v[164:167], v[44:47]
	v_mfma_f32_16x16x32_bf16 v[40:43], v[198:201], v[168:171], v[40:43]
	v_mfma_f32_16x16x32_bf16 v[36:39], v[198:201], v[172:175], v[36:39]
	v_mfma_f32_16x16x32_bf16 v[32:35], v[202:205], v[160:163], v[32:35]
	v_mfma_f32_16x16x32_bf16 v[28:31], v[202:205], v[164:167], v[28:31]
	v_mfma_f32_16x16x32_bf16 v[24:27], v[202:205], v[168:171], v[24:27]
	v_mfma_f32_16x16x32_bf16 v[20:23], v[202:205], v[172:175], v[20:23]
	v_mfma_f32_16x16x32_bf16 v[16:19], v[206:209], v[160:163], v[16:19]
	v_mfma_f32_16x16x32_bf16 v[12:15], v[206:209], v[164:167], v[12:15]
	v_mfma_f32_16x16x32_bf16 v[8:11], v[206:209], v[168:171], v[8:11]
	v_mfma_f32_16x16x32_bf16 v[2:5], v[206:209], v[172:175], v[4:7]
	v_add_u32_e32 v0, s70, v157
	s_nop 0
	v_add_u32_e32 v6, v0, v155
	v_add_u32_e32 v0, v0, v156
	ds_read_b128 v[160:163], v6 offset:32768
	ds_read_b128 v[164:167], v6 offset:34816
	ds_read_b128 v[168:171], v6 offset:36864
	ds_read_b128 v[172:175], v6 offset:38912
	ds_read_b128 v[176:179], v0
	ds_read_b128 v[182:185], v0 offset:2048
	ds_read_b128 v[186:189], v0 offset:4096
	ds_read_b128 v[190:193], v0 offset:6144
	ds_read_b128 v[194:197], v0 offset:8192
	ds_read_b128 v[198:201], v0 offset:10240
	ds_read_b128 v[202:205], v0 offset:12288
	ds_read_b128 v[206:209], v0 offset:14336
	s_waitcnt lgkmcnt(0)
	v_mfma_f32_16x16x32_bf16 v[128:131], v[176:179], v[160:163], v[128:131]
	v_mfma_f32_16x16x32_bf16 v[124:127], v[176:179], v[164:167], v[124:127]
	v_mfma_f32_16x16x32_bf16 v[120:123], v[176:179], v[168:171], v[120:123]
	v_mfma_f32_16x16x32_bf16 v[116:119], v[176:179], v[172:175], v[116:119]
	v_mfma_f32_16x16x32_bf16 v[112:115], v[182:185], v[160:163], v[112:115]
	v_mfma_f32_16x16x32_bf16 v[108:111], v[182:185], v[164:167], v[108:111]
	v_mfma_f32_16x16x32_bf16 v[104:107], v[182:185], v[168:171], v[104:107]
	v_mfma_f32_16x16x32_bf16 v[100:103], v[182:185], v[172:175], v[100:103]
	v_mfma_f32_16x16x32_bf16 v[96:99], v[186:189], v[160:163], v[96:99]
	v_mfma_f32_16x16x32_bf16 v[92:95], v[186:189], v[164:167], v[92:95]
	v_mfma_f32_16x16x32_bf16 v[88:91], v[186:189], v[168:171], v[88:91]
	v_mfma_f32_16x16x32_bf16 v[84:87], v[186:189], v[172:175], v[84:87]
	v_mfma_f32_16x16x32_bf16 v[80:83], v[190:193], v[160:163], v[80:83]
	v_mfma_f32_16x16x32_bf16 v[76:79], v[190:193], v[164:167], v[76:79]
	v_mfma_f32_16x16x32_bf16 v[72:75], v[190:193], v[168:171], v[72:75]
	v_mfma_f32_16x16x32_bf16 v[68:71], v[190:193], v[172:175], v[68:71]
	v_mfma_f32_16x16x32_bf16 v[64:67], v[194:197], v[160:163], v[64:67]
	v_mfma_f32_16x16x32_bf16 v[60:63], v[194:197], v[164:167], v[60:63]
	v_mfma_f32_16x16x32_bf16 v[56:59], v[194:197], v[168:171], v[56:59]
	v_mfma_f32_16x16x32_bf16 v[52:55], v[194:197], v[172:175], v[52:55]
	v_mfma_f32_16x16x32_bf16 v[48:51], v[198:201], v[160:163], v[48:51]
	v_mfma_f32_16x16x32_bf16 v[44:47], v[198:201], v[164:167], v[44:47]
	v_mfma_f32_16x16x32_bf16 v[40:43], v[198:201], v[168:171], v[40:43]
	v_mfma_f32_16x16x32_bf16 v[36:39], v[198:201], v[172:175], v[36:39]
	v_mfma_f32_16x16x32_bf16 v[32:35], v[202:205], v[160:163], v[32:35]
	v_mfma_f32_16x16x32_bf16 v[28:31], v[202:205], v[164:167], v[28:31]
	v_mfma_f32_16x16x32_bf16 v[24:27], v[202:205], v[168:171], v[24:27]
	v_mfma_f32_16x16x32_bf16 v[20:23], v[202:205], v[172:175], v[20:23]
	v_mfma_f32_16x16x32_bf16 v[16:19], v[206:209], v[160:163], v[16:19]
	v_mfma_f32_16x16x32_bf16 v[12:15], v[206:209], v[164:167], v[12:15]
	v_mfma_f32_16x16x32_bf16 v[8:11], v[206:209], v[168:171], v[8:11]
	v_mfma_f32_16x16x32_bf16 v[4:7], v[206:209], v[172:175], v[2:5]

; template <class AF>
; DI void g256_mainloop_t(int tid, const AF& af, const bft* Bt, int ldb, int bcol, int K, f32x4 (&acc)[8][4]) {
;     ...
;   for (int kt = 0; kt < nk; ++kt) {
;     asm volatile("s_waitcnt vmcnt(0)" ::: "memory");
;     __syncthreads();
;     char* cur = smem + (kt & 1) * 65536; char* nxt = smem + ((kt + 1) & 1) * 65536;
;     if (tid < 256) {
;       if (kt + 1 < nk) g256_stage(tid, af, Bt, ldb, bcol, kt + 1, nxt, nxt + 32768);
;       g256_compute<0, 2>(tid, cur, cur + 32768, acc);
;     } else {
;       g256_compute<0, 1>(tid, cur, cur + 32768, acc);
;       if (kt + 1 < nk) g256_stage(tid, af, Bt, ldb, bcol, kt + 1, nxt, nxt + 32768);
;       g256_compute<1, 2>(tid, cur, cur + 32768, acc);
;     }
.LBB0_967:
	s_add_i32 s34, s69, 0xffff0000
	s_waitcnt vmcnt(0)
	s_and_b32 s34, s34, 0x10000
	s_add_i32 s70, s34, 16
	s_and_b32 s34, s69, 0x10000
	s_add_i32 s71, s34, 16
	s_waitcnt vmcnt(0) lgkmcnt(0)
	s_barrier
	s_and_saveexec_b64 s[34:35], vcc
	s_xor_b64 s[34:35], exec, s[34:35]
	s_cbranch_execz .LBB0_971
	v_add_u32_e32 v0, s70, v154
	v_add_u32_e32 v2, v0, v155
	v_add_u32_e32 v0, v0, v156
	ds_read_b128 v[160:163], v2 offset:32768
	ds_read_b128 v[164:167], v2 offset:34816
	ds_read_b128 v[168:171], v2 offset:36864
	ds_read_b128 v[172:175], v2 offset:38912
	ds_read_b128 v[176:179], v0
	ds_read_b128 v[182:185], v0 offset:2048
	ds_read_b128 v[186:189], v0 offset:4096
	ds_read_b128 v[190:193], v0 offset:6144
	ds_read_b128 v[194:197], v0 offset:8192
	ds_read_b128 v[198:201], v0 offset:10240
	ds_read_b128 v[202:205], v0 offset:12288
	ds_read_b128 v[206:209], v0 offset:14336
	s_waitcnt lgkmcnt(7)
	v_mfma_f32_16x16x32_bf16 v[128:131], v[176:179], v[160:163], v[128:131]
	v_mfma_f32_16x16x32_bf16 v[124:127], v[176:179], v[164:167], v[124:127]
	v_mfma_f32_16x16x32_bf16 v[120:123], v[176:179], v[168:171], v[120:123]
	v_mfma_f32_16x16x32_bf16 v[116:119], v[176:179], v[172:175], v[116:119]
	s_waitcnt lgkmcnt(6)
	v_mfma_f32_16x16x32_bf16 v[112:115], v[182:185], v[160:163], v[112:115]
	v_mfma_f32_16x16x32_bf16 v[108:111], v[182:185], v[164:167], v[108:111]
	v_mfma_f32_16x16x32_bf16 v[104:107], v[182:185], v[168:171], v[104:107]
	v_mfma_f32_16x16x32_bf16 v[100:103], v[182:185], v[172:175], v[100:103]
	s_waitcnt lgkmcnt(5)
	v_mfma_f32_16x16x32_bf16 v[96:99], v[186:189], v[160:163], v[96:99]
	v_mfma_f32_16x16x32_bf16 v[92:95], v[186:189], v[164:167], v[92:95]
	v_mfma_f32_16x16x32_bf16 v[88:91], v[186:189], v[168:171], v[88:91]
	v_mfma_f32_16x16x32_bf16 v[84:87], v[186:189], v[172:175], v[84:87]
	s_waitcnt lgkmcnt(4)
	v_mfma_f32_16x16x32_bf16 v[80:83], v[190:193], v[160:163], v[80:83]
	v_mfma_f32_16x16x32_bf16 v[76:79], v[190:193], v[164:167], v[76:79]
	v_mfma_f32_16x16x32_bf16 v[72:75], v[190:193], v[168:171], v[72:75]
	v_mfma_f32_16x16x32_bf16 v[68:71], v[190:193], v[172:175], v[68:71]
	s_waitcnt lgkmcnt(3)
	v_mfma_f32_16x16x32_bf16 v[64:67], v[194:197], v[160:163], v[64:67]
	v_mfma_f32_16x16x32_bf16 v[60:63], v[194:197], v[164:167], v[60:63]
	v_mfma_f32_16x16x32_bf16 v[56:59], v[194:197], v[168:171], v[56:59]
	v_mfma_f32_16x16x32_bf16 v[52:55], v[194:197], v[172:175], v[52:55]
	s_waitcnt lgkmcnt(2)
	v_mfma_f32_16x16x32_bf16 v[48:51], v[198:201], v[160:163], v[48:51]
	v_mfma_f32_16x16x32_bf16 v[44:47], v[198:201], v[164:167], v[44:47]
	v_mfma_f32_16x16x32_bf16 v[40:43], v[198:201], v[168:171], v[40:43]
	v_mfma_f32_16x16x32_bf16 v[36:39], v[198:201], v[172:175], v[36:39]
	s_waitcnt lgkmcnt(1)
	v_mfma_f32_16x16x32_bf16 v[32:35], v[202:205], v[160:163], v[32:35]
	v_mfma_f32_16x16x32_bf16 v[28:31], v[202:205], v[164:167], v[28:31]
	v_mfma_f32_16x16x32_bf16 v[24:27], v[202:205], v[168:171], v[24:27]
	v_mfma_f32_16x16x32_bf16 v[20:23], v[202:205], v[172:175], v[20:23]
	s_waitcnt lgkmcnt(0)
	v_mfma_f32_16x16x32_bf16 v[16:19], v[206:209], v[160:163], v[16:19]
	v_mfma_f32_16x16x32_bf16 v[12:15], v[206:209], v[164:167], v[12:15]
	v_mfma_f32_16x16x32_bf16 v[8:11], v[206:209], v[168:171], v[8:11]
	v_mfma_f32_16x16x32_bf16 v[2:5], v[206:209], v[172:175], v[4:7]
	s_cmp_gt_u32 s68, 30
	s_cbranch_scc1 .LBB0_970
	v_add_u32_e32 v0, s71, v150
	v_add_u32_e32 v159, s71, v151
	v_readfirstlane_b32 s38, v0
	v_lshl_add_u64 v[6:7], v[132:133], 0, s[22:23]
	s_mov_b32 m0, s38
	v_readfirstlane_b32 s38, v159
	v_add_u32_e32 v160, s71, v152
	global_load_lds_dwordx4 v[6:7], off
	v_lshl_add_u64 v[6:7], v[134:135], 0, s[22:23]
	s_mov_b32 m0, s38
	v_readfirstlane_b32 s38, v160
	v_add_u32_e32 v161, s71, v153
	global_load_lds_dwordx4 v[6:7], off
	v_lshl_add_u64 v[6:7], v[136:137], 0, s[22:23]
	s_mov_b32 m0, s38
	v_readfirstlane_b32 s38, v161
	v_add_u32_e32 v0, 0x8000, v0
	global_load_lds_dwordx4 v[6:7], off
	v_lshl_add_u64 v[6:7], v[138:139], 0, s[22:23]
	s_mov_b32 m0, s38
	v_readfirstlane_b32 s38, v0
	v_add_u32_e32 v0, 0x8000, v159
	global_load_lds_dwordx4 v[6:7], off
	v_lshl_add_u64 v[6:7], v[140:141], 0, s[22:23]
	s_mov_b32 m0, s38
	v_readfirstlane_b32 s38, v0
	v_add_u32_e32 v0, 0x8000, v160
	global_load_lds_dwordx4 v[6:7], off
	v_lshl_add_u64 v[6:7], v[142:143], 0, s[22:23]
	s_mov_b32 m0, s38
	v_readfirstlane_b32 s38, v0
	v_add_u32_e32 v0, 0x8000, v161
	global_load_lds_dwordx4 v[6:7], off
	v_lshl_add_u64 v[6:7], v[144:145], 0, s[22:23]
	s_mov_b32 m0, s38
	v_readfirstlane_b32 s38, v0
	global_load_lds_dwordx4 v[6:7], off
	v_lshl_add_u64 v[6:7], v[146:147], 0, s[22:23]
	s_mov_b32 m0, s38
	s_nop 0
	global_load_lds_dwordx4 v[6:7], off
; template <int KK0, int KK1>
; DI void g256_compute(int tid, const char* sA, const char* sB, f32x4 (&acc)[8][4]) {
;     ...
;   for (int kk = KK0; kk < KK1; ++kk) {
;     bf16x8 b[4], a[4], a2[4];
; #pragma unroll
;     for (int n = 0; n < 4; ++n) { int row = wc * 64 + n * 16 + fr; b[n] = *(const bf16x8*)(sB + row * 128 + (((kk * 4 + fq) ^ (row & 7)) << 4)); }
; #pragma unroll
;     for (int m = 0; m < 4; ++m) { int row = wr * 128 + m * 16 + fr; a[m] = *(const bf16x8*)(sA + row * 128 + (((kk * 4 + fq) ^ (row & 7)) << 4)); }
;     __builtin_amdgcn_sched_barrier(0);
; #pragma unroll
;     for (int m = 0; m < 4; ++m) { int row = wr * 128 + (4 + m) * 16 + fr; a2[m] = *(const bf16x8*)(sA + row * 128 + (((kk * 4 + fq) ^ (row & 7)) << 4)); }
;     __builtin_amdgcn_s_setprio(1);
; #pragma unroll
;     for (int m = 0; m < 4; ++m)
; #pragma unroll
;       for (int n = 0; n < 4; ++n) acc[m][n] = __builtin_amdgcn_mfma_f32_16x16x32_bf16(a[m], b[n], acc[m][n], 0, 0, 0);
;     __builtin_amdgcn_sched_barrier(0);
; #pragma unroll
;     for (int m = 0; m < 4; ++m)
; #pragma unroll
;       for (int n = 0; n < 4; ++n) acc[4 + m][n] = __builtin_amdgcn_mfma_f32_16x16x32_bf16(a2[m], b[n], acc[4 + m][n], 0, 0, 0);
;     __builtin_amdgcn_s_setprio(0);
;     __builtin_amdgcn_sched_barrier(0);
;   }
.LBB0_970:
	v_add_u32_e32 v0, s70, v157
	v_add_u32_e32 v6, v0, v155
	v_add_u32_e32 v0, v0, v156
	ds_read_b128 v[160:163], v6 offset:32768
	ds_read_b128 v[164:167], v6 offset:34816
	ds_read_b128 v[168:171], v6 offset:36864
	ds_read_b128 v[172:175], v6 offset:38912
	ds_read_b128 v[176:179], v0
	ds_read_b128 v[182:185], v0 offset:2048
	ds_read_b128 v[186:189], v0 offset:4096
	ds_read_b128 v[190:193], v0 offset:6144
	ds_read_b128 v[194:197], v0 offset:8192
	ds_read_b128 v[198:201], v0 offset:10240
	ds_read_b128 v[202:205], v0 offset:12288
	ds_read_b128 v[206:209], v0 offset:14336
	s_waitcnt lgkmcnt(0)
	v_mfma_f32_16x16x32_bf16 v[128:131], v[176:179], v[160:163], v[128:131]
	v_mfma_f32_16x16x32_bf16 v[124:127], v[176:179], v[164:167], v[124:127]
	v_mfma_f32_16x16x32_bf16 v[120:123], v[176:179], v[168:171], v[120:123]
	v_mfma_f32_16x16x32_bf16 v[116:119], v[176:179], v[172:175], v[116:119]
	v_mfma_f32_16x16x32_bf16 v[112:115], v[182:185], v[160:163], v[112:115]
	v_mfma_f32_16x16x32_bf16 v[108:111], v[182:185], v[164:167], v[108:111]
	v_mfma_f32_16x16x32_bf16 v[104:107], v[182:185], v[168:171], v[104:107]
	v_mfma_f32_16x16x32_bf16 v[100:103], v[182:185], v[172:175], v[100:103]
	v_mfma_f32_16x16x32_bf16 v[96:99], v[186:189], v[160:163], v[96:99]
	v_mfma_f32_16x16x32_bf16 v[92:95], v[186:189], v[164:167], v[92:95]
	v_mfma_f32_16x16x32_bf16 v[88:91], v[186:189], v[168:171], v[88:91]
	v_mfma_f32_16x16x32_bf16 v[84:87], v[186:189], v[172:175], v[84:87]
	v_mfma_f32_16x16x32_bf16 v[80:83], v[190:193], v[160:163], v[80:83]
	v_mfma_f32_16x16x32_bf16 v[76:79], v[190:193], v[164:167], v[76:79]
	v_mfma_f32_16x16x32_bf16 v[72:75], v[190:193], v[168:171], v[72:75]
	v_mfma_f32_16x16x32_bf16 v[68:71], v[190:193], v[172:175], v[68:71]
	v_mfma_f32_16x16x32_bf16 v[64:67], v[194:197], v[160:163], v[64:67]
	v_mfma_f32_16x16x32_bf16 v[60:63], v[194:197], v[164:167], v[60:63]
	v_mfma_f32_16x16x32_bf16 v[56:59], v[194:197], v[168:171], v[56:59]
	v_mfma_f32_16x16x32_bf16 v[52:55], v[194:197], v[172:175], v[52:55]
	v_mfma_f32_16x16x32_bf16 v[48:51], v[198:201], v[160:163], v[48:51]
	v_mfma_f32_16x16x32_bf16 v[44:47], v[198:201], v[164:167], v[44:47]
	v_mfma_f32_16x16x32_bf16 v[40:43], v[198:201], v[168:171], v[40:43]
	v_mfma_f32_16x16x32_bf16 v[36:39], v[198:201], v[172:175], v[36:39]
	v_mfma_f32_16x16x32_bf16 v[32:35], v[202:205], v[160:163], v[32:35]
	v_mfma_f32_16x16x32_bf16 v[28:31], v[202:205], v[164:167], v[28:31]
	v_mfma_f32_16x16x32_bf16 v[24:27], v[202:205], v[168:171], v[24:27]
	v_mfma_f32_16x16x32_bf16 v[20:23], v[202:205], v[172:175], v[20:23]
	v_mfma_f32_16x16x32_bf16 v[16:19], v[206:209], v[160:163], v[16:19]
	v_mfma_f32_16x16x32_bf16 v[12:15], v[206:209], v[164:167], v[12:15]
	v_mfma_f32_16x16x32_bf16 v[8:11], v[206:209], v[168:171], v[8:11]
	v_mfma_f32_16x16x32_bf16 v[4:7], v[206:209], v[172:175], v[2:5]

; template <int KK0, int KK1>
; DI void g256_compute(int tid, const char* sA, const char* sB, f32x4 (&acc)[8][4]) {
;     ...
;   for (int kk = KK0; kk < KK1; ++kk) {
;     bf16x8 b[4], a[4], a2[4];
; #pragma unroll
;     for (int n = 0; n < 4; ++n) { int row = wc * 64 + n * 16 + fr; b[n] = *(const bf16x8*)(sB + row * 128 + (((kk * 4 + fq) ^ (row & 7)) << 4)); }
; #pragma unroll
;     for (int m = 0; m < 4; ++m) { int row = wr * 128 + m * 16 + fr; a[m] = *(const bf16x8*)(sA + row * 128 + (((kk * 4 + fq) ^ (row & 7)) << 4)); }
;     __builtin_amdgcn_sched_barrier(0);
; #pragma unroll
;     for (int m = 0; m < 4; ++m) { int row = wr * 128 + (4 + m) * 16 + fr; a2[m] = *(const bf16x8*)(sA + row * 128 + (((kk * 4 + fq) ^ (row & 7)) << 4)); }
;     __builtin_amdgcn_s_setprio(1);
; #pragma unroll
;     for (int m = 0; m < 4; ++m)
; #pragma unroll
;       for (int n = 0; n < 4; ++n) acc[m][n] = __builtin_amdgcn_mfma_f32_16x16x32_bf16(a[m], b[n], acc[m][n], 0, 0, 0);
;     __builtin_amdgcn_sched_barrier(0);
; #pragma unroll
;     for (int m = 0; m < 4; ++m)
; #pragma unroll
;       for (int n = 0; n < 4; ++n) acc[4 + m][n] = __builtin_amdgcn_mfma_f32_16x16x32_bf16(a2[m], b[n], acc[4 + m][n], 0, 0, 0);
;     __builtin_amdgcn_s_setprio(0);
;     __builtin_amdgcn_sched_barrier(0);
;   }
; template <class AF>
; DI void g256_mainloop_t(int tid, const AF& af, const bft* Bt, int ldb, int bcol, int K, f32x4 (&acc)[8][4]) {
;     ...
;     if (tid < 256) {
;       if (kt + 1 < nk) g256_stage(tid, af, Bt, ldb, bcol, kt + 1, nxt, nxt + 32768);
;       g256_compute<0, 2>(tid, cur, cur + 32768, acc);
.LBB0_1118:
	v_add_u32_e32 v0, s20, v166
	v_add_u32_e32 v2, v0, v163
	v_add_u32_e32 v0, v0, v164
	ds_read_b128 v[168:171], v2 offset:32768
	ds_read_b128 v[172:175], v2 offset:34816
	ds_read_b128 v[176:179], v2 offset:36864
	ds_read_b128 v[182:185], v2 offset:38912
	ds_read_b128 v[186:189], v0
	ds_read_b128 v[190:193], v0 offset:2048
	ds_read_b128 v[194:197], v0 offset:4096
	ds_read_b128 v[198:201], v0 offset:6144
	ds_read_b128 v[202:205], v0 offset:8192
	ds_read_b128 v[206:209], v0 offset:10240
	ds_read_b128 v[210:213], v0 offset:12288
	ds_read_b128 v[214:217], v0 offset:14336
	s_waitcnt lgkmcnt(0)
	v_mfma_f32_16x16x32_bf16 v[128:131], v[186:189], v[168:171], v[128:131]
	v_mfma_f32_16x16x32_bf16 v[124:127], v[186:189], v[172:175], v[124:127]
	v_mfma_f32_16x16x32_bf16 v[120:123], v[186:189], v[176:179], v[120:123]
	v_mfma_f32_16x16x32_bf16 v[116:119], v[186:189], v[182:185], v[116:119]
	v_mfma_f32_16x16x32_bf16 v[112:115], v[190:193], v[168:171], v[112:115]
	v_mfma_f32_16x16x32_bf16 v[108:111], v[190:193], v[172:175], v[108:111]
	v_mfma_f32_16x16x32_bf16 v[104:107], v[190:193], v[176:179], v[104:107]
	v_mfma_f32_16x16x32_bf16 v[100:103], v[190:193], v[182:185], v[100:103]
	v_mfma_f32_16x16x32_bf16 v[96:99], v[194:197], v[168:171], v[96:99]
	v_mfma_f32_16x16x32_bf16 v[92:95], v[194:197], v[172:175], v[92:95]
	v_mfma_f32_16x16x32_bf16 v[88:91], v[194:197], v[176:179], v[88:91]
	v_mfma_f32_16x16x32_bf16 v[84:87], v[194:197], v[182:185], v[84:87]
	v_mfma_f32_16x16x32_bf16 v[80:83], v[198:201], v[168:171], v[80:83]
	v_mfma_f32_16x16x32_bf16 v[76:79], v[198:201], v[172:175], v[76:79]
	v_mfma_f32_16x16x32_bf16 v[72:75], v[198:201], v[176:179], v[72:75]
	v_mfma_f32_16x16x32_bf16 v[68:71], v[198:201], v[182:185], v[68:71]
	v_mfma_f32_16x16x32_bf16 v[64:67], v[202:205], v[168:171], v[64:67]
	v_mfma_f32_16x16x32_bf16 v[60:63], v[202:205], v[172:175], v[60:63]
	v_mfma_f32_16x16x32_bf16 v[56:59], v[202:205], v[176:179], v[56:59]
	v_mfma_f32_16x16x32_bf16 v[52:55], v[202:205], v[182:185], v[52:55]
	v_mfma_f32_16x16x32_bf16 v[48:51], v[206:209], v[168:171], v[48:51]
	v_mfma_f32_16x16x32_bf16 v[44:47], v[206:209], v[172:175], v[44:47]
	v_mfma_f32_16x16x32_bf16 v[40:43], v[206:209], v[176:179], v[40:43]
	v_mfma_f32_16x16x32_bf16 v[36:39], v[206:209], v[182:185], v[36:39]
	v_mfma_f32_16x16x32_bf16 v[32:35], v[210:213], v[168:171], v[32:35]
	v_mfma_f32_16x16x32_bf16 v[28:31], v[210:213], v[172:175], v[28:31]
	v_mfma_f32_16x16x32_bf16 v[24:27], v[210:213], v[176:179], v[24:27]
	v_mfma_f32_16x16x32_bf16 v[20:23], v[210:213], v[182:185], v[20:23]
	v_mfma_f32_16x16x32_bf16 v[16:19], v[214:217], v[168:171], v[16:19]
	v_mfma_f32_16x16x32_bf16 v[12:15], v[214:217], v[172:175], v[12:15]
	v_mfma_f32_16x16x32_bf16 v[8:11], v[214:217], v[176:179], v[8:11]
	v_mfma_f32_16x16x32_bf16 v[2:5], v[214:217], v[182:185], v[4:7]
	v_add_u32_e32 v0, s20, v165
	s_nop 0
	v_add_u32_e32 v6, v0, v163
	v_add_u32_e32 v0, v0, v164
	ds_read_b128 v[168:171], v6 offset:32768
	ds_read_b128 v[172:175], v6 offset:34816
	ds_read_b128 v[176:179], v6 offset:36864
	ds_read_b128 v[182:185], v6 offset:38912
	ds_read_b128 v[186:189], v0
	ds_read_b128 v[190:193], v0 offset:2048
	ds_read_b128 v[194:197], v0 offset:4096
	ds_read_b128 v[198:201], v0 offset:6144
	ds_read_b128 v[202:205], v0 offset:8192
	ds_read_b128 v[206:209], v0 offset:10240
	ds_read_b128 v[210:213], v0 offset:12288
	ds_read_b128 v[214:217], v0 offset:14336
	s_waitcnt lgkmcnt(0)
	v_mfma_f32_16x16x32_bf16 v[128:131], v[186:189], v[168:171], v[128:131]
	v_mfma_f32_16x16x32_bf16 v[124:127], v[186:189], v[172:175], v[124:127]
	v_mfma_f32_16x16x32_bf16 v[120:123], v[186:189], v[176:179], v[120:123]
	v_mfma_f32_16x16x32_bf16 v[116:119], v[186:189], v[182:185], v[116:119]
	v_mfma_f32_16x16x32_bf16 v[112:115], v[190:193], v[168:171], v[112:115]
	v_mfma_f32_16x16x32_bf16 v[108:111], v[190:193], v[172:175], v[108:111]
	v_mfma_f32_16x16x32_bf16 v[104:107], v[190:193], v[176:179], v[104:107]
	v_mfma_f32_16x16x32_bf16 v[100:103], v[190:193], v[182:185], v[100:103]
	v_mfma_f32_16x16x32_bf16 v[96:99], v[194:197], v[168:171], v[96:99]
	v_mfma_f32_16x16x32_bf16 v[92:95], v[194:197], v[172:175], v[92:95]
	v_mfma_f32_16x16x32_bf16 v[88:91], v[194:197], v[176:179], v[88:91]
	v_mfma_f32_16x16x32_bf16 v[84:87], v[194:197], v[182:185], v[84:87]
	v_mfma_f32_16x16x32_bf16 v[80:83], v[198:201], v[168:171], v[80:83]
	v_mfma_f32_16x16x32_bf16 v[76:79], v[198:201], v[172:175], v[76:79]
	v_mfma_f32_16x16x32_bf16 v[72:75], v[198:201], v[176:179], v[72:75]
	v_mfma_f32_16x16x32_bf16 v[68:71], v[198:201], v[182:185], v[68:71]
	v_mfma_f32_16x16x32_bf16 v[64:67], v[202:205], v[168:171], v[64:67]
	v_mfma_f32_16x16x32_bf16 v[60:63], v[202:205], v[172:175], v[60:63]
	v_mfma_f32_16x16x32_bf16 v[56:59], v[202:205], v[176:179], v[56:59]
	v_mfma_f32_16x16x32_bf16 v[52:55], v[202:205], v[182:185], v[52:55]
	v_mfma_f32_16x16x32_bf16 v[48:51], v[206:209], v[168:171], v[48:51]
	v_mfma_f32_16x16x32_bf16 v[44:47], v[206:209], v[172:175], v[44:47]
	v_mfma_f32_16x16x32_bf16 v[40:43], v[206:209], v[176:179], v[40:43]
	v_mfma_f32_16x16x32_bf16 v[36:39], v[206:209], v[182:185], v[36:39]
	v_mfma_f32_16x16x32_bf16 v[32:35], v[210:213], v[168:171], v[32:35]
	v_mfma_f32_16x16x32_bf16 v[28:31], v[210:213], v[172:175], v[28:31]
	v_mfma_f32_16x16x32_bf16 v[24:27], v[210:213], v[176:179], v[24:27]
	v_mfma_f32_16x16x32_bf16 v[20:23], v[210:213], v[182:185], v[20:23]
	v_mfma_f32_16x16x32_bf16 v[16:19], v[214:217], v[168:171], v[16:19]
	v_mfma_f32_16x16x32_bf16 v[12:15], v[214:217], v[172:175], v[12:15]
	v_mfma_f32_16x16x32_bf16 v[8:11], v[214:217], v[176:179], v[8:11]
	v_mfma_f32_16x16x32_bf16 v[4:7], v[214:217], v[182:185], v[2:5]

; template <class AF>
; DI void g256_mainloop_t(int tid, const AF& af, const bft* Bt, int ldb, int bcol, int K, f32x4 (&acc)[8][4]) {
;     ...
;   for (int kt = 0; kt < nk; ++kt) {
;     asm volatile("s_waitcnt vmcnt(0)" ::: "memory");
;     __syncthreads();
;     char* cur = smem + (kt & 1) * 65536; char* nxt = smem + ((kt + 1) & 1) * 65536;
;     if (tid < 256) {
;       if (kt + 1 < nk) g256_stage(tid, af, Bt, ldb, bcol, kt + 1, nxt, nxt + 32768);
;       g256_compute<0, 2>(tid, cur, cur + 32768, acc);
;     } else {
;       g256_compute<0, 1>(tid, cur, cur + 32768, acc);
;       if (kt + 1 < nk) g256_stage(tid, af, Bt, ldb, bcol, kt + 1, nxt, nxt + 32768);
;       g256_compute<1, 2>(tid, cur, cur + 32768, acc);
;     }
.LBB0_1120:
	s_add_i32 s8, s15, 0xffff0000
	s_waitcnt vmcnt(0)
	s_and_b32 s8, s8, 0x10000
	s_add_i32 s20, s8, 16
	s_and_b32 s8, s15, 0x10000
	s_add_i32 s21, s8, 16
	s_waitcnt vmcnt(0) lgkmcnt(0)
	s_barrier
	s_and_saveexec_b64 s[8:9], vcc
	s_xor_b64 s[8:9], exec, s[8:9]
	s_cbranch_execz .LBB0_1124
	v_add_u32_e32 v0, s20, v162
	v_add_u32_e32 v2, v0, v163
	v_add_u32_e32 v0, v0, v164
	ds_read_b128 v[168:171], v2 offset:32768
	ds_read_b128 v[172:175], v2 offset:34816
	ds_read_b128 v[176:179], v2 offset:36864
	ds_read_b128 v[182:185], v2 offset:38912
	ds_read_b128 v[186:189], v0
	ds_read_b128 v[190:193], v0 offset:2048
	ds_read_b128 v[194:197], v0 offset:4096
	ds_read_b128 v[198:201], v0 offset:6144
	ds_read_b128 v[202:205], v0 offset:8192
	ds_read_b128 v[206:209], v0 offset:10240
	ds_read_b128 v[210:213], v0 offset:12288
	ds_read_b128 v[214:217], v0 offset:14336
	s_waitcnt lgkmcnt(7)
	v_mfma_f32_16x16x32_bf16 v[128:131], v[186:189], v[168:171], v[128:131]
	v_mfma_f32_16x16x32_bf16 v[124:127], v[186:189], v[172:175], v[124:127]
	v_mfma_f32_16x16x32_bf16 v[120:123], v[186:189], v[176:179], v[120:123]
	v_mfma_f32_16x16x32_bf16 v[116:119], v[186:189], v[182:185], v[116:119]
	s_waitcnt lgkmcnt(6)
	v_mfma_f32_16x16x32_bf16 v[112:115], v[190:193], v[168:171], v[112:115]
	v_mfma_f32_16x16x32_bf16 v[108:111], v[190:193], v[172:175], v[108:111]
	v_mfma_f32_16x16x32_bf16 v[104:107], v[190:193], v[176:179], v[104:107]
	v_mfma_f32_16x16x32_bf16 v[100:103], v[190:193], v[182:185], v[100:103]
	s_waitcnt lgkmcnt(5)
	v_mfma_f32_16x16x32_bf16 v[96:99], v[194:197], v[168:171], v[96:99]
	v_mfma_f32_16x16x32_bf16 v[92:95], v[194:197], v[172:175], v[92:95]
	v_mfma_f32_16x16x32_bf16 v[88:91], v[194:197], v[176:179], v[88:91]
	v_mfma_f32_16x16x32_bf16 v[84:87], v[194:197], v[182:185], v[84:87]
	s_waitcnt lgkmcnt(4)
	v_mfma_f32_16x16x32_bf16 v[80:83], v[198:201], v[168:171], v[80:83]
	v_mfma_f32_16x16x32_bf16 v[76:79], v[198:201], v[172:175], v[76:79]
	v_mfma_f32_16x16x32_bf16 v[72:75], v[198:201], v[176:179], v[72:75]
	v_mfma_f32_16x16x32_bf16 v[68:71], v[198:201], v[182:185], v[68:71]
	s_waitcnt lgkmcnt(3)
	v_mfma_f32_16x16x32_bf16 v[64:67], v[202:205], v[168:171], v[64:67]
	v_mfma_f32_16x16x32_bf16 v[60:63], v[202:205], v[172:175], v[60:63]
	v_mfma_f32_16x16x32_bf16 v[56:59], v[202:205], v[176:179], v[56:59]
	v_mfma_f32_16x16x32_bf16 v[52:55], v[202:205], v[182:185], v[52:55]
	s_waitcnt lgkmcnt(2)
	v_mfma_f32_16x16x32_bf16 v[48:51], v[206:209], v[168:171], v[48:51]
	v_mfma_f32_16x16x32_bf16 v[44:47], v[206:209], v[172:175], v[44:47]
	v_mfma_f32_16x16x32_bf16 v[40:43], v[206:209], v[176:179], v[40:43]
	v_mfma_f32_16x16x32_bf16 v[36:39], v[206:209], v[182:185], v[36:39]
	s_waitcnt lgkmcnt(1)
	v_mfma_f32_16x16x32_bf16 v[32:35], v[210:213], v[168:171], v[32:35]
	v_mfma_f32_16x16x32_bf16 v[28:31], v[210:213], v[172:175], v[28:31]
	v_mfma_f32_16x16x32_bf16 v[24:27], v[210:213], v[176:179], v[24:27]
	v_mfma_f32_16x16x32_bf16 v[20:23], v[210:213], v[182:185], v[20:23]
	s_waitcnt lgkmcnt(0)
	v_mfma_f32_16x16x32_bf16 v[16:19], v[214:217], v[168:171], v[16:19]
	v_mfma_f32_16x16x32_bf16 v[12:15], v[214:217], v[172:175], v[12:15]
	v_mfma_f32_16x16x32_bf16 v[8:11], v[214:217], v[176:179], v[8:11]
	v_mfma_f32_16x16x32_bf16 v[2:5], v[214:217], v[182:185], v[4:7]
	s_cmp_gt_u32 s14, 14
	s_cbranch_scc1 .LBB0_1123
	v_add_u32_e32 v0, s21, v158
	v_add_u32_e32 v167, s21, v159
	v_readfirstlane_b32 s22, v0
	v_lshl_add_u64 v[6:7], v[132:133], 0, s[0:1]
	s_mov_b32 m0, s22
	v_readfirstlane_b32 s22, v167
	v_add_u32_e32 v168, s21, v160
	global_load_lds_dwordx4 v[6:7], off
	v_lshl_add_u64 v[6:7], v[134:135], 0, s[0:1]
	s_mov_b32 m0, s22
	v_readfirstlane_b32 s22, v168
	v_add_u32_e32 v169, s21, v161
	global_load_lds_dwordx4 v[6:7], off
	v_lshl_add_u64 v[6:7], v[136:137], 0, s[0:1]
	s_mov_b32 m0, s22
	v_readfirstlane_b32 s22, v169
	v_add_u32_e32 v0, 0x8000, v0
	global_load_lds_dwordx4 v[6:7], off
	v_lshl_add_u64 v[6:7], v[138:139], 0, s[0:1]
	s_mov_b32 m0, s22
	v_readfirstlane_b32 s22, v0
	v_add_u32_e32 v0, 0x8000, v167
	global_load_lds_dwordx4 v[6:7], off
	v_lshl_add_u64 v[6:7], v[140:141], 0, s[0:1]
	s_mov_b32 m0, s22
	v_readfirstlane_b32 s22, v0
	v_add_u32_e32 v0, 0x8000, v168
	global_load_lds_dwordx4 v[6:7], off
	v_lshl_add_u64 v[6:7], v[142:143], 0, s[0:1]
	s_mov_b32 m0, s22
	v_readfirstlane_b32 s22, v0
	v_add_u32_e32 v0, 0x8000, v169
	global_load_lds_dwordx4 v[6:7], off
	v_lshl_add_u64 v[6:7], v[144:145], 0, s[0:1]
	s_mov_b32 m0, s22
	v_readfirstlane_b32 s22, v0
	global_load_lds_dwordx4 v[6:7], off
	v_lshl_add_u64 v[6:7], v[146:147], 0, s[0:1]
	s_mov_b32 m0, s22
	s_nop 0
	global_load_lds_dwordx4 v[6:7], off
; template <int KK0, int KK1>
; DI void g256_compute(int tid, const char* sA, const char* sB, f32x4 (&acc)[8][4]) {
;     ...
;   for (int kk = KK0; kk < KK1; ++kk) {
;     bf16x8 b[4], a[4], a2[4];
; #pragma unroll
;     for (int n = 0; n < 4; ++n) { int row = wc * 64 + n * 16 + fr; b[n] = *(const bf16x8*)(sB + row * 128 + (((kk * 4 + fq) ^ (row & 7)) << 4)); }
; #pragma unroll
;     for (int m = 0; m < 4; ++m) { int row = wr * 128 + m * 16 + fr; a[m] = *(const bf16x8*)(sA + row * 128 + (((kk * 4 + fq) ^ (row & 7)) << 4)); }
;     __builtin_amdgcn_sched_barrier(0);
; #pragma unroll
;     for (int m = 0; m < 4; ++m) { int row = wr * 128 + (4 + m) * 16 + fr; a2[m] = *(const bf16x8*)(sA + row * 128 + (((kk * 4 + fq) ^ (row & 7)) << 4)); }
;     __builtin_amdgcn_s_setprio(1);
; #pragma unroll
;     for (int m = 0; m < 4; ++m)
; #pragma unroll
;       for (int n = 0; n < 4; ++n) acc[m][n] = __builtin_amdgcn_mfma_f32_16x16x32_bf16(a[m], b[n], acc[m][n], 0, 0, 0);
;     __builtin_amdgcn_sched_barrier(0);
; #pragma unroll
;     for (int m = 0; m < 4; ++m)
; #pragma unroll
;       for (int n = 0; n < 4; ++n) acc[4 + m][n] = __builtin_amdgcn_mfma_f32_16x16x32_bf16(a2[m], b[n], acc[4 + m][n], 0, 0, 0);
;     __builtin_amdgcn_s_setprio(0);
;     __builtin_amdgcn_sched_barrier(0);
;   }
.LBB0_1123:
	v_add_u32_e32 v0, s20, v165
	v_add_u32_e32 v6, v0, v163
	v_add_u32_e32 v0, v0, v164
	ds_read_b128 v[168:171], v6 offset:32768
	ds_read_b128 v[172:175], v6 offset:34816
	ds_read_b128 v[176:179], v6 offset:36864
	ds_read_b128 v[182:185], v6 offset:38912
	ds_read_b128 v[186:189], v0
	ds_read_b128 v[190:193], v0 offset:2048
	ds_read_b128 v[194:197], v0 offset:4096
	ds_read_b128 v[198:201], v0 offset:6144
	ds_read_b128 v[202:205], v0 offset:8192
	ds_read_b128 v[206:209], v0 offset:10240
	ds_read_b128 v[210:213], v0 offset:12288
	ds_read_b128 v[214:217], v0 offset:14336
	s_waitcnt lgkmcnt(0)
	v_mfma_f32_16x16x32_bf16 v[128:131], v[186:189], v[168:171], v[128:131]
	v_mfma_f32_16x16x32_bf16 v[124:127], v[186:189], v[172:175], v[124:127]
	v_mfma_f32_16x16x32_bf16 v[120:123], v[186:189], v[176:179], v[120:123]
	v_mfma_f32_16x16x32_bf16 v[116:119], v[186:189], v[182:185], v[116:119]
	v_mfma_f32_16x16x32_bf16 v[112:115], v[190:193], v[168:171], v[112:115]
	v_mfma_f32_16x16x32_bf16 v[108:111], v[190:193], v[172:175], v[108:111]
	v_mfma_f32_16x16x32_bf16 v[104:107], v[190:193], v[176:179], v[104:107]
	v_mfma_f32_16x16x32_bf16 v[100:103], v[190:193], v[182:185], v[100:103]
	v_mfma_f32_16x16x32_bf16 v[96:99], v[194:197], v[168:171], v[96:99]
	v_mfma_f32_16x16x32_bf16 v[92:95], v[194:197], v[172:175], v[92:95]
	v_mfma_f32_16x16x32_bf16 v[88:91], v[194:197], v[176:179], v[88:91]
	v_mfma_f32_16x16x32_bf16 v[84:87], v[194:197], v[182:185], v[84:87]
	v_mfma_f32_16x16x32_bf16 v[80:83], v[198:201], v[168:171], v[80:83]
	v_mfma_f32_16x16x32_bf16 v[76:79], v[198:201], v[172:175], v[76:79]
	v_mfma_f32_16x16x32_bf16 v[72:75], v[198:201], v[176:179], v[72:75]
	v_mfma_f32_16x16x32_bf16 v[68:71], v[198:201], v[182:185], v[68:71]
	v_mfma_f32_16x16x32_bf16 v[64:67], v[202:205], v[168:171], v[64:67]
	v_mfma_f32_16x16x32_bf16 v[60:63], v[202:205], v[172:175], v[60:63]
	v_mfma_f32_16x16x32_bf16 v[56:59], v[202:205], v[176:179], v[56:59]
	v_mfma_f32_16x16x32_bf16 v[52:55], v[202:205], v[182:185], v[52:55]
	v_mfma_f32_16x16x32_bf16 v[48:51], v[206:209], v[168:171], v[48:51]
	v_mfma_f32_16x16x32_bf16 v[44:47], v[206:209], v[172:175], v[44:47]
	v_mfma_f32_16x16x32_bf16 v[40:43], v[206:209], v[176:179], v[40:43]
	v_mfma_f32_16x16x32_bf16 v[36:39], v[206:209], v[182:185], v[36:39]
	v_mfma_f32_16x16x32_bf16 v[32:35], v[210:213], v[168:171], v[32:35]
	v_mfma_f32_16x16x32_bf16 v[28:31], v[210:213], v[172:175], v[28:31]
	v_mfma_f32_16x16x32_bf16 v[24:27], v[210:213], v[176:179], v[24:27]
	v_mfma_f32_16x16x32_bf16 v[20:23], v[210:213], v[182:185], v[20:23]
	v_mfma_f32_16x16x32_bf16 v[16:19], v[214:217], v[168:171], v[16:19]
	v_mfma_f32_16x16x32_bf16 v[12:15], v[214:217], v[172:175], v[12:15]
	v_mfma_f32_16x16x32_bf16 v[8:11], v[214:217], v[176:179], v[8:11]
	v_mfma_f32_16x16x32_bf16 v[4:7], v[214:217], v[182:185], v[2:5]

; template <int KK0, int KK1>
; DI void g256_compute(int tid, const char* sA, const char* sB, f32x4 (&acc)[8][4]) {
;   const int wid = tid >> 6, lane = tid & 63, wr = wid >> 2, wc = wid & 3, fr = lane & 15, fq = lane >> 4;
; #pragma unroll
;   for (int kk = KK0; kk < KK1; ++kk) {
;     bf16x8 b[4], a[4], a2[4];
; #pragma unroll
;     for (int n = 0; n < 4; ++n) { int row = wc * 64 + n * 16 + fr; b[n] = *(const bf16x8*)(sB + row * 128 + (((kk * 4 + fq) ^ (row & 7)) << 4)); }
; #pragma unroll
;     for (int m = 0; m < 4; ++m) { int row = wr * 128 + m * 16 + fr; a[m] = *(const bf16x8*)(sA + row * 128 + (((kk * 4 + fq) ^ (row & 7)) << 4)); }
;     __builtin_amdgcn_sched_barrier(0);
; #pragma unroll
;     for (int m = 0; m < 4; ++m) { int row = wr * 128 + (4 + m) * 16 + fr; a2[m] = *(const bf16x8*)(sA + row * 128 + (((kk * 4 + fq) ^ (row & 7)) << 4)); }
;     __builtin_amdgcn_s_setprio(1);
; #pragma unroll
;     for (int m = 0; m < 4; ++m)
; #pragma unroll
;       for (int n = 0; n < 4; ++n) acc[m][n] = __builtin_amdgcn_mfma_f32_16x16x32_bf16(a[m], b[n], acc[m][n], 0, 0, 0);
;     __builtin_amdgcn_sched_barrier(0);
; #pragma unroll
;     for (int m = 0; m < 4; ++m)
; #pragma unroll
;       for (int n = 0; n < 4; ++n) acc[4 + m][n] = __builtin_amdgcn_mfma_f32_16x16x32_bf16(a2[m], b[n], acc[4 + m][n], 0, 0, 0);
;     __builtin_amdgcn_s_setprio(0);
.LBB0_1132:
	v_add_u32_e32 v0, s22, v166
	v_add_u32_e32 v2, v0, v163
	v_add_u32_e32 v0, v0, v164
	ds_read_b128 v[168:171], v2 offset:32768
	ds_read_b128 v[172:175], v2 offset:34816
	ds_read_b128 v[176:179], v2 offset:36864
	ds_read_b128 v[182:185], v2 offset:38912
	ds_read_b128 v[186:189], v0
	ds_read_b128 v[190:193], v0 offset:2048
	ds_read_b128 v[194:197], v0 offset:4096
	ds_read_b128 v[198:201], v0 offset:6144
	ds_read_b128 v[202:205], v0 offset:8192
	ds_read_b128 v[206:209], v0 offset:10240
	ds_read_b128 v[210:213], v0 offset:12288
	ds_read_b128 v[214:217], v0 offset:14336
	s_waitcnt lgkmcnt(0)
	v_mfma_f32_16x16x32_bf16 v[128:131], v[186:189], v[168:171], v[128:131]
	v_mfma_f32_16x16x32_bf16 v[124:127], v[186:189], v[172:175], v[124:127]
	v_mfma_f32_16x16x32_bf16 v[120:123], v[186:189], v[176:179], v[120:123]
	v_mfma_f32_16x16x32_bf16 v[116:119], v[186:189], v[182:185], v[116:119]
	v_mfma_f32_16x16x32_bf16 v[112:115], v[190:193], v[168:171], v[112:115]
	v_mfma_f32_16x16x32_bf16 v[108:111], v[190:193], v[172:175], v[108:111]
	v_mfma_f32_16x16x32_bf16 v[104:107], v[190:193], v[176:179], v[104:107]
	v_mfma_f32_16x16x32_bf16 v[100:103], v[190:193], v[182:185], v[100:103]
	v_mfma_f32_16x16x32_bf16 v[96:99], v[194:197], v[168:171], v[96:99]
	v_mfma_f32_16x16x32_bf16 v[92:95], v[194:197], v[172:175], v[92:95]
	v_mfma_f32_16x16x32_bf16 v[88:91], v[194:197], v[176:179], v[88:91]
	v_mfma_f32_16x16x32_bf16 v[84:87], v[194:197], v[182:185], v[84:87]
	v_mfma_f32_16x16x32_bf16 v[80:83], v[198:201], v[168:171], v[80:83]
	v_mfma_f32_16x16x32_bf16 v[76:79], v[198:201], v[172:175], v[76:79]
	v_mfma_f32_16x16x32_bf16 v[72:75], v[198:201], v[176:179], v[72:75]
	v_mfma_f32_16x16x32_bf16 v[68:71], v[198:201], v[182:185], v[68:71]
	v_mfma_f32_16x16x32_bf16 v[64:67], v[202:205], v[168:171], v[64:67]
	v_mfma_f32_16x16x32_bf16 v[60:63], v[202:205], v[172:175], v[60:63]
	v_mfma_f32_16x16x32_bf16 v[56:59], v[202:205], v[176:179], v[56:59]
	v_mfma_f32_16x16x32_bf16 v[52:55], v[202:205], v[182:185], v[52:55]
	v_mfma_f32_16x16x32_bf16 v[48:51], v[206:209], v[168:171], v[48:51]
	v_mfma_f32_16x16x32_bf16 v[44:47], v[206:209], v[172:175], v[44:47]
	v_mfma_f32_16x16x32_bf16 v[40:43], v[206:209], v[176:179], v[40:43]
	v_mfma_f32_16x16x32_bf16 v[36:39], v[206:209], v[182:185], v[36:39]
	v_mfma_f32_16x16x32_bf16 v[32:35], v[210:213], v[168:171], v[32:35]
	v_mfma_f32_16x16x32_bf16 v[28:31], v[210:213], v[172:175], v[28:31]
	v_mfma_f32_16x16x32_bf16 v[24:27], v[210:213], v[176:179], v[24:27]
	v_mfma_f32_16x16x32_bf16 v[20:23], v[210:213], v[182:185], v[20:23]
	v_mfma_f32_16x16x32_bf16 v[16:19], v[214:217], v[168:171], v[16:19]
	v_mfma_f32_16x16x32_bf16 v[12:15], v[214:217], v[172:175], v[12:15]
	v_mfma_f32_16x16x32_bf16 v[8:11], v[214:217], v[176:179], v[8:11]
	v_mfma_f32_16x16x32_bf16 v[2:5], v[214:217], v[182:185], v[4:7]
	v_add_u32_e32 v0, s22, v165
	s_nop 0
	v_add_u32_e32 v6, v0, v163
	v_add_u32_e32 v0, v0, v164
	ds_read_b128 v[168:171], v6 offset:32768
	ds_read_b128 v[172:175], v6 offset:34816
	ds_read_b128 v[176:179], v6 offset:36864
	ds_read_b128 v[182:185], v6 offset:38912
	ds_read_b128 v[186:189], v0
	ds_read_b128 v[190:193], v0 offset:2048
	ds_read_b128 v[194:197], v0 offset:4096
	ds_read_b128 v[198:201], v0 offset:6144
	ds_read_b128 v[202:205], v0 offset:8192
	ds_read_b128 v[206:209], v0 offset:10240
	ds_read_b128 v[210:213], v0 offset:12288
	ds_read_b128 v[214:217], v0 offset:14336
	s_waitcnt lgkmcnt(0)
	v_mfma_f32_16x16x32_bf16 v[128:131], v[186:189], v[168:171], v[128:131]
	v_mfma_f32_16x16x32_bf16 v[124:127], v[186:189], v[172:175], v[124:127]
	v_mfma_f32_16x16x32_bf16 v[120:123], v[186:189], v[176:179], v[120:123]
	v_mfma_f32_16x16x32_bf16 v[116:119], v[186:189], v[182:185], v[116:119]
	v_mfma_f32_16x16x32_bf16 v[112:115], v[190:193], v[168:171], v[112:115]
	v_mfma_f32_16x16x32_bf16 v[108:111], v[190:193], v[172:175], v[108:111]
	v_mfma_f32_16x16x32_bf16 v[104:107], v[190:193], v[176:179], v[104:107]
	v_mfma_f32_16x16x32_bf16 v[100:103], v[190:193], v[182:185], v[100:103]
	v_mfma_f32_16x16x32_bf16 v[96:99], v[194:197], v[168:171], v[96:99]
	v_mfma_f32_16x16x32_bf16 v[92:95], v[194:197], v[172:175], v[92:95]
	v_mfma_f32_16x16x32_bf16 v[88:91], v[194:197], v[176:179], v[88:91]
	v_mfma_f32_16x16x32_bf16 v[84:87], v[194:197], v[182:185], v[84:87]
	v_mfma_f32_16x16x32_bf16 v[80:83], v[198:201], v[168:171], v[80:83]
	v_mfma_f32_16x16x32_bf16 v[76:79], v[198:201], v[172:175], v[76:79]
	v_mfma_f32_16x16x32_bf16 v[72:75], v[198:201], v[176:179], v[72:75]
	v_mfma_f32_16x16x32_bf16 v[68:71], v[198:201], v[182:185], v[68:71]
	v_mfma_f32_16x16x32_bf16 v[64:67], v[202:205], v[168:171], v[64:67]
	v_mfma_f32_16x16x32_bf16 v[60:63], v[202:205], v[172:175], v[60:63]
	v_mfma_f32_16x16x32_bf16 v[56:59], v[202:205], v[176:179], v[56:59]
	v_mfma_f32_16x16x32_bf16 v[52:55], v[202:205], v[182:185], v[52:55]
	v_mfma_f32_16x16x32_bf16 v[48:51], v[206:209], v[168:171], v[48:51]
	v_mfma_f32_16x16x32_bf16 v[44:47], v[206:209], v[172:175], v[44:47]
	v_mfma_f32_16x16x32_bf16 v[40:43], v[206:209], v[176:179], v[40:43]
	v_mfma_f32_16x16x32_bf16 v[36:39], v[206:209], v[182:185], v[36:39]
	v_mfma_f32_16x16x32_bf16 v[32:35], v[210:213], v[168:171], v[32:35]
	v_mfma_f32_16x16x32_bf16 v[28:31], v[210:213], v[172:175], v[28:31]
	v_mfma_f32_16x16x32_bf16 v[24:27], v[210:213], v[176:179], v[24:27]
	v_mfma_f32_16x16x32_bf16 v[20:23], v[210:213], v[182:185], v[20:23]
	v_mfma_f32_16x16x32_bf16 v[16:19], v[214:217], v[168:171], v[16:19]
	v_mfma_f32_16x16x32_bf16 v[12:15], v[214:217], v[172:175], v[12:15]
	v_mfma_f32_16x16x32_bf16 v[8:11], v[214:217], v[176:179], v[8:11]
	v_mfma_f32_16x16x32_bf16 v[4:7], v[214:217], v[182:185], v[2:5]

; template <class AF>
; DI void g256_stage(int tid, const AF& af, const bft* Bt, int ldb, int bcol, int kt, char* sA, char* sB) {
;     ...
;   for (int i = 0; i < 4; ++i) { int slot = tid + i * 512, row = slot >> 3, ch = (slot & 7) ^ (row & 7);
;     __builtin_amdgcn_global_load_lds((const unsigned*)af(row, kt, ch), (unsigned*)(sA + slot * 16), 16, 0, 0); }
; #pragma unroll
;   for (int i = 0; i < 4; ++i) { int slot = tid + i * 512, row = slot >> 3, ch = (slot & 7) ^ (row & 7);
;     __builtin_amdgcn_global_load_lds((const unsigned*)(Bt + (size_t)(bcol + row) * ldb + kt * 64 + ch * 8), (unsigned*)(sB + slot * 16), 16, 0, 0); }
; template <class AF>
; DI void g256_mainloop_t(int tid, const AF& af, const bft* Bt, int ldb, int bcol, int K, f32x4 (&acc)[8][4]) {
;     ...
;     asm volatile("s_waitcnt vmcnt(0)" ::: "memory");
;     __syncthreads();
;     char* cur = smem + (kt & 1) * 65536; char* nxt = smem + ((kt + 1) & 1) * 65536;
;     if (tid < 256) {
;       if (kt + 1 < nk) g256_stage(tid, af, Bt, ldb, bcol, kt + 1, nxt, nxt + 32768);
;       g256_compute<0, 2>(tid, cur, cur + 32768, acc);
;     } else {
;       g256_compute<0, 1>(tid, cur, cur + 32768, acc);
;       if (kt + 1 < nk) g256_stage(tid, af, Bt, ldb, bcol, kt + 1, nxt, nxt + 32768);
.LBB0_1134:
	s_add_i32 s8, s21, 0xffff0000
	s_waitcnt vmcnt(0)
	s_and_b32 s8, s8, 0x10000
	s_add_i32 s22, s8, 16
	s_and_b32 s8, s21, 0x10000
	s_add_i32 s23, s8, 16
	s_waitcnt vmcnt(0) lgkmcnt(0)
	s_barrier
	s_and_saveexec_b64 s[8:9], vcc
	s_xor_b64 s[8:9], exec, s[8:9]
	s_cbranch_execz .LBB0_1138
	v_add_u32_e32 v0, s22, v162
	v_add_u32_e32 v2, v0, v163
	v_add_u32_e32 v0, v0, v164
	ds_read_b128 v[168:171], v2 offset:32768
	ds_read_b128 v[172:175], v2 offset:34816
	ds_read_b128 v[176:179], v2 offset:36864
	ds_read_b128 v[182:185], v2 offset:38912
	ds_read_b128 v[186:189], v0
	ds_read_b128 v[190:193], v0 offset:2048
	ds_read_b128 v[194:197], v0 offset:4096
	ds_read_b128 v[198:201], v0 offset:6144
	ds_read_b128 v[202:205], v0 offset:8192
	ds_read_b128 v[206:209], v0 offset:10240
	ds_read_b128 v[210:213], v0 offset:12288
	ds_read_b128 v[214:217], v0 offset:14336
	s_waitcnt lgkmcnt(7)
	v_mfma_f32_16x16x32_bf16 v[128:131], v[186:189], v[168:171], v[128:131]
	v_mfma_f32_16x16x32_bf16 v[124:127], v[186:189], v[172:175], v[124:127]
	v_mfma_f32_16x16x32_bf16 v[120:123], v[186:189], v[176:179], v[120:123]
	v_mfma_f32_16x16x32_bf16 v[116:119], v[186:189], v[182:185], v[116:119]
	s_waitcnt lgkmcnt(6)
	v_mfma_f32_16x16x32_bf16 v[112:115], v[190:193], v[168:171], v[112:115]
	v_mfma_f32_16x16x32_bf16 v[108:111], v[190:193], v[172:175], v[108:111]
	v_mfma_f32_16x16x32_bf16 v[104:107], v[190:193], v[176:179], v[104:107]
	v_mfma_f32_16x16x32_bf16 v[100:103], v[190:193], v[182:185], v[100:103]
	s_waitcnt lgkmcnt(5)
	v_mfma_f32_16x16x32_bf16 v[96:99], v[194:197], v[168:171], v[96:99]
	v_mfma_f32_16x16x32_bf16 v[92:95], v[194:197], v[172:175], v[92:95]
	v_mfma_f32_16x16x32_bf16 v[88:91], v[194:197], v[176:179], v[88:91]
	v_mfma_f32_16x16x32_bf16 v[84:87], v[194:197], v[182:185], v[84:87]
	s_waitcnt lgkmcnt(4)
	v_mfma_f32_16x16x32_bf16 v[80:83], v[198:201], v[168:171], v[80:83]
	v_mfma_f32_16x16x32_bf16 v[76:79], v[198:201], v[172:175], v[76:79]
	v_mfma_f32_16x16x32_bf16 v[72:75], v[198:201], v[176:179], v[72:75]
	v_mfma_f32_16x16x32_bf16 v[68:71], v[198:201], v[182:185], v[68:71]
	s_waitcnt lgkmcnt(3)
	v_mfma_f32_16x16x32_bf16 v[64:67], v[202:205], v[168:171], v[64:67]
	v_mfma_f32_16x16x32_bf16 v[60:63], v[202:205], v[172:175], v[60:63]
	v_mfma_f32_16x16x32_bf16 v[56:59], v[202:205], v[176:179], v[56:59]
	v_mfma_f32_16x16x32_bf16 v[52:55], v[202:205], v[182:185], v[52:55]
	s_waitcnt lgkmcnt(2)
	v_mfma_f32_16x16x32_bf16 v[48:51], v[206:209], v[168:171], v[48:51]
	v_mfma_f32_16x16x32_bf16 v[44:47], v[206:209], v[172:175], v[44:47]
	v_mfma_f32_16x16x32_bf16 v[40:43], v[206:209], v[176:179], v[40:43]
	v_mfma_f32_16x16x32_bf16 v[36:39], v[206:209], v[182:185], v[36:39]
	s_waitcnt lgkmcnt(1)
	v_mfma_f32_16x16x32_bf16 v[32:35], v[210:213], v[168:171], v[32:35]
	v_mfma_f32_16x16x32_bf16 v[28:31], v[210:213], v[172:175], v[28:31]
	v_mfma_f32_16x16x32_bf16 v[24:27], v[210:213], v[176:179], v[24:27]
	v_mfma_f32_16x16x32_bf16 v[20:23], v[210:213], v[182:185], v[20:23]
	s_waitcnt lgkmcnt(0)
	v_mfma_f32_16x16x32_bf16 v[16:19], v[214:217], v[168:171], v[16:19]
	v_mfma_f32_16x16x32_bf16 v[12:15], v[214:217], v[172:175], v[12:15]
	v_mfma_f32_16x16x32_bf16 v[8:11], v[214:217], v[176:179], v[8:11]
	v_mfma_f32_16x16x32_bf16 v[2:5], v[214:217], v[182:185], v[4:7]
	s_cmp_gt_u32 s20, 14
	s_cbranch_scc1 .LBB0_1137
	v_add_u32_e32 v0, s23, v158
	v_add_u32_e32 v167, s23, v159
	v_readfirstlane_b32 s30, v0
	v_lshl_add_u64 v[6:7], v[132:133], 0, s[0:1]
	s_mov_b32 m0, s30
	v_readfirstlane_b32 s30, v167
	v_add_u32_e32 v168, s23, v160
	global_load_lds_dwordx4 v[6:7], off
	v_lshl_add_u64 v[6:7], v[134:135], 0, s[0:1]
	s_mov_b32 m0, s30
	v_readfirstlane_b32 s30, v168
	v_add_u32_e32 v169, s23, v161
	global_load_lds_dwordx4 v[6:7], off
	v_lshl_add_u64 v[6:7], v[136:137], 0, s[0:1]
	s_mov_b32 m0, s30
	v_readfirstlane_b32 s30, v169
	v_add_u32_e32 v0, 0x8000, v0
	global_load_lds_dwordx4 v[6:7], off
	v_lshl_add_u64 v[6:7], v[138:139], 0, s[0:1]
	s_mov_b32 m0, s30
	v_readfirstlane_b32 s30, v0
	v_add_u32_e32 v0, 0x8000, v167
	global_load_lds_dwordx4 v[6:7], off
	v_lshl_add_u64 v[6:7], v[140:141], 0, s[0:1]
	s_mov_b32 m0, s30
	v_readfirstlane_b32 s30, v0
	v_add_u32_e32 v0, 0x8000, v168
	global_load_lds_dwordx4 v[6:7], off
	v_lshl_add_u64 v[6:7], v[142:143], 0, s[0:1]
	s_mov_b32 m0, s30
	v_readfirstlane_b32 s30, v0
	v_add_u32_e32 v0, 0x8000, v169
	global_load_lds_dwordx4 v[6:7], off
	v_lshl_add_u64 v[6:7], v[144:145], 0, s[0:1]
	s_mov_b32 m0, s30
	v_readfirstlane_b32 s30, v0
	global_load_lds_dwordx4 v[6:7], off
	v_lshl_add_u64 v[6:7], v[146:147], 0, s[0:1]
	s_mov_b32 m0, s30
	s_nop 0
	global_load_lds_dwordx4 v[6:7], off
; template <int KK0, int KK1>
; DI void g256_compute(int tid, const char* sA, const char* sB, f32x4 (&acc)[8][4]) {
;     ...
;   for (int kk = KK0; kk < KK1; ++kk) {
;     bf16x8 b[4], a[4], a2[4];
; #pragma unroll
;     for (int n = 0; n < 4; ++n) { int row = wc * 64 + n * 16 + fr; b[n] = *(const bf16x8*)(sB + row * 128 + (((kk * 4 + fq) ^ (row & 7)) << 4)); }
; #pragma unroll
;     for (int m = 0; m < 4; ++m) { int row = wr * 128 + m * 16 + fr; a[m] = *(const bf16x8*)(sA + row * 128 + (((kk * 4 + fq) ^ (row & 7)) << 4)); }
;     __builtin_amdgcn_sched_barrier(0);
; #pragma unroll
;     for (int m = 0; m < 4; ++m) { int row = wr * 128 + (4 + m) * 16 + fr; a2[m] = *(const bf16x8*)(sA + row * 128 + (((kk * 4 + fq) ^ (row & 7)) << 4)); }
;     __builtin_amdgcn_s_setprio(1);
; #pragma unroll
;     for (int m = 0; m < 4; ++m)
; #pragma unroll
;       for (int n = 0; n < 4; ++n) acc[m][n] = __builtin_amdgcn_mfma_f32_16x16x32_bf16(a[m], b[n], acc[m][n], 0, 0, 0);
;     __builtin_amdgcn_sched_barrier(0);
; #pragma unroll
;     for (int m = 0; m < 4; ++m)
; #pragma unroll
;       for (int n = 0; n < 4; ++n) acc[4 + m][n] = __builtin_amdgcn_mfma_f32_16x16x32_bf16(a2[m], b[n], acc[4 + m][n], 0, 0, 0);
;     __builtin_amdgcn_s_setprio(0);
.LBB0_1137:
	v_add_u32_e32 v0, s22, v165
	v_add_u32_e32 v6, v0, v163
	v_add_u32_e32 v0, v0, v164
	ds_read_b128 v[168:171], v6 offset:32768
	ds_read_b128 v[172:175], v6 offset:34816
	ds_read_b128 v[176:179], v6 offset:36864
	ds_read_b128 v[182:185], v6 offset:38912
	ds_read_b128 v[186:189], v0
	ds_read_b128 v[190:193], v0 offset:2048
	ds_read_b128 v[194:197], v0 offset:4096
	ds_read_b128 v[198:201], v0 offset:6144
	ds_read_b128 v[202:205], v0 offset:8192
	ds_read_b128 v[206:209], v0 offset:10240
	ds_read_b128 v[210:213], v0 offset:12288
	ds_read_b128 v[214:217], v0 offset:14336
	s_waitcnt lgkmcnt(0)
	v_mfma_f32_16x16x32_bf16 v[128:131], v[186:189], v[168:171], v[128:131]
	v_mfma_f32_16x16x32_bf16 v[124:127], v[186:189], v[172:175], v[124:127]
	v_mfma_f32_16x16x32_bf16 v[120:123], v[186:189], v[176:179], v[120:123]
	v_mfma_f32_16x16x32_bf16 v[116:119], v[186:189], v[182:185], v[116:119]
	v_mfma_f32_16x16x32_bf16 v[112:115], v[190:193], v[168:171], v[112:115]
	v_mfma_f32_16x16x32_bf16 v[108:111], v[190:193], v[172:175], v[108:111]
	v_mfma_f32_16x16x32_bf16 v[104:107], v[190:193], v[176:179], v[104:107]
	v_mfma_f32_16x16x32_bf16 v[100:103], v[190:193], v[182:185], v[100:103]
	v_mfma_f32_16x16x32_bf16 v[96:99], v[194:197], v[168:171], v[96:99]
	v_mfma_f32_16x16x32_bf16 v[92:95], v[194:197], v[172:175], v[92:95]
	v_mfma_f32_16x16x32_bf16 v[88:91], v[194:197], v[176:179], v[88:91]
	v_mfma_f32_16x16x32_bf16 v[84:87], v[194:197], v[182:185], v[84:87]
	v_mfma_f32_16x16x32_bf16 v[80:83], v[198:201], v[168:171], v[80:83]
	v_mfma_f32_16x16x32_bf16 v[76:79], v[198:201], v[172:175], v[76:79]
	v_mfma_f32_16x16x32_bf16 v[72:75], v[198:201], v[176:179], v[72:75]
	v_mfma_f32_16x16x32_bf16 v[68:71], v[198:201], v[182:185], v[68:71]
	v_mfma_f32_16x16x32_bf16 v[64:67], v[202:205], v[168:171], v[64:67]
	v_mfma_f32_16x16x32_bf16 v[60:63], v[202:205], v[172:175], v[60:63]
	v_mfma_f32_16x16x32_bf16 v[56:59], v[202:205], v[176:179], v[56:59]
	v_mfma_f32_16x16x32_bf16 v[52:55], v[202:205], v[182:185], v[52:55]
	v_mfma_f32_16x16x32_bf16 v[48:51], v[206:209], v[168:171], v[48:51]
	v_mfma_f32_16x16x32_bf16 v[44:47], v[206:209], v[172:175], v[44:47]
	v_mfma_f32_16x16x32_bf16 v[40:43], v[206:209], v[176:179], v[40:43]
	v_mfma_f32_16x16x32_bf16 v[36:39], v[206:209], v[182:185], v[36:39]
	v_mfma_f32_16x16x32_bf16 v[32:35], v[210:213], v[168:171], v[32:35]
	v_mfma_f32_16x16x32_bf16 v[28:31], v[210:213], v[172:175], v[28:31]
	v_mfma_f32_16x16x32_bf16 v[24:27], v[210:213], v[176:179], v[24:27]
	v_mfma_f32_16x16x32_bf16 v[20:23], v[210:213], v[182:185], v[20:23]
	v_mfma_f32_16x16x32_bf16 v[16:19], v[214:217], v[168:171], v[16:19]
	v_mfma_f32_16x16x32_bf16 v[12:15], v[214:217], v[172:175], v[12:15]
	v_mfma_f32_16x16x32_bf16 v[8:11], v[214:217], v[176:179], v[8:11]
	v_mfma_f32_16x16x32_bf16 v[4:7], v[214:217], v[182:185], v[2:5]

; template <int KK0, int KK1>
; DI void g256_compute(int tid, const char* sA, const char* sB, f32x4 (&acc)[8][4]) {
;   const int wid = tid >> 6, lane = tid & 63, wr = wid >> 2, wc = wid & 3, fr = lane & 15, fq = lane >> 4;
; #pragma unroll
;   for (int kk = KK0; kk < KK1; ++kk) {
;     bf16x8 b[4], a[4], a2[4];
; #pragma unroll
;     for (int n = 0; n < 4; ++n) { int row = wc * 64 + n * 16 + fr; b[n] = *(const bf16x8*)(sB + row * 128 + (((kk * 4 + fq) ^ (row & 7)) << 4)); }
; #pragma unroll
;     for (int m = 0; m < 4; ++m) { int row = wr * 128 + m * 16 + fr; a[m] = *(const bf16x8*)(sA + row * 128 + (((kk * 4 + fq) ^ (row & 7)) << 4)); }
;     __builtin_amdgcn_sched_barrier(0);
; #pragma unroll
;     for (int m = 0; m < 4; ++m) { int row = wr * 128 + (4 + m) * 16 + fr; a2[m] = *(const bf16x8*)(sA + row * 128 + (((kk * 4 + fq) ^ (row & 7)) << 4)); }
;     __builtin_amdgcn_s_setprio(1);
; #pragma unroll
;     for (int m = 0; m < 4; ++m)
; #pragma unroll
;       for (int n = 0; n < 4; ++n) acc[m][n] = __builtin_amdgcn_mfma_f32_16x16x32_bf16(a[m], b[n], acc[m][n], 0, 0, 0);
;     __builtin_amdgcn_sched_barrier(0);
; #pragma unroll
;     for (int m = 0; m < 4; ++m)
; #pragma unroll
;       for (int n = 0; n < 4; ++n) acc[4 + m][n] = __builtin_amdgcn_mfma_f32_16x16x32_bf16(a2[m], b[n], acc[4 + m][n], 0, 0, 0);
;     __builtin_amdgcn_s_setprio(0);
.LBB0_1771:
	v_add_u32_e32 v0, s30, v158
	v_add_u32_e32 v2, v0, v155
	v_add_u32_e32 v0, v0, v156
	ds_read_b128 v[160:163], v2 offset:32768
	ds_read_b128 v[164:167], v2 offset:34816
	ds_read_b128 v[168:171], v2 offset:36864
	ds_read_b128 v[172:175], v2 offset:38912
	ds_read_b128 v[176:179], v0
	ds_read_b128 v[182:185], v0 offset:2048
	ds_read_b128 v[186:189], v0 offset:4096
	ds_read_b128 v[190:193], v0 offset:6144
	ds_read_b128 v[194:197], v0 offset:8192
	ds_read_b128 v[198:201], v0 offset:10240
	ds_read_b128 v[202:205], v0 offset:12288
	ds_read_b128 v[206:209], v0 offset:14336
	s_waitcnt lgkmcnt(0)
	v_mfma_f32_16x16x32_bf16 v[128:131], v[176:179], v[160:163], v[128:131]
	v_mfma_f32_16x16x32_bf16 v[124:127], v[176:179], v[164:167], v[124:127]
	v_mfma_f32_16x16x32_bf16 v[120:123], v[176:179], v[168:171], v[120:123]
	v_mfma_f32_16x16x32_bf16 v[116:119], v[176:179], v[172:175], v[116:119]
	v_mfma_f32_16x16x32_bf16 v[112:115], v[182:185], v[160:163], v[112:115]
	v_mfma_f32_16x16x32_bf16 v[108:111], v[182:185], v[164:167], v[108:111]
	v_mfma_f32_16x16x32_bf16 v[104:107], v[182:185], v[168:171], v[104:107]
	v_mfma_f32_16x16x32_bf16 v[100:103], v[182:185], v[172:175], v[100:103]
	v_mfma_f32_16x16x32_bf16 v[96:99], v[186:189], v[160:163], v[96:99]
	v_mfma_f32_16x16x32_bf16 v[92:95], v[186:189], v[164:167], v[92:95]
	v_mfma_f32_16x16x32_bf16 v[88:91], v[186:189], v[168:171], v[88:91]
	v_mfma_f32_16x16x32_bf16 v[84:87], v[186:189], v[172:175], v[84:87]
	v_mfma_f32_16x16x32_bf16 v[80:83], v[190:193], v[160:163], v[80:83]
	v_mfma_f32_16x16x32_bf16 v[76:79], v[190:193], v[164:167], v[76:79]
	v_mfma_f32_16x16x32_bf16 v[72:75], v[190:193], v[168:171], v[72:75]
	v_mfma_f32_16x16x32_bf16 v[68:71], v[190:193], v[172:175], v[68:71]
	v_mfma_f32_16x16x32_bf16 v[64:67], v[194:197], v[160:163], v[64:67]
	v_mfma_f32_16x16x32_bf16 v[60:63], v[194:197], v[164:167], v[60:63]
	v_mfma_f32_16x16x32_bf16 v[56:59], v[194:197], v[168:171], v[56:59]
	v_mfma_f32_16x16x32_bf16 v[52:55], v[194:197], v[172:175], v[52:55]
	v_mfma_f32_16x16x32_bf16 v[48:51], v[198:201], v[160:163], v[48:51]
	v_mfma_f32_16x16x32_bf16 v[44:47], v[198:201], v[164:167], v[44:47]
	v_mfma_f32_16x16x32_bf16 v[40:43], v[198:201], v[168:171], v[40:43]
	v_mfma_f32_16x16x32_bf16 v[36:39], v[198:201], v[172:175], v[36:39]
	v_mfma_f32_16x16x32_bf16 v[32:35], v[202:205], v[160:163], v[32:35]
	v_mfma_f32_16x16x32_bf16 v[28:31], v[202:205], v[164:167], v[28:31]
	v_mfma_f32_16x16x32_bf16 v[24:27], v[202:205], v[168:171], v[24:27]
	v_mfma_f32_16x16x32_bf16 v[20:23], v[202:205], v[172:175], v[20:23]
	v_mfma_f32_16x16x32_bf16 v[16:19], v[206:209], v[160:163], v[16:19]
	v_mfma_f32_16x16x32_bf16 v[12:15], v[206:209], v[164:167], v[12:15]
	v_mfma_f32_16x16x32_bf16 v[8:11], v[206:209], v[168:171], v[8:11]
	v_mfma_f32_16x16x32_bf16 v[2:5], v[206:209], v[172:175], v[4:7]
	v_add_u32_e32 v0, s30, v157
	s_nop 0
	v_add_u32_e32 v6, v0, v155
	v_add_u32_e32 v0, v0, v156
	ds_read_b128 v[160:163], v6 offset:32768
	ds_read_b128 v[164:167], v6 offset:34816
	ds_read_b128 v[168:171], v6 offset:36864
	ds_read_b128 v[172:175], v6 offset:38912
	ds_read_b128 v[176:179], v0
	ds_read_b128 v[182:185], v0 offset:2048
	ds_read_b128 v[186:189], v0 offset:4096
	ds_read_b128 v[190:193], v0 offset:6144
	ds_read_b128 v[194:197], v0 offset:8192
	ds_read_b128 v[198:201], v0 offset:10240
	ds_read_b128 v[202:205], v0 offset:12288
	ds_read_b128 v[206:209], v0 offset:14336
	s_waitcnt lgkmcnt(0)
	v_mfma_f32_16x16x32_bf16 v[128:131], v[176:179], v[160:163], v[128:131]
	v_mfma_f32_16x16x32_bf16 v[124:127], v[176:179], v[164:167], v[124:127]
	v_mfma_f32_16x16x32_bf16 v[120:123], v[176:179], v[168:171], v[120:123]
	v_mfma_f32_16x16x32_bf16 v[116:119], v[176:179], v[172:175], v[116:119]
	v_mfma_f32_16x16x32_bf16 v[112:115], v[182:185], v[160:163], v[112:115]
	v_mfma_f32_16x16x32_bf16 v[108:111], v[182:185], v[164:167], v[108:111]
	v_mfma_f32_16x16x32_bf16 v[104:107], v[182:185], v[168:171], v[104:107]
	v_mfma_f32_16x16x32_bf16 v[100:103], v[182:185], v[172:175], v[100:103]
	v_mfma_f32_16x16x32_bf16 v[96:99], v[186:189], v[160:163], v[96:99]
	v_mfma_f32_16x16x32_bf16 v[92:95], v[186:189], v[164:167], v[92:95]
	v_mfma_f32_16x16x32_bf16 v[88:91], v[186:189], v[168:171], v[88:91]
	v_mfma_f32_16x16x32_bf16 v[84:87], v[186:189], v[172:175], v[84:87]
	v_mfma_f32_16x16x32_bf16 v[80:83], v[190:193], v[160:163], v[80:83]
	v_mfma_f32_16x16x32_bf16 v[76:79], v[190:193], v[164:167], v[76:79]
	v_mfma_f32_16x16x32_bf16 v[72:75], v[190:193], v[168:171], v[72:75]
	v_mfma_f32_16x16x32_bf16 v[68:71], v[190:193], v[172:175], v[68:71]
	v_mfma_f32_16x16x32_bf16 v[64:67], v[194:197], v[160:163], v[64:67]
	v_mfma_f32_16x16x32_bf16 v[60:63], v[194:197], v[164:167], v[60:63]
	v_mfma_f32_16x16x32_bf16 v[56:59], v[194:197], v[168:171], v[56:59]
	v_mfma_f32_16x16x32_bf16 v[52:55], v[194:197], v[172:175], v[52:55]
	v_mfma_f32_16x16x32_bf16 v[48:51], v[198:201], v[160:163], v[48:51]
	v_mfma_f32_16x16x32_bf16 v[44:47], v[198:201], v[164:167], v[44:47]
	v_mfma_f32_16x16x32_bf16 v[40:43], v[198:201], v[168:171], v[40:43]
	v_mfma_f32_16x16x32_bf16 v[36:39], v[198:201], v[172:175], v[36:39]
	v_mfma_f32_16x16x32_bf16 v[32:35], v[202:205], v[160:163], v[32:35]
	v_mfma_f32_16x16x32_bf16 v[28:31], v[202:205], v[164:167], v[28:31]
	v_mfma_f32_16x16x32_bf16 v[24:27], v[202:205], v[168:171], v[24:27]
	v_mfma_f32_16x16x32_bf16 v[20:23], v[202:205], v[172:175], v[20:23]
	v_mfma_f32_16x16x32_bf16 v[16:19], v[206:209], v[160:163], v[16:19]
	v_mfma_f32_16x16x32_bf16 v[12:15], v[206:209], v[164:167], v[12:15]
	v_mfma_f32_16x16x32_bf16 v[8:11], v[206:209], v[168:171], v[8:11]
	v_mfma_f32_16x16x32_bf16 v[4:7], v[206:209], v[172:175], v[2:5]

; template <class AF>
; DI void g256_stage(int tid, const AF& af, const bft* Bt, int ldb, int bcol, int kt, char* sA, char* sB) {
;     ...
;   for (int i = 0; i < 4; ++i) { int slot = tid + i * 512, row = slot >> 3, ch = (slot & 7) ^ (row & 7);
;     __builtin_amdgcn_global_load_lds((const unsigned*)af(row, kt, ch), (unsigned*)(sA + slot * 16), 16, 0, 0); }
; #pragma unroll
;   for (int i = 0; i < 4; ++i) { int slot = tid + i * 512, row = slot >> 3, ch = (slot & 7) ^ (row & 7);
;     __builtin_amdgcn_global_load_lds((const unsigned*)(Bt + (size_t)(bcol + row) * ldb + kt * 64 + ch * 8), (unsigned*)(sB + slot * 16), 16, 0, 0); }
; template <class AF>
; DI void g256_mainloop_t(int tid, const AF& af, const bft* Bt, int ldb, int bcol, int K, f32x4 (&acc)[8][4]) {
;     ...
;     asm volatile("s_waitcnt vmcnt(0)" ::: "memory");
;     __syncthreads();
;     char* cur = smem + (kt & 1) * 65536; char* nxt = smem + ((kt + 1) & 1) * 65536;
;     if (tid < 256) {
;       if (kt + 1 < nk) g256_stage(tid, af, Bt, ldb, bcol, kt + 1, nxt, nxt + 32768);
;       g256_compute<0, 2>(tid, cur, cur + 32768, acc);
;     } else {
;       g256_compute<0, 1>(tid, cur, cur + 32768, acc);
;       if (kt + 1 < nk) g256_stage(tid, af, Bt, ldb, bcol, kt + 1, nxt, nxt + 32768);
.LBB0_1773:
	s_add_i32 s18, s29, 0xffff0000
	s_waitcnt vmcnt(0)
	s_and_b32 s18, s18, 0x10000
	s_add_i32 s30, s18, 16
	s_and_b32 s18, s29, 0x10000
	s_add_i32 s31, s18, 16
	s_waitcnt vmcnt(0) lgkmcnt(0)
	s_barrier
	s_and_saveexec_b64 s[18:19], vcc
	s_xor_b64 s[18:19], exec, s[18:19]
	s_cbranch_execz .LBB0_1777
	v_add_u32_e32 v0, s30, v154
	v_add_u32_e32 v2, v0, v155
	v_add_u32_e32 v0, v0, v156
	ds_read_b128 v[160:163], v2 offset:32768
	ds_read_b128 v[164:167], v2 offset:34816
	ds_read_b128 v[168:171], v2 offset:36864
	ds_read_b128 v[172:175], v2 offset:38912
	ds_read_b128 v[176:179], v0
	ds_read_b128 v[182:185], v0 offset:2048
	ds_read_b128 v[186:189], v0 offset:4096
	ds_read_b128 v[190:193], v0 offset:6144
	ds_read_b128 v[194:197], v0 offset:8192
	ds_read_b128 v[198:201], v0 offset:10240
	ds_read_b128 v[202:205], v0 offset:12288
	ds_read_b128 v[206:209], v0 offset:14336
	s_waitcnt lgkmcnt(7)
	v_mfma_f32_16x16x32_bf16 v[128:131], v[176:179], v[160:163], v[128:131]
	v_mfma_f32_16x16x32_bf16 v[124:127], v[176:179], v[164:167], v[124:127]
	v_mfma_f32_16x16x32_bf16 v[120:123], v[176:179], v[168:171], v[120:123]
	v_mfma_f32_16x16x32_bf16 v[116:119], v[176:179], v[172:175], v[116:119]
	s_waitcnt lgkmcnt(6)
	v_mfma_f32_16x16x32_bf16 v[112:115], v[182:185], v[160:163], v[112:115]
	v_mfma_f32_16x16x32_bf16 v[108:111], v[182:185], v[164:167], v[108:111]
	v_mfma_f32_16x16x32_bf16 v[104:107], v[182:185], v[168:171], v[104:107]
	v_mfma_f32_16x16x32_bf16 v[100:103], v[182:185], v[172:175], v[100:103]
	s_waitcnt lgkmcnt(5)
	v_mfma_f32_16x16x32_bf16 v[96:99], v[186:189], v[160:163], v[96:99]
	v_mfma_f32_16x16x32_bf16 v[92:95], v[186:189], v[164:167], v[92:95]
	v_mfma_f32_16x16x32_bf16 v[88:91], v[186:189], v[168:171], v[88:91]
	v_mfma_f32_16x16x32_bf16 v[84:87], v[186:189], v[172:175], v[84:87]
	s_waitcnt lgkmcnt(4)
	v_mfma_f32_16x16x32_bf16 v[80:83], v[190:193], v[160:163], v[80:83]
	v_mfma_f32_16x16x32_bf16 v[76:79], v[190:193], v[164:167], v[76:79]
	v_mfma_f32_16x16x32_bf16 v[72:75], v[190:193], v[168:171], v[72:75]
	v_mfma_f32_16x16x32_bf16 v[68:71], v[190:193], v[172:175], v[68:71]
	s_waitcnt lgkmcnt(3)
	v_mfma_f32_16x16x32_bf16 v[64:67], v[194:197], v[160:163], v[64:67]
	v_mfma_f32_16x16x32_bf16 v[60:63], v[194:197], v[164:167], v[60:63]
	v_mfma_f32_16x16x32_bf16 v[56:59], v[194:197], v[168:171], v[56:59]
	v_mfma_f32_16x16x32_bf16 v[52:55], v[194:197], v[172:175], v[52:55]
	s_waitcnt lgkmcnt(2)
	v_mfma_f32_16x16x32_bf16 v[48:51], v[198:201], v[160:163], v[48:51]
	v_mfma_f32_16x16x32_bf16 v[44:47], v[198:201], v[164:167], v[44:47]
	v_mfma_f32_16x16x32_bf16 v[40:43], v[198:201], v[168:171], v[40:43]
	v_mfma_f32_16x16x32_bf16 v[36:39], v[198:201], v[172:175], v[36:39]
	s_waitcnt lgkmcnt(1)
	v_mfma_f32_16x16x32_bf16 v[32:35], v[202:205], v[160:163], v[32:35]
	v_mfma_f32_16x16x32_bf16 v[28:31], v[202:205], v[164:167], v[28:31]
	v_mfma_f32_16x16x32_bf16 v[24:27], v[202:205], v[168:171], v[24:27]
	v_mfma_f32_16x16x32_bf16 v[20:23], v[202:205], v[172:175], v[20:23]
	s_waitcnt lgkmcnt(0)
	v_mfma_f32_16x16x32_bf16 v[16:19], v[206:209], v[160:163], v[16:19]
	v_mfma_f32_16x16x32_bf16 v[12:15], v[206:209], v[164:167], v[12:15]
	v_mfma_f32_16x16x32_bf16 v[8:11], v[206:209], v[168:171], v[8:11]
	v_mfma_f32_16x16x32_bf16 v[2:5], v[206:209], v[172:175], v[4:7]
	s_cmp_gt_u32 s27, 14
	s_cbranch_scc1 .LBB0_1776
	v_add_u32_e32 v0, s31, v150
	v_add_u32_e32 v159, s31, v151
	v_readfirstlane_b32 s34, v0
	v_lshl_add_u64 v[6:7], v[132:133], 0, s[16:17]
	s_mov_b32 m0, s34
	v_readfirstlane_b32 s34, v159
	v_add_u32_e32 v160, s31, v152
	global_load_lds_dwordx4 v[6:7], off
	v_lshl_add_u64 v[6:7], v[134:135], 0, s[16:17]
	s_mov_b32 m0, s34
	v_readfirstlane_b32 s34, v160
	v_add_u32_e32 v161, s31, v153
	global_load_lds_dwordx4 v[6:7], off
	v_lshl_add_u64 v[6:7], v[136:137], 0, s[16:17]
	s_mov_b32 m0, s34
	v_readfirstlane_b32 s34, v161
	v_add_u32_e32 v0, 0x8000, v0
	global_load_lds_dwordx4 v[6:7], off
	v_lshl_add_u64 v[6:7], v[138:139], 0, s[16:17]
	s_mov_b32 m0, s34
	v_readfirstlane_b32 s34, v0
	v_add_u32_e32 v0, 0x8000, v159
	global_load_lds_dwordx4 v[6:7], off
	v_lshl_add_u64 v[6:7], v[140:141], 0, s[16:17]
	s_mov_b32 m0, s34
	v_readfirstlane_b32 s34, v0
	v_add_u32_e32 v0, 0x8000, v160
	global_load_lds_dwordx4 v[6:7], off
	v_lshl_add_u64 v[6:7], v[142:143], 0, s[16:17]
	s_mov_b32 m0, s34
	v_readfirstlane_b32 s34, v0
	v_add_u32_e32 v0, 0x8000, v161
	global_load_lds_dwordx4 v[6:7], off
	v_lshl_add_u64 v[6:7], v[144:145], 0, s[16:17]
	s_mov_b32 m0, s34
	v_readfirstlane_b32 s34, v0
	global_load_lds_dwordx4 v[6:7], off
	v_lshl_add_u64 v[6:7], v[146:147], 0, s[16:17]
	s_mov_b32 m0, s34
	s_nop 0
	global_load_lds_dwordx4 v[6:7], off
; template <int KK0, int KK1>
; DI void g256_compute(int tid, const char* sA, const char* sB, f32x4 (&acc)[8][4]) {
;     ...
;   for (int kk = KK0; kk < KK1; ++kk) {
;     bf16x8 b[4], a[4], a2[4];
; #pragma unroll
;     for (int n = 0; n < 4; ++n) { int row = wc * 64 + n * 16 + fr; b[n] = *(const bf16x8*)(sB + row * 128 + (((kk * 4 + fq) ^ (row & 7)) << 4)); }
; #pragma unroll
;     for (int m = 0; m < 4; ++m) { int row = wr * 128 + m * 16 + fr; a[m] = *(const bf16x8*)(sA + row * 128 + (((kk * 4 + fq) ^ (row & 7)) << 4)); }
;     __builtin_amdgcn_sched_barrier(0);
; #pragma unroll
;     for (int m = 0; m < 4; ++m) { int row = wr * 128 + (4 + m) * 16 + fr; a2[m] = *(const bf16x8*)(sA + row * 128 + (((kk * 4 + fq) ^ (row & 7)) << 4)); }
;     __builtin_amdgcn_s_setprio(1);
; #pragma unroll
;     for (int m = 0; m < 4; ++m)
; #pragma unroll
;       for (int n = 0; n < 4; ++n) acc[m][n] = __builtin_amdgcn_mfma_f32_16x16x32_bf16(a[m], b[n], acc[m][n], 0, 0, 0);
;     __builtin_amdgcn_sched_barrier(0);
; #pragma unroll
;     for (int m = 0; m < 4; ++m)
; #pragma unroll
;       for (int n = 0; n < 4; ++n) acc[4 + m][n] = __builtin_amdgcn_mfma_f32_16x16x32_bf16(a2[m], b[n], acc[4 + m][n], 0, 0, 0);
;     __builtin_amdgcn_s_setprio(0);
.LBB0_1776:
	v_add_u32_e32 v0, s30, v157
	v_add_u32_e32 v6, v0, v155
	v_add_u32_e32 v0, v0, v156
	ds_read_b128 v[160:163], v6 offset:32768
	ds_read_b128 v[164:167], v6 offset:34816
	ds_read_b128 v[168:171], v6 offset:36864
	ds_read_b128 v[172:175], v6 offset:38912
	ds_read_b128 v[176:179], v0
	ds_read_b128 v[182:185], v0 offset:2048
	ds_read_b128 v[186:189], v0 offset:4096
	ds_read_b128 v[190:193], v0 offset:6144
	ds_read_b128 v[194:197], v0 offset:8192
	ds_read_b128 v[198:201], v0 offset:10240
	ds_read_b128 v[202:205], v0 offset:12288
	ds_read_b128 v[206:209], v0 offset:14336
	s_waitcnt lgkmcnt(0)
	v_mfma_f32_16x16x32_bf16 v[128:131], v[176:179], v[160:163], v[128:131]
	v_mfma_f32_16x16x32_bf16 v[124:127], v[176:179], v[164:167], v[124:127]
	v_mfma_f32_16x16x32_bf16 v[120:123], v[176:179], v[168:171], v[120:123]
	v_mfma_f32_16x16x32_bf16 v[116:119], v[176:179], v[172:175], v[116:119]
	v_mfma_f32_16x16x32_bf16 v[112:115], v[182:185], v[160:163], v[112:115]
	v_mfma_f32_16x16x32_bf16 v[108:111], v[182:185], v[164:167], v[108:111]
	v_mfma_f32_16x16x32_bf16 v[104:107], v[182:185], v[168:171], v[104:107]
	v_mfma_f32_16x16x32_bf16 v[100:103], v[182:185], v[172:175], v[100:103]
	v_mfma_f32_16x16x32_bf16 v[96:99], v[186:189], v[160:163], v[96:99]
	v_mfma_f32_16x16x32_bf16 v[92:95], v[186:189], v[164:167], v[92:95]
	v_mfma_f32_16x16x32_bf16 v[88:91], v[186:189], v[168:171], v[88:91]
	v_mfma_f32_16x16x32_bf16 v[84:87], v[186:189], v[172:175], v[84:87]
	v_mfma_f32_16x16x32_bf16 v[80:83], v[190:193], v[160:163], v[80:83]
	v_mfma_f32_16x16x32_bf16 v[76:79], v[190:193], v[164:167], v[76:79]
	v_mfma_f32_16x16x32_bf16 v[72:75], v[190:193], v[168:171], v[72:75]
	v_mfma_f32_16x16x32_bf16 v[68:71], v[190:193], v[172:175], v[68:71]
	v_mfma_f32_16x16x32_bf16 v[64:67], v[194:197], v[160:163], v[64:67]
	v_mfma_f32_16x16x32_bf16 v[60:63], v[194:197], v[164:167], v[60:63]
	v_mfma_f32_16x16x32_bf16 v[56:59], v[194:197], v[168:171], v[56:59]
	v_mfma_f32_16x16x32_bf16 v[52:55], v[194:197], v[172:175], v[52:55]
	v_mfma_f32_16x16x32_bf16 v[48:51], v[198:201], v[160:163], v[48:51]
	v_mfma_f32_16x16x32_bf16 v[44:47], v[198:201], v[164:167], v[44:47]
	v_mfma_f32_16x16x32_bf16 v[40:43], v[198:201], v[168:171], v[40:43]
	v_mfma_f32_16x16x32_bf16 v[36:39], v[198:201], v[172:175], v[36:39]
	v_mfma_f32_16x16x32_bf16 v[32:35], v[202:205], v[160:163], v[32:35]
	v_mfma_f32_16x16x32_bf16 v[28:31], v[202:205], v[164:167], v[28:31]
	v_mfma_f32_16x16x32_bf16 v[24:27], v[202:205], v[168:171], v[24:27]
	v_mfma_f32_16x16x32_bf16 v[20:23], v[202:205], v[172:175], v[20:23]
	v_mfma_f32_16x16x32_bf16 v[16:19], v[206:209], v[160:163], v[16:19]
	v_mfma_f32_16x16x32_bf16 v[12:15], v[206:209], v[164:167], v[12:15]
	v_mfma_f32_16x16x32_bf16 v[8:11], v[206:209], v[168:171], v[8:11]
	v_mfma_f32_16x16x32_bf16 v[4:7], v[206:209], v[172:175], v[2:5]
